# K-loop LDS-DMA addresses: SGPR base + 32-bit VGPR offset instead of per-DMA 64-bit VALU adds (20 GEMM loops)
# baseline (speedup 1.0000x reference)
; #define PG8_STAGE(bufoff, gbase, voff) do { _Pragma("unroll") for (int _i = 0; _i < 2; ++_i) \
;         __builtin_amdgcn_global_load_lds((const unsigned*)((const char*)(gbase) + (voff)[_i]), (PG8_LAS unsigned*)(lds + (bufoff) + ldsw + _i * 8192), 16, 0, 0); } while (0)
; #define PG8_LDA(dst, b, h) do { _Pragma("unroll") for (int m = 0; m < 4; ++m) _Pragma("unroll") for (int k = 0; k < 2; ++k) dst[m][k] = *(const PG8_LAS bf16x8*)(lds + PG8_SA(b, h) + aoff + m * 2048 + k * 1024); } while (0)
; #define PG8_LDB(dst, b, h) do { _Pragma("unroll") for (int n = 0; n < 2; ++n) _Pragma("unroll") for (int k = 0; k < 2; ++k) dst[n][k] = *(const PG8_LAS bf16x8*)(lds + PG8_SB(b, h) + boff + n * 2048 + k * 1024); } while (0)
; #define PG8_MMA(ai, bj, At, Bt) do { __builtin_amdgcn_s_setprio(1); _Pragma("unroll") for (int m = 0; m < 4; ++m) _Pragma("unroll") for (int n = 0; n < 2; ++n) _Pragma("unroll") for (int k = 0; k < 2; ++k) \
;         acc[ai][bj][m][n] = __builtin_amdgcn_mfma_f32_16x16x32_bf16(Bt[n][k], At[m][k], acc[ai][bj][m][n], 0, 0, 0); __builtin_amdgcn_s_setprio(0); } while (0)
; #define PG8_WAIT_V(n) asm volatile("s_waitcnt vmcnt(" #n ")" ::: "memory")
; #define PG8_WAIT_L(n) asm volatile("s_waitcnt lgkmcnt(" #n ")" ::: "memory")
; template <class Epi, class Sched, bool ALIGN_EPI = false, bool SP2 = false>
; __device__ __forceinline__ void gemm_phase(PG8_LAS unsigned char* lds, const Gemm g, const Sched S, const Epi E, const int tid) {
;     ...
;             const bool last = (t == nt - 2);
;             const char* a1 = cA + (size_t)(t + 1) * kstep;
;             const char* a2 = last ? nA : cA + (size_t)(t + 2) * kstep; const char* b2 = last ? nB : cB + (size_t)(t + 2) * kstep;
;             const char* a3 = a2 + kstep; const char* b3 = b2 + kstep;
;             if (last && has_next) S.a_ready(nxt);
;             if constexpr (SP2) {
;             PG8_LDB(B0, 0, 0); PG8_LDB(B1, 0, 1); PG8_SCHED; PG8_LDA(At, 0, 0); PG8_STAGE(PG8_SA(1, 1), a1 + hstepA, voffA);
;             PG8_WAIT_V(8); PG8_WAIT_L(0); PG8_BAR; PG8_MMA(0, 0, At, B0); PG8_MMA(0, 1, At, B1); PG8_BAR; PG8_SCHED;
;             PG8_LDA(At, 0, 1); PG8_STAGE(PG8_SB(0, 0), b2, voffB); PG8_STAGE(PG8_SB(0, 1), b2 + hstepB, voffB); PG8_STAGE(PG8_SA(0, 0), a2, voffA);
;             PG8_WAIT_V(8); PG8_WAIT_L(0); PG8_BAR; PG8_MMA(1, 0, At, B0); PG8_MMA(1, 1, At, B1); PG8_BAR; PG8_SCHED;
.LBB0_157:
	ds_read_b128 v[146:149], v169
	ds_read_b128 v[150:153], v169 offset:1024
	ds_read_b128 v[172:175], v169 offset:2048
	ds_read_b128 v[176:179], v169 offset:3072
	ds_read_b128 v[180:183], v170
	ds_read_b128 v[188:191], v170 offset:1024
	ds_read_b128 v[192:195], v170 offset:2048
	ds_read_b128 v[196:199], v170 offset:3072
	s_add_u32 s34, s30, 0xfffc0080
	s_addc_u32 s35, s31, -1
	s_cmp_eq_u32 s65, 12
	s_cselect_b32 s37, s23, s35
	s_cselect_b32 s36, s61, s34
	s_cselect_b32 s35, s15, s64
	s_cselect_b32 s34, s62, s63
	s_add_i32 m0, s29, 0xc000
	ds_read_b128 v[200:203], v171
	ds_read_b128 v[204:207], v171 offset:1024
	ds_read_b128 v[208:211], v171 offset:2048
	ds_read_b128 v[212:215], v171 offset:3072
	ds_read_b128 v[216:219], v171 offset:4096
	ds_read_b128 v[220:223], v171 offset:5120
	ds_read_b128 v[224:227], v171 offset:6144
	ds_read_b128 v[228:231], v171 offset:7168
	global_load_lds_dwordx4 v138, s[30:31]
	s_add_i32 m0, s29, 0xe000
	s_nop 0
	global_load_lds_dwordx4 v140, s[30:31]
	s_waitcnt vmcnt(8)
	s_waitcnt lgkmcnt(0)
	s_barrier
	s_setprio 1
	s_waitcnt lgkmcnt(0)
	v_mfma_f32_16x16x32_bf16 v[124:127], v[146:149], v[200:203], v[124:127]
	v_mfma_f32_16x16x32_bf16 v[120:123], v[172:175], v[200:203], v[120:123]
	v_mfma_f32_16x16x32_bf16 v[108:111], v[146:149], v[208:211], v[108:111]
	v_mfma_f32_16x16x32_bf16 v[104:107], v[172:175], v[208:211], v[104:107]
	v_mfma_f32_16x16x32_bf16 v[92:95], v[146:149], v[216:219], v[92:95]
	v_mfma_f32_16x16x32_bf16 v[88:91], v[172:175], v[216:219], v[88:91]
	v_mfma_f32_16x16x32_bf16 v[76:79], v[146:149], v[224:227], v[76:79]
	v_mfma_f32_16x16x32_bf16 v[72:75], v[172:175], v[224:227], v[72:75]
	v_mfma_f32_16x16x32_bf16 v[124:127], v[150:153], v[204:207], v[124:127]
	v_mfma_f32_16x16x32_bf16 v[120:123], v[176:179], v[204:207], v[120:123]
	v_mfma_f32_16x16x32_bf16 v[108:111], v[150:153], v[212:215], v[108:111]
	v_mfma_f32_16x16x32_bf16 v[104:107], v[176:179], v[212:215], v[104:107]
	v_mfma_f32_16x16x32_bf16 v[92:95], v[150:153], v[220:223], v[92:95]
	v_mfma_f32_16x16x32_bf16 v[88:91], v[176:179], v[220:223], v[88:91]
	v_mfma_f32_16x16x32_bf16 v[76:79], v[150:153], v[228:231], v[76:79]
	v_mfma_f32_16x16x32_bf16 v[72:75], v[176:179], v[228:231], v[72:75]
	s_setprio 0
	s_setprio 1
	v_mfma_f32_16x16x32_bf16 v[116:119], v[180:183], v[200:203], v[116:119]
	v_mfma_f32_16x16x32_bf16 v[112:115], v[192:195], v[200:203], v[112:115]
	v_mfma_f32_16x16x32_bf16 v[100:103], v[180:183], v[208:211], v[100:103]
	v_mfma_f32_16x16x32_bf16 v[96:99], v[192:195], v[208:211], v[96:99]
	v_mfma_f32_16x16x32_bf16 v[84:87], v[180:183], v[216:219], v[84:87]
	v_mfma_f32_16x16x32_bf16 v[80:83], v[192:195], v[216:219], v[80:83]
	v_mfma_f32_16x16x32_bf16 v[68:71], v[180:183], v[224:227], v[68:71]
	v_mfma_f32_16x16x32_bf16 v[64:67], v[192:195], v[224:227], v[64:67]
	v_mfma_f32_16x16x32_bf16 v[116:119], v[188:191], v[204:207], v[116:119]
	v_mfma_f32_16x16x32_bf16 v[112:115], v[196:199], v[204:207], v[112:115]
	v_mfma_f32_16x16x32_bf16 v[100:103], v[188:191], v[212:215], v[100:103]
	v_mfma_f32_16x16x32_bf16 v[96:99], v[196:199], v[212:215], v[96:99]
	v_mfma_f32_16x16x32_bf16 v[84:87], v[188:191], v[220:223], v[84:87]
	v_mfma_f32_16x16x32_bf16 v[80:83], v[196:199], v[220:223], v[80:83]
	v_mfma_f32_16x16x32_bf16 v[68:71], v[188:191], v[228:231], v[68:71]
	v_mfma_f32_16x16x32_bf16 v[64:67], v[196:199], v[228:231], v[64:67]
	s_setprio 0
	s_barrier
	s_add_u32 s98, s34, 0x80
	s_addc_u32 s99, s35, 0
	s_add_u32 s100, s36, 0x80
	s_addc_u32 s101, s37, 0
	s_add_i32 s66, s52, s13
	s_mov_b32 m0, s66
	ds_read_b128 v[200:203], v171 offset:16384
	ds_read_b128 v[204:207], v171 offset:17408
	ds_read_b128 v[208:211], v171 offset:18432
	ds_read_b128 v[212:215], v171 offset:19456
	ds_read_b128 v[216:219], v171 offset:20480
	ds_read_b128 v[220:223], v171 offset:21504
	ds_read_b128 v[224:227], v171 offset:22528
	ds_read_b128 v[228:231], v171 offset:23552
	global_load_lds_dwordx4 v130, s[34:35]
	s_add_i32 m0, s66, 0x2000
	s_add_u32 s66, s34, 0x40000
	s_addc_u32 s67, s35, 0
	s_add_i32 s69, s53, s13
	global_load_lds_dwordx4 v134, s[34:35]
	s_mov_b32 m0, s69
	s_nop 0
	global_load_lds_dwordx4 v130, s[66:67]
	s_add_i32 m0, s69, 0x2000
	s_nop 0
	global_load_lds_dwordx4 v134, s[66:67]
	s_mov_b32 m0, s29
	s_nop 0
	global_load_lds_dwordx4 v128, s[36:37]
	s_mov_b32 m0, s47
	s_nop 0
	global_load_lds_dwordx4 v132, s[36:37]
	s_waitcnt vmcnt(8)
	s_waitcnt lgkmcnt(0)
	s_barrier
	s_setprio 1
	s_waitcnt lgkmcnt(0)
	v_mfma_f32_16x16x32_bf16 v[60:63], v[146:149], v[200:203], v[60:63]
	v_mfma_f32_16x16x32_bf16 v[56:59], v[172:175], v[200:203], v[56:59]
	v_mfma_f32_16x16x32_bf16 v[44:47], v[146:149], v[208:211], v[44:47]
	v_mfma_f32_16x16x32_bf16 v[40:43], v[172:175], v[208:211], v[40:43]
	v_mfma_f32_16x16x32_bf16 v[28:31], v[146:149], v[216:219], v[28:31]
	v_mfma_f32_16x16x32_bf16 v[24:27], v[172:175], v[216:219], v[24:27]
	v_mfma_f32_16x16x32_bf16 v[12:15], v[146:149], v[224:227], v[12:15]
	v_mfma_f32_16x16x32_bf16 v[8:11], v[172:175], v[224:227], v[8:11]
	v_mfma_f32_16x16x32_bf16 v[60:63], v[150:153], v[204:207], v[60:63]
	v_mfma_f32_16x16x32_bf16 v[56:59], v[176:179], v[204:207], v[56:59]
	v_mfma_f32_16x16x32_bf16 v[44:47], v[150:153], v[212:215], v[44:47]
	v_mfma_f32_16x16x32_bf16 v[40:43], v[176:179], v[212:215], v[40:43]
	v_mfma_f32_16x16x32_bf16 v[28:31], v[150:153], v[220:223], v[28:31]
	v_mfma_f32_16x16x32_bf16 v[24:27], v[176:179], v[220:223], v[24:27]
	v_mfma_f32_16x16x32_bf16 v[12:15], v[150:153], v[228:231], v[12:15]
	v_mfma_f32_16x16x32_bf16 v[8:11], v[176:179], v[228:231], v[8:11]
	s_setprio 0
	s_setprio 1
	v_mfma_f32_16x16x32_bf16 v[52:55], v[180:183], v[200:203], v[52:55]
	v_mfma_f32_16x16x32_bf16 v[48:51], v[192:195], v[200:203], v[48:51]
	v_mfma_f32_16x16x32_bf16 v[36:39], v[180:183], v[208:211], v[36:39]
	v_mfma_f32_16x16x32_bf16 v[32:35], v[192:195], v[208:211], v[32:35]
	v_mfma_f32_16x16x32_bf16 v[20:23], v[180:183], v[216:219], v[20:23]
	v_mfma_f32_16x16x32_bf16 v[16:19], v[192:195], v[216:219], v[16:19]
	v_mfma_f32_16x16x32_bf16 v[4:7], v[180:183], v[224:227], v[4:7]
	v_mfma_f32_16x16x32_bf16 v[0:3], v[192:195], v[224:227], v[0:3]
	v_mfma_f32_16x16x32_bf16 v[52:55], v[188:191], v[204:207], v[52:55]
	v_mfma_f32_16x16x32_bf16 v[48:51], v[196:199], v[204:207], v[48:51]
	v_mfma_f32_16x16x32_bf16 v[36:39], v[188:191], v[212:215], v[36:39]
	v_mfma_f32_16x16x32_bf16 v[32:35], v[196:199], v[212:215], v[32:35]
	v_mfma_f32_16x16x32_bf16 v[20:23], v[188:191], v[220:223], v[20:23]
	v_mfma_f32_16x16x32_bf16 v[16:19], v[196:199], v[220:223], v[16:19]
	v_mfma_f32_16x16x32_bf16 v[4:7], v[188:191], v[228:231], v[4:7]
	v_mfma_f32_16x16x32_bf16 v[0:3], v[196:199], v[228:231], v[0:3]
	s_setprio 0
	s_barrier
; #define PG8_STAGE(bufoff, gbase, voff) do { _Pragma("unroll") for (int _i = 0; _i < 2; ++_i) \
;         __builtin_amdgcn_global_load_lds((const unsigned*)((const char*)(gbase) + (voff)[_i]), (PG8_LAS unsigned*)(lds + (bufoff) + ldsw + _i * 8192), 16, 0, 0); } while (0)
; #define PG8_LDA(dst, b, h) do { _Pragma("unroll") for (int m = 0; m < 4; ++m) _Pragma("unroll") for (int k = 0; k < 2; ++k) dst[m][k] = *(const PG8_LAS bf16x8*)(lds + PG8_SA(b, h) + aoff + m * 2048 + k * 1024); } while (0)
; #define PG8_LDB(dst, b, h) do { _Pragma("unroll") for (int n = 0; n < 2; ++n) _Pragma("unroll") for (int k = 0; k < 2; ++k) dst[n][k] = *(const PG8_LAS bf16x8*)(lds + PG8_SB(b, h) + boff + n * 2048 + k * 1024); } while (0)
; #define PG8_MMA(ai, bj, At, Bt) do { __builtin_amdgcn_s_setprio(1); _Pragma("unroll") for (int m = 0; m < 4; ++m) _Pragma("unroll") for (int n = 0; n < 2; ++n) _Pragma("unroll") for (int k = 0; k < 2; ++k) \
;         acc[ai][bj][m][n] = __builtin_amdgcn_mfma_f32_16x16x32_bf16(Bt[n][k], At[m][k], acc[ai][bj][m][n], 0, 0, 0); __builtin_amdgcn_s_setprio(0); } while (0)
; #define PG8_WAIT_V(n) asm volatile("s_waitcnt vmcnt(" #n ")" ::: "memory")
; #define PG8_WAIT_L(n) asm volatile("s_waitcnt lgkmcnt(" #n ")" ::: "memory")
; #define PG8_BAR __builtin_amdgcn_s_barrier()
; #define PG8_SCHED __builtin_amdgcn_sched_barrier(0)
; template <class Epi, class Sched, bool ALIGN_EPI = false, bool SP2 = false>
; __device__ __forceinline__ void gemm_phase(PG8_LAS unsigned char* lds, const Gemm g, const Sched S, const Epi E, const int tid) {
;     ...
;             PG8_LDB(B0, 1, 0); PG8_LDB(B1, 1, 1); PG8_SCHED; PG8_LDA(At, 1, 0); PG8_STAGE(PG8_SA(0, 1), a2 + hstepA, voffA);
;             PG8_WAIT_V(8); PG8_WAIT_L(0); PG8_BAR; PG8_MMA(0, 0, At, B0); PG8_MMA(0, 1, At, B1); PG8_BAR; PG8_SCHED;
;             PG8_LDA(At, 1, 1); PG8_STAGE(PG8_SB(1, 0), b3, voffB); PG8_STAGE(PG8_SB(1, 1), b3 + hstepB, voffB); PG8_STAGE(PG8_SA(1, 0), a3, voffA);
;             PG8_WAIT_V(8); PG8_WAIT_L(0); PG8_BAR; PG8_MMA(1, 0, At, B0); PG8_MMA(1, 1, At, B1); PG8_BAR; PG8_SCHED;
	s_add_i32 s66, 0, 0x18000
	s_add_i32 s67, 0, 0x1c000
	v_add_u32_e32 v176, s66, v166
	v_add_u32_e32 v187, s67, v166
	ds_read_b128 v[146:149], v176
	ds_read_b128 v[150:153], v176 offset:1024
	ds_read_b128 v[172:175], v176 offset:2048
	ds_read_b128 v[176:179], v176 offset:3072
	ds_read_b128 v[180:183], v187
	ds_read_b128 v[188:191], v187 offset:1024
	ds_read_b128 v[192:195], v187 offset:2048
	ds_read_b128 v[196:199], v187 offset:3072
	s_add_u32 s36, s36, 0x40000
	s_addc_u32 s37, s37, 0
	s_mov_b32 m0, s48
	ds_read_b128 v[200:203], v171 offset:32768
	ds_read_b128 v[204:207], v171 offset:33792
	ds_read_b128 v[208:211], v171 offset:34816
	ds_read_b128 v[212:215], v171 offset:35840
	ds_read_b128 v[216:219], v171 offset:36864
	ds_read_b128 v[220:223], v171 offset:37888
	ds_read_b128 v[224:227], v171 offset:38912
	ds_read_b128 v[228:231], v171 offset:39936
	global_load_lds_dwordx4 v128, s[36:37]
	s_mov_b32 m0, s49
	s_nop 0
	global_load_lds_dwordx4 v132, s[36:37]
	s_waitcnt vmcnt(8)
	s_waitcnt lgkmcnt(0)
	s_barrier
	s_setprio 1
	s_waitcnt lgkmcnt(0)
	v_mfma_f32_16x16x32_bf16 v[124:127], v[146:149], v[200:203], v[124:127]
	v_mfma_f32_16x16x32_bf16 v[120:123], v[172:175], v[200:203], v[120:123]
	v_mfma_f32_16x16x32_bf16 v[108:111], v[146:149], v[208:211], v[108:111]
	v_mfma_f32_16x16x32_bf16 v[104:107], v[172:175], v[208:211], v[104:107]
	v_mfma_f32_16x16x32_bf16 v[92:95], v[146:149], v[216:219], v[92:95]
	v_mfma_f32_16x16x32_bf16 v[88:91], v[172:175], v[216:219], v[88:91]
	v_mfma_f32_16x16x32_bf16 v[76:79], v[146:149], v[224:227], v[76:79]
	v_mfma_f32_16x16x32_bf16 v[72:75], v[172:175], v[224:227], v[72:75]
	v_mfma_f32_16x16x32_bf16 v[124:127], v[150:153], v[204:207], v[124:127]
	v_mfma_f32_16x16x32_bf16 v[120:123], v[176:179], v[204:207], v[120:123]
	v_mfma_f32_16x16x32_bf16 v[108:111], v[150:153], v[212:215], v[108:111]
	v_mfma_f32_16x16x32_bf16 v[104:107], v[176:179], v[212:215], v[104:107]
	v_mfma_f32_16x16x32_bf16 v[92:95], v[150:153], v[220:223], v[92:95]
	v_mfma_f32_16x16x32_bf16 v[88:91], v[176:179], v[220:223], v[88:91]
	v_mfma_f32_16x16x32_bf16 v[76:79], v[150:153], v[228:231], v[76:79]
	v_mfma_f32_16x16x32_bf16 v[72:75], v[176:179], v[228:231], v[72:75]
	s_setprio 0
	s_setprio 1
	v_mfma_f32_16x16x32_bf16 v[116:119], v[180:183], v[200:203], v[116:119]
	v_mfma_f32_16x16x32_bf16 v[112:115], v[192:195], v[200:203], v[112:115]
	v_mfma_f32_16x16x32_bf16 v[100:103], v[180:183], v[208:211], v[100:103]
	v_mfma_f32_16x16x32_bf16 v[96:99], v[192:195], v[208:211], v[96:99]
	v_mfma_f32_16x16x32_bf16 v[84:87], v[180:183], v[216:219], v[84:87]
	v_mfma_f32_16x16x32_bf16 v[80:83], v[192:195], v[216:219], v[80:83]
	v_mfma_f32_16x16x32_bf16 v[68:71], v[180:183], v[224:227], v[68:71]
	v_mfma_f32_16x16x32_bf16 v[64:67], v[192:195], v[224:227], v[64:67]
	v_mfma_f32_16x16x32_bf16 v[116:119], v[188:191], v[204:207], v[116:119]
	v_mfma_f32_16x16x32_bf16 v[112:115], v[196:199], v[204:207], v[112:115]
	v_mfma_f32_16x16x32_bf16 v[100:103], v[188:191], v[212:215], v[100:103]
	v_mfma_f32_16x16x32_bf16 v[96:99], v[196:199], v[212:215], v[96:99]
	v_mfma_f32_16x16x32_bf16 v[84:87], v[188:191], v[220:223], v[84:87]
	v_mfma_f32_16x16x32_bf16 v[80:83], v[196:199], v[220:223], v[80:83]
	v_mfma_f32_16x16x32_bf16 v[68:71], v[188:191], v[228:231], v[68:71]
	v_mfma_f32_16x16x32_bf16 v[64:67], v[196:199], v[228:231], v[64:67]
	s_setprio 0
	s_barrier
	s_add_i32 s36, s66, s13
	s_mov_b32 m0, s36
	ds_read_b128 v[200:203], v171 offset:49152
	ds_read_b128 v[204:207], v171 offset:50176
	ds_read_b128 v[208:211], v171 offset:51200
	ds_read_b128 v[212:215], v171 offset:52224
	ds_read_b128 v[216:219], v171 offset:53248
	ds_read_b128 v[220:223], v171 offset:54272
	ds_read_b128 v[224:227], v171 offset:55296
	ds_read_b128 v[228:231], v171 offset:56320
	global_load_lds_dwordx4 v130, s[98:99]
	s_add_i32 m0, s36, 0x2000
	s_add_u32 s34, s34, 0x40080
	s_addc_u32 s35, s35, 0
	s_add_i32 s36, s67, s13
	global_load_lds_dwordx4 v134, s[98:99]
	s_mov_b32 m0, s36
	s_nop 0
	global_load_lds_dwordx4 v130, s[34:35]
	s_add_i32 m0, s36, 0x2000
	s_nop 0
	global_load_lds_dwordx4 v134, s[34:35]
	s_mov_b32 m0, s50
	s_nop 0
	global_load_lds_dwordx4 v128, s[100:101]
	s_mov_b32 m0, s51
	s_nop 0
	global_load_lds_dwordx4 v132, s[100:101]
	s_waitcnt vmcnt(8)
	s_waitcnt lgkmcnt(0)
	s_barrier
	s_setprio 1
	s_waitcnt lgkmcnt(0)
	v_mfma_f32_16x16x32_bf16 v[60:63], v[146:149], v[200:203], v[60:63]
	v_mfma_f32_16x16x32_bf16 v[56:59], v[172:175], v[200:203], v[56:59]
	v_mfma_f32_16x16x32_bf16 v[44:47], v[146:149], v[208:211], v[44:47]
	v_mfma_f32_16x16x32_bf16 v[40:43], v[172:175], v[208:211], v[40:43]
	v_mfma_f32_16x16x32_bf16 v[28:31], v[146:149], v[216:219], v[28:31]
	v_mfma_f32_16x16x32_bf16 v[24:27], v[172:175], v[216:219], v[24:27]
	v_mfma_f32_16x16x32_bf16 v[12:15], v[146:149], v[224:227], v[12:15]
	v_mfma_f32_16x16x32_bf16 v[8:11], v[172:175], v[224:227], v[8:11]
	v_mfma_f32_16x16x32_bf16 v[60:63], v[150:153], v[204:207], v[60:63]
	v_mfma_f32_16x16x32_bf16 v[56:59], v[176:179], v[204:207], v[56:59]
	v_mfma_f32_16x16x32_bf16 v[44:47], v[150:153], v[212:215], v[44:47]
	v_mfma_f32_16x16x32_bf16 v[40:43], v[176:179], v[212:215], v[40:43]
	v_mfma_f32_16x16x32_bf16 v[28:31], v[150:153], v[220:223], v[28:31]
	v_mfma_f32_16x16x32_bf16 v[24:27], v[176:179], v[220:223], v[24:27]
	v_mfma_f32_16x16x32_bf16 v[12:15], v[150:153], v[228:231], v[12:15]
	v_mfma_f32_16x16x32_bf16 v[8:11], v[176:179], v[228:231], v[8:11]
	s_setprio 0
	s_setprio 1
	v_mfma_f32_16x16x32_bf16 v[52:55], v[180:183], v[200:203], v[52:55]
	v_mfma_f32_16x16x32_bf16 v[48:51], v[192:195], v[200:203], v[48:51]
	v_mfma_f32_16x16x32_bf16 v[36:39], v[180:183], v[208:211], v[36:39]
	v_mfma_f32_16x16x32_bf16 v[32:35], v[192:195], v[208:211], v[32:35]
	v_mfma_f32_16x16x32_bf16 v[20:23], v[180:183], v[216:219], v[20:23]
	v_mfma_f32_16x16x32_bf16 v[16:19], v[192:195], v[216:219], v[16:19]
	v_mfma_f32_16x16x32_bf16 v[4:7], v[180:183], v[224:227], v[4:7]
	v_mfma_f32_16x16x32_bf16 v[0:3], v[192:195], v[224:227], v[0:3]
	v_mfma_f32_16x16x32_bf16 v[52:55], v[188:191], v[204:207], v[52:55]
	v_mfma_f32_16x16x32_bf16 v[48:51], v[196:199], v[204:207], v[48:51]
	v_mfma_f32_16x16x32_bf16 v[36:39], v[188:191], v[212:215], v[36:39]
	v_mfma_f32_16x16x32_bf16 v[32:35], v[196:199], v[212:215], v[32:35]
	v_mfma_f32_16x16x32_bf16 v[20:23], v[188:191], v[220:223], v[20:23]
	v_mfma_f32_16x16x32_bf16 v[16:19], v[196:199], v[220:223], v[16:19]
	v_mfma_f32_16x16x32_bf16 v[4:7], v[188:191], v[228:231], v[4:7]
	v_mfma_f32_16x16x32_bf16 v[0:3], v[196:199], v[228:231], v[0:3]
	s_setprio 0
	s_barrier
	s_add_i32 s65, s65, 2
	s_add_u32 s30, s30, 0x100
	s_addc_u32 s31, s31, 0
	s_add_u32 s63, s63, 0x100
	s_addc_u32 s64, s64, 0
	s_cmp_gt_u32 s65, 13
	s_cbranch_scc0 .LBB0_157
	s_and_b64 vcc, exec, s[10:11]
	s_cbranch_vccz .LBB0_160
	s_barrier

; #define PG8_STAGE(bufoff, gbase, voff) do { _Pragma("unroll") for (int _i = 0; _i < 2; ++_i) \
;         __builtin_amdgcn_global_load_lds((const unsigned*)((const char*)(gbase) + (voff)[_i]), (PG8_LAS unsigned*)(lds + (bufoff) + ldsw + _i * 8192), 16, 0, 0); } while (0)
; #define PG8_LDA(dst, b, h) do { _Pragma("unroll") for (int m = 0; m < 4; ++m) _Pragma("unroll") for (int k = 0; k < 2; ++k) dst[m][k] = *(const PG8_LAS bf16x8*)(lds + PG8_SA(b, h) + aoff + m * 2048 + k * 1024); } while (0)
; #define PG8_LDB(dst, b, h) do { _Pragma("unroll") for (int n = 0; n < 2; ++n) _Pragma("unroll") for (int k = 0; k < 2; ++k) dst[n][k] = *(const PG8_LAS bf16x8*)(lds + PG8_SB(b, h) + boff + n * 2048 + k * 1024); } while (0)
; #define PG8_MMA(ai, bj, At, Bt) do { __builtin_amdgcn_s_setprio(1); _Pragma("unroll") for (int m = 0; m < 4; ++m) _Pragma("unroll") for (int n = 0; n < 2; ++n) _Pragma("unroll") for (int k = 0; k < 2; ++k) \
;         acc[ai][bj][m][n] = __builtin_amdgcn_mfma_f32_16x16x32_bf16(Bt[n][k], At[m][k], acc[ai][bj][m][n], 0, 0, 0); __builtin_amdgcn_s_setprio(0); } while (0)
; #define PG8_WAIT_V(n) asm volatile("s_waitcnt vmcnt(" #n ")" ::: "memory")
; #define PG8_WAIT_L(n) asm volatile("s_waitcnt lgkmcnt(" #n ")" ::: "memory")
; template <class Epi, class Sched, bool ALIGN_EPI = false, bool SP2 = false>
; __device__ __forceinline__ void gemm_phase(PG8_LAS unsigned char* lds, const Gemm g, const Sched S, const Epi E, const int tid) {
;     ...
;             const bool last = (t == nt - 2);
;             const char* a1 = cA + (size_t)(t + 1) * kstep;
;             const char* a2 = last ? nA : cA + (size_t)(t + 2) * kstep; const char* b2 = last ? nB : cB + (size_t)(t + 2) * kstep;
;             const char* a3 = a2 + kstep; const char* b3 = b2 + kstep;
;             if (last && has_next) S.a_ready(nxt);
;             if constexpr (SP2) {
;             PG8_LDB(B0, 0, 0); PG8_LDB(B1, 0, 1); PG8_SCHED; PG8_LDA(At, 0, 0); PG8_STAGE(PG8_SA(1, 1), a1 + hstepA, voffA);
;             PG8_WAIT_V(8); PG8_WAIT_L(0); PG8_BAR; PG8_MMA(0, 0, At, B0); PG8_MMA(0, 1, At, B1); PG8_BAR; PG8_SCHED;
;             PG8_LDA(At, 0, 1); PG8_STAGE(PG8_SB(0, 0), b2, voffB); PG8_STAGE(PG8_SB(0, 1), b2 + hstepB, voffB); PG8_STAGE(PG8_SA(0, 0), a2, voffA);
;             PG8_WAIT_V(8); PG8_WAIT_L(0); PG8_BAR; PG8_MMA(1, 0, At, B0); PG8_MMA(1, 1, At, B1); PG8_BAR; PG8_SCHED;
.LBB0_204:
	ds_read_b128 v[150:153], v147
	ds_read_b128 v[166:169], v147 offset:1024
	ds_read_b128 v[170:173], v147 offset:2048
	ds_read_b128 v[174:177], v147 offset:3072
	ds_read_b128 v[178:181], v148
	ds_read_b128 v[182:185], v148 offset:1024
	ds_read_b128 v[188:191], v148 offset:2048
	ds_read_b128 v[192:195], v148 offset:3072
	s_add_u32 s52, s50, 0xfffc0080
	s_addc_u32 s53, s51, -1
	s_cmp_eq_u32 s80, 12
	s_cselect_b32 s55, s37, s53
	s_cselect_b32 s54, s76, s52
	s_cselect_b32 s53, s35, s79
	s_cselect_b32 s52, s77, s78
	s_add_i32 m0, s49, 0xc000
	ds_read_b128 v[196:199], v149
	ds_read_b128 v[200:203], v149 offset:1024
	ds_read_b128 v[204:207], v149 offset:2048
	ds_read_b128 v[208:211], v149 offset:3072
	ds_read_b128 v[212:215], v149 offset:4096
	ds_read_b128 v[216:219], v149 offset:5120
	ds_read_b128 v[220:223], v149 offset:6144
	ds_read_b128 v[224:227], v149 offset:7168
	global_load_lds_dwordx4 v138, s[50:51]
	s_add_i32 m0, s49, 0xe000
	s_nop 0
	global_load_lds_dwordx4 v140, s[50:51]
	s_waitcnt vmcnt(8)
	s_waitcnt lgkmcnt(0)
	s_barrier
	s_setprio 1
	s_waitcnt lgkmcnt(0)
	v_mfma_f32_16x16x32_bf16 v[124:127], v[150:153], v[196:199], v[124:127]
	v_mfma_f32_16x16x32_bf16 v[120:123], v[170:173], v[196:199], v[120:123]
	v_mfma_f32_16x16x32_bf16 v[112:115], v[150:153], v[204:207], v[112:115]
	v_mfma_f32_16x16x32_bf16 v[104:107], v[170:173], v[204:207], v[104:107]
	v_mfma_f32_16x16x32_bf16 v[96:99], v[150:153], v[212:215], v[96:99]
	v_mfma_f32_16x16x32_bf16 v[88:91], v[170:173], v[212:215], v[88:91]
	v_mfma_f32_16x16x32_bf16 v[80:83], v[150:153], v[220:223], v[80:83]
	v_mfma_f32_16x16x32_bf16 v[72:75], v[170:173], v[220:223], v[72:75]
	v_mfma_f32_16x16x32_bf16 v[124:127], v[166:169], v[200:203], v[124:127]
	v_mfma_f32_16x16x32_bf16 v[120:123], v[174:177], v[200:203], v[120:123]
	v_mfma_f32_16x16x32_bf16 v[112:115], v[166:169], v[208:211], v[112:115]
	v_mfma_f32_16x16x32_bf16 v[104:107], v[174:177], v[208:211], v[104:107]
	v_mfma_f32_16x16x32_bf16 v[96:99], v[166:169], v[216:219], v[96:99]
	v_mfma_f32_16x16x32_bf16 v[88:91], v[174:177], v[216:219], v[88:91]
	v_mfma_f32_16x16x32_bf16 v[80:83], v[166:169], v[224:227], v[80:83]
	v_mfma_f32_16x16x32_bf16 v[72:75], v[174:177], v[224:227], v[72:75]
	s_setprio 0
	s_setprio 1
	v_mfma_f32_16x16x32_bf16 v[116:119], v[178:181], v[196:199], v[116:119]
	v_mfma_f32_16x16x32_bf16 v[108:111], v[188:191], v[196:199], v[108:111]
	v_mfma_f32_16x16x32_bf16 v[100:103], v[178:181], v[204:207], v[100:103]
	v_mfma_f32_16x16x32_bf16 v[92:95], v[188:191], v[204:207], v[92:95]
	v_mfma_f32_16x16x32_bf16 v[84:87], v[178:181], v[212:215], v[84:87]
	v_mfma_f32_16x16x32_bf16 v[76:79], v[188:191], v[212:215], v[76:79]
	v_mfma_f32_16x16x32_bf16 v[68:71], v[178:181], v[220:223], v[68:71]
	v_mfma_f32_16x16x32_bf16 v[64:67], v[188:191], v[220:223], v[64:67]
	v_mfma_f32_16x16x32_bf16 v[116:119], v[182:185], v[200:203], v[116:119]
	v_mfma_f32_16x16x32_bf16 v[108:111], v[192:195], v[200:203], v[108:111]
	v_mfma_f32_16x16x32_bf16 v[100:103], v[182:185], v[208:211], v[100:103]
	v_mfma_f32_16x16x32_bf16 v[92:95], v[192:195], v[208:211], v[92:95]
	v_mfma_f32_16x16x32_bf16 v[84:87], v[182:185], v[216:219], v[84:87]
	v_mfma_f32_16x16x32_bf16 v[76:79], v[192:195], v[216:219], v[76:79]
	v_mfma_f32_16x16x32_bf16 v[68:71], v[182:185], v[224:227], v[68:71]
	v_mfma_f32_16x16x32_bf16 v[64:67], v[192:195], v[224:227], v[64:67]
	s_setprio 0
	s_barrier
	s_add_u32 s98, s52, 0x80
	s_addc_u32 s99, s53, 0
	s_add_u32 s100, s54, 0x80
	s_addc_u32 s101, s55, 0
	s_add_i32 s81, s73, s65
	s_mov_b32 m0, s81
	ds_read_b128 v[196:199], v149 offset:16384
	ds_read_b128 v[200:203], v149 offset:17408
	ds_read_b128 v[204:207], v149 offset:18432
	ds_read_b128 v[208:211], v149 offset:19456
	ds_read_b128 v[212:215], v149 offset:20480
	ds_read_b128 v[216:219], v149 offset:21504
	ds_read_b128 v[220:223], v149 offset:22528
	ds_read_b128 v[224:227], v149 offset:23552
	global_load_lds_dwordx4 v130, s[52:53]
	s_add_i32 m0, s81, 0x2000
	s_add_u32 s82, s52, 0x40000
	s_addc_u32 s83, s53, 0
	s_add_i32 s81, s74, s65
	global_load_lds_dwordx4 v134, s[52:53]
	s_mov_b32 m0, s81
	s_nop 0
	global_load_lds_dwordx4 v130, s[82:83]
	s_add_i32 m0, s81, 0x2000
	s_nop 0
	global_load_lds_dwordx4 v134, s[82:83]
	s_mov_b32 m0, s49
	s_nop 0
	global_load_lds_dwordx4 v128, s[54:55]
	s_mov_b32 m0, s66
	s_nop 0
	global_load_lds_dwordx4 v132, s[54:55]
	s_waitcnt vmcnt(8)
	s_waitcnt lgkmcnt(0)
	s_barrier
	s_setprio 1
	s_waitcnt lgkmcnt(0)
	v_mfma_f32_16x16x32_bf16 v[60:63], v[150:153], v[196:199], v[60:63]
	v_mfma_f32_16x16x32_bf16 v[56:59], v[170:173], v[196:199], v[56:59]
	v_mfma_f32_16x16x32_bf16 v[52:55], v[150:153], v[204:207], v[52:55]
	v_mfma_f32_16x16x32_bf16 v[44:47], v[170:173], v[204:207], v[44:47]
	v_mfma_f32_16x16x32_bf16 v[36:39], v[150:153], v[212:215], v[36:39]
	v_mfma_f32_16x16x32_bf16 v[28:31], v[170:173], v[212:215], v[28:31]
	v_mfma_f32_16x16x32_bf16 v[20:23], v[150:153], v[220:223], v[20:23]
	v_mfma_f32_16x16x32_bf16 v[12:15], v[170:173], v[220:223], v[12:15]
	v_mfma_f32_16x16x32_bf16 v[60:63], v[166:169], v[200:203], v[60:63]
	v_mfma_f32_16x16x32_bf16 v[56:59], v[174:177], v[200:203], v[56:59]
	v_mfma_f32_16x16x32_bf16 v[52:55], v[166:169], v[208:211], v[52:55]
	v_mfma_f32_16x16x32_bf16 v[44:47], v[174:177], v[208:211], v[44:47]
	v_mfma_f32_16x16x32_bf16 v[36:39], v[166:169], v[216:219], v[36:39]
	v_mfma_f32_16x16x32_bf16 v[28:31], v[174:177], v[216:219], v[28:31]
	v_mfma_f32_16x16x32_bf16 v[20:23], v[166:169], v[224:227], v[20:23]
	v_mfma_f32_16x16x32_bf16 v[12:15], v[174:177], v[224:227], v[12:15]
	s_setprio 0
	s_setprio 1
	v_mfma_f32_16x16x32_bf16 v[48:51], v[178:181], v[196:199], v[48:51]
	v_mfma_f32_16x16x32_bf16 v[40:43], v[188:191], v[196:199], v[40:43]
	v_mfma_f32_16x16x32_bf16 v[32:35], v[178:181], v[204:207], v[32:35]
	v_mfma_f32_16x16x32_bf16 v[24:27], v[188:191], v[204:207], v[24:27]
	v_mfma_f32_16x16x32_bf16 v[16:19], v[178:181], v[212:215], v[16:19]
	v_mfma_f32_16x16x32_bf16 v[8:11], v[188:191], v[212:215], v[8:11]
	v_mfma_f32_16x16x32_bf16 v[4:7], v[178:181], v[220:223], v[4:7]
	v_mfma_f32_16x16x32_bf16 v[0:3], v[188:191], v[220:223], v[0:3]
	v_mfma_f32_16x16x32_bf16 v[48:51], v[182:185], v[200:203], v[48:51]
	v_mfma_f32_16x16x32_bf16 v[40:43], v[192:195], v[200:203], v[40:43]
	v_mfma_f32_16x16x32_bf16 v[32:35], v[182:185], v[208:211], v[32:35]
	v_mfma_f32_16x16x32_bf16 v[24:27], v[192:195], v[208:211], v[24:27]
	v_mfma_f32_16x16x32_bf16 v[16:19], v[182:185], v[216:219], v[16:19]
	v_mfma_f32_16x16x32_bf16 v[8:11], v[192:195], v[216:219], v[8:11]
	v_mfma_f32_16x16x32_bf16 v[4:7], v[182:185], v[224:227], v[4:7]
	v_mfma_f32_16x16x32_bf16 v[0:3], v[192:195], v[224:227], v[0:3]
	s_setprio 0
	s_barrier
; #define PG8_STAGE(bufoff, gbase, voff) do { _Pragma("unroll") for (int _i = 0; _i < 2; ++_i) \
;         __builtin_amdgcn_global_load_lds((const unsigned*)((const char*)(gbase) + (voff)[_i]), (PG8_LAS unsigned*)(lds + (bufoff) + ldsw + _i * 8192), 16, 0, 0); } while (0)
; #define PG8_LDA(dst, b, h) do { _Pragma("unroll") for (int m = 0; m < 4; ++m) _Pragma("unroll") for (int k = 0; k < 2; ++k) dst[m][k] = *(const PG8_LAS bf16x8*)(lds + PG8_SA(b, h) + aoff + m * 2048 + k * 1024); } while (0)
; #define PG8_LDB(dst, b, h) do { _Pragma("unroll") for (int n = 0; n < 2; ++n) _Pragma("unroll") for (int k = 0; k < 2; ++k) dst[n][k] = *(const PG8_LAS bf16x8*)(lds + PG8_SB(b, h) + boff + n * 2048 + k * 1024); } while (0)
; #define PG8_MMA(ai, bj, At, Bt) do { __builtin_amdgcn_s_setprio(1); _Pragma("unroll") for (int m = 0; m < 4; ++m) _Pragma("unroll") for (int n = 0; n < 2; ++n) _Pragma("unroll") for (int k = 0; k < 2; ++k) \
;         acc[ai][bj][m][n] = __builtin_amdgcn_mfma_f32_16x16x32_bf16(Bt[n][k], At[m][k], acc[ai][bj][m][n], 0, 0, 0); __builtin_amdgcn_s_setprio(0); } while (0)
; #define PG8_WAIT_V(n) asm volatile("s_waitcnt vmcnt(" #n ")" ::: "memory")
; #define PG8_WAIT_L(n) asm volatile("s_waitcnt lgkmcnt(" #n ")" ::: "memory")
; #define PG8_BAR __builtin_amdgcn_s_barrier()
; #define PG8_SCHED __builtin_amdgcn_sched_barrier(0)
; template <class Epi, class Sched, bool ALIGN_EPI = false, bool SP2 = false>
; __device__ __forceinline__ void gemm_phase(PG8_LAS unsigned char* lds, const Gemm g, const Sched S, const Epi E, const int tid) {
;     ...
;             PG8_LDB(B0, 1, 0); PG8_LDB(B1, 1, 1); PG8_SCHED; PG8_LDA(At, 1, 0); PG8_STAGE(PG8_SA(0, 1), a2 + hstepA, voffA);
;             PG8_WAIT_V(8); PG8_WAIT_L(0); PG8_BAR; PG8_MMA(0, 0, At, B0); PG8_MMA(0, 1, At, B1); PG8_BAR; PG8_SCHED;
;             PG8_LDA(At, 1, 1); PG8_STAGE(PG8_SB(1, 0), b3, voffB); PG8_STAGE(PG8_SB(1, 1), b3 + hstepB, voffB); PG8_STAGE(PG8_SA(1, 0), a3, voffA);
;             PG8_WAIT_V(8); PG8_WAIT_L(0); PG8_BAR; PG8_MMA(1, 0, At, B0); PG8_MMA(1, 1, At, B1); PG8_BAR; PG8_SCHED;
	s_add_i32 s81, 0, 0x18000
	v_add_u32_e32 v165, s81, v145
	s_add_i32 s82, 0, 0x1c000
	ds_read_b128 v[150:153], v165
	ds_read_b128 v[166:169], v165 offset:1024
	ds_read_b128 v[170:173], v165 offset:2048
	ds_read_b128 v[174:177], v165 offset:3072
	v_add_u32_e32 v165, s82, v145
	ds_read_b128 v[178:181], v165
	ds_read_b128 v[182:185], v165 offset:1024
	ds_read_b128 v[188:191], v165 offset:2048
	ds_read_b128 v[192:195], v165 offset:3072
	s_add_u32 s54, s54, 0x40000
	s_addc_u32 s55, s55, 0
	s_mov_b32 m0, s67
	ds_read_b128 v[196:199], v149 offset:32768
	ds_read_b128 v[200:203], v149 offset:33792
	ds_read_b128 v[204:207], v149 offset:34816
	ds_read_b128 v[208:211], v149 offset:35840
	ds_read_b128 v[212:215], v149 offset:36864
	ds_read_b128 v[216:219], v149 offset:37888
	ds_read_b128 v[220:223], v149 offset:38912
	ds_read_b128 v[224:227], v149 offset:39936
	global_load_lds_dwordx4 v128, s[54:55]
	s_mov_b32 m0, s69
	s_nop 0
	global_load_lds_dwordx4 v132, s[54:55]
	s_waitcnt vmcnt(8)
	s_waitcnt lgkmcnt(0)
	s_barrier
	s_setprio 1
	s_waitcnt lgkmcnt(0)
	v_mfma_f32_16x16x32_bf16 v[124:127], v[150:153], v[196:199], v[124:127]
	v_mfma_f32_16x16x32_bf16 v[120:123], v[170:173], v[196:199], v[120:123]
	v_mfma_f32_16x16x32_bf16 v[112:115], v[150:153], v[204:207], v[112:115]
	v_mfma_f32_16x16x32_bf16 v[104:107], v[170:173], v[204:207], v[104:107]
	v_mfma_f32_16x16x32_bf16 v[96:99], v[150:153], v[212:215], v[96:99]
	v_mfma_f32_16x16x32_bf16 v[88:91], v[170:173], v[212:215], v[88:91]
	v_mfma_f32_16x16x32_bf16 v[80:83], v[150:153], v[220:223], v[80:83]
	v_mfma_f32_16x16x32_bf16 v[72:75], v[170:173], v[220:223], v[72:75]
	v_mfma_f32_16x16x32_bf16 v[124:127], v[166:169], v[200:203], v[124:127]
	v_mfma_f32_16x16x32_bf16 v[120:123], v[174:177], v[200:203], v[120:123]
	v_mfma_f32_16x16x32_bf16 v[112:115], v[166:169], v[208:211], v[112:115]
	v_mfma_f32_16x16x32_bf16 v[104:107], v[174:177], v[208:211], v[104:107]
	v_mfma_f32_16x16x32_bf16 v[96:99], v[166:169], v[216:219], v[96:99]
	v_mfma_f32_16x16x32_bf16 v[88:91], v[174:177], v[216:219], v[88:91]
	v_mfma_f32_16x16x32_bf16 v[80:83], v[166:169], v[224:227], v[80:83]
	v_mfma_f32_16x16x32_bf16 v[72:75], v[174:177], v[224:227], v[72:75]
	s_setprio 0
	s_setprio 1
	v_mfma_f32_16x16x32_bf16 v[116:119], v[178:181], v[196:199], v[116:119]
	v_mfma_f32_16x16x32_bf16 v[108:111], v[188:191], v[196:199], v[108:111]
	v_mfma_f32_16x16x32_bf16 v[100:103], v[178:181], v[204:207], v[100:103]
	v_mfma_f32_16x16x32_bf16 v[92:95], v[188:191], v[204:207], v[92:95]
	v_mfma_f32_16x16x32_bf16 v[84:87], v[178:181], v[212:215], v[84:87]
	v_mfma_f32_16x16x32_bf16 v[76:79], v[188:191], v[212:215], v[76:79]
	v_mfma_f32_16x16x32_bf16 v[68:71], v[178:181], v[220:223], v[68:71]
	v_mfma_f32_16x16x32_bf16 v[64:67], v[188:191], v[220:223], v[64:67]
	v_mfma_f32_16x16x32_bf16 v[116:119], v[182:185], v[200:203], v[116:119]
	v_mfma_f32_16x16x32_bf16 v[108:111], v[192:195], v[200:203], v[108:111]
	v_mfma_f32_16x16x32_bf16 v[100:103], v[182:185], v[208:211], v[100:103]
	v_mfma_f32_16x16x32_bf16 v[92:95], v[192:195], v[208:211], v[92:95]
	v_mfma_f32_16x16x32_bf16 v[84:87], v[182:185], v[216:219], v[84:87]
	v_mfma_f32_16x16x32_bf16 v[76:79], v[192:195], v[216:219], v[76:79]
	v_mfma_f32_16x16x32_bf16 v[68:71], v[182:185], v[224:227], v[68:71]
	v_mfma_f32_16x16x32_bf16 v[64:67], v[192:195], v[224:227], v[64:67]
	s_setprio 0
	s_barrier
	s_add_i32 s54, s81, s65
	s_mov_b32 m0, s54
	ds_read_b128 v[196:199], v149 offset:49152
	ds_read_b128 v[200:203], v149 offset:50176
	ds_read_b128 v[204:207], v149 offset:51200
	ds_read_b128 v[208:211], v149 offset:52224
	ds_read_b128 v[212:215], v149 offset:53248
	ds_read_b128 v[216:219], v149 offset:54272
	ds_read_b128 v[220:223], v149 offset:55296
	ds_read_b128 v[224:227], v149 offset:56320
	global_load_lds_dwordx4 v130, s[98:99]
	s_add_i32 m0, s54, 0x2000
	s_add_u32 s52, s52, 0x40080
	s_addc_u32 s53, s53, 0
	s_add_i32 s54, s82, s65
	global_load_lds_dwordx4 v134, s[98:99]
	s_mov_b32 m0, s54
	s_nop 0
	global_load_lds_dwordx4 v130, s[52:53]
	s_add_i32 m0, s54, 0x2000
	s_nop 0
	global_load_lds_dwordx4 v134, s[52:53]
	s_mov_b32 m0, s71
	s_nop 0
	global_load_lds_dwordx4 v128, s[100:101]
	s_mov_b32 m0, s72
	s_nop 0
	global_load_lds_dwordx4 v132, s[100:101]
	s_waitcnt vmcnt(8)
	s_waitcnt lgkmcnt(0)
	s_barrier
	s_setprio 1
	s_waitcnt lgkmcnt(0)
	v_mfma_f32_16x16x32_bf16 v[60:63], v[150:153], v[196:199], v[60:63]
	v_mfma_f32_16x16x32_bf16 v[56:59], v[170:173], v[196:199], v[56:59]
	v_mfma_f32_16x16x32_bf16 v[52:55], v[150:153], v[204:207], v[52:55]
	v_mfma_f32_16x16x32_bf16 v[44:47], v[170:173], v[204:207], v[44:47]
	v_mfma_f32_16x16x32_bf16 v[36:39], v[150:153], v[212:215], v[36:39]
	v_mfma_f32_16x16x32_bf16 v[28:31], v[170:173], v[212:215], v[28:31]
	v_mfma_f32_16x16x32_bf16 v[20:23], v[150:153], v[220:223], v[20:23]
	v_mfma_f32_16x16x32_bf16 v[12:15], v[170:173], v[220:223], v[12:15]
	v_mfma_f32_16x16x32_bf16 v[60:63], v[166:169], v[200:203], v[60:63]
	v_mfma_f32_16x16x32_bf16 v[56:59], v[174:177], v[200:203], v[56:59]
	v_mfma_f32_16x16x32_bf16 v[52:55], v[166:169], v[208:211], v[52:55]
	v_mfma_f32_16x16x32_bf16 v[44:47], v[174:177], v[208:211], v[44:47]
	v_mfma_f32_16x16x32_bf16 v[36:39], v[166:169], v[216:219], v[36:39]
	v_mfma_f32_16x16x32_bf16 v[28:31], v[174:177], v[216:219], v[28:31]
	v_mfma_f32_16x16x32_bf16 v[20:23], v[166:169], v[224:227], v[20:23]
	v_mfma_f32_16x16x32_bf16 v[12:15], v[174:177], v[224:227], v[12:15]
	s_setprio 0
	s_setprio 1
	v_mfma_f32_16x16x32_bf16 v[48:51], v[178:181], v[196:199], v[48:51]
	v_mfma_f32_16x16x32_bf16 v[40:43], v[188:191], v[196:199], v[40:43]
	v_mfma_f32_16x16x32_bf16 v[32:35], v[178:181], v[204:207], v[32:35]
	v_mfma_f32_16x16x32_bf16 v[24:27], v[188:191], v[204:207], v[24:27]
	v_mfma_f32_16x16x32_bf16 v[16:19], v[178:181], v[212:215], v[16:19]
	v_mfma_f32_16x16x32_bf16 v[8:11], v[188:191], v[212:215], v[8:11]
	v_mfma_f32_16x16x32_bf16 v[4:7], v[178:181], v[220:223], v[4:7]
	v_mfma_f32_16x16x32_bf16 v[0:3], v[188:191], v[220:223], v[0:3]
	v_mfma_f32_16x16x32_bf16 v[48:51], v[182:185], v[200:203], v[48:51]
	v_mfma_f32_16x16x32_bf16 v[40:43], v[192:195], v[200:203], v[40:43]
	v_mfma_f32_16x16x32_bf16 v[32:35], v[182:185], v[208:211], v[32:35]
	v_mfma_f32_16x16x32_bf16 v[24:27], v[192:195], v[208:211], v[24:27]
	v_mfma_f32_16x16x32_bf16 v[16:19], v[182:185], v[216:219], v[16:19]
	v_mfma_f32_16x16x32_bf16 v[8:11], v[192:195], v[216:219], v[8:11]
	v_mfma_f32_16x16x32_bf16 v[4:7], v[182:185], v[224:227], v[4:7]
	v_mfma_f32_16x16x32_bf16 v[0:3], v[192:195], v[224:227], v[0:3]
	s_setprio 0
	s_barrier
	s_add_i32 s80, s80, 2
	s_add_u32 s50, s50, 0x100
	s_addc_u32 s51, s51, 0
	s_add_u32 s78, s78, 0x100
	s_addc_u32 s79, s79, 0
	s_cmp_gt_u32 s80, 13
	s_cbranch_scc0 .LBB0_204
	s_and_b64 vcc, exec, s[10:11]
	s_cbranch_vccz .LBB0_207
	s_barrier

; #define PG8_STAGE(bufoff, gbase, voff) do { _Pragma("unroll") for (int _i = 0; _i < 2; ++_i) \
;         __builtin_amdgcn_global_load_lds((const unsigned*)((const char*)(gbase) + (voff)[_i]), (PG8_LAS unsigned*)(lds + (bufoff) + ldsw + _i * 8192), 16, 0, 0); } while (0)
; #define PG8_LDA(dst, b, h) do { _Pragma("unroll") for (int m = 0; m < 4; ++m) _Pragma("unroll") for (int k = 0; k < 2; ++k) dst[m][k] = *(const PG8_LAS bf16x8*)(lds + PG8_SA(b, h) + aoff + m * 2048 + k * 1024); } while (0)
; #define PG8_LDB(dst, b, h) do { _Pragma("unroll") for (int n = 0; n < 2; ++n) _Pragma("unroll") for (int k = 0; k < 2; ++k) dst[n][k] = *(const PG8_LAS bf16x8*)(lds + PG8_SB(b, h) + boff + n * 2048 + k * 1024); } while (0)
; #define PG8_MMA(ai, bj, At, Bt) do { __builtin_amdgcn_s_setprio(1); _Pragma("unroll") for (int m = 0; m < 4; ++m) _Pragma("unroll") for (int n = 0; n < 2; ++n) _Pragma("unroll") for (int k = 0; k < 2; ++k) \
;         acc[ai][bj][m][n] = __builtin_amdgcn_mfma_f32_16x16x32_bf16(Bt[n][k], At[m][k], acc[ai][bj][m][n], 0, 0, 0); __builtin_amdgcn_s_setprio(0); } while (0)
; #define PG8_WAIT_V(n) asm volatile("s_waitcnt vmcnt(" #n ")" ::: "memory")
; #define PG8_WAIT_L(n) asm volatile("s_waitcnt lgkmcnt(" #n ")" ::: "memory")
; template <class Epi, class Sched, bool ALIGN_EPI = false, bool SP2 = false>
; __device__ __forceinline__ void gemm_phase(PG8_LAS unsigned char* lds, const Gemm g, const Sched S, const Epi E, const int tid) {
;     ...
;             const bool last = (t == nt - 2);
;             const char* a1 = cA + (size_t)(t + 1) * kstep;
;             const char* a2 = last ? nA : cA + (size_t)(t + 2) * kstep; const char* b2 = last ? nB : cB + (size_t)(t + 2) * kstep;
;             const char* a3 = a2 + kstep; const char* b3 = b2 + kstep;
;             if (last && has_next) S.a_ready(nxt);
;             if constexpr (SP2) {
;             PG8_LDB(B0, 0, 0); PG8_LDB(B1, 0, 1); PG8_SCHED; PG8_LDA(At, 0, 0); PG8_STAGE(PG8_SA(1, 1), a1 + hstepA, voffA);
;             PG8_WAIT_V(8); PG8_WAIT_L(0); PG8_BAR; PG8_MMA(0, 0, At, B0); PG8_MMA(0, 1, At, B1); PG8_BAR; PG8_SCHED;
;             PG8_LDA(At, 0, 1); PG8_STAGE(PG8_SB(0, 0), b2, voffB); PG8_STAGE(PG8_SB(0, 1), b2 + hstepB, voffB); PG8_STAGE(PG8_SA(0, 0), a2, voffA);
;             PG8_WAIT_V(8); PG8_WAIT_L(0); PG8_BAR; PG8_MMA(1, 0, At, B0); PG8_MMA(1, 1, At, B1); PG8_BAR; PG8_SCHED;
.LBB0_220:
	ds_read_b128 v[148:151], v145
	ds_read_b128 v[152:155], v145 offset:1024
	ds_read_b128 v[156:159], v145 offset:2048
	ds_read_b128 v[160:163], v145 offset:3072
	ds_read_b128 v[164:167], v146
	ds_read_b128 v[168:171], v146 offset:1024
	ds_read_b128 v[172:175], v146 offset:2048
	ds_read_b128 v[176:179], v146 offset:3072
	s_add_u32 s52, s50, 0xfffc0080
	s_addc_u32 s53, s51, -1
	s_cmp_eq_u32 s77, 12
	s_cselect_b32 s55, s37, s53
	s_cselect_b32 s54, s73, s52
	s_cselect_b32 s53, s35, s76
	s_cselect_b32 s52, s74, s75
	s_add_i32 m0, s49, 0xc000
	ds_read_b128 v[180:183], v147
	ds_read_b128 v[188:191], v147 offset:1024
	ds_read_b128 v[192:195], v147 offset:2048
	ds_read_b128 v[196:199], v147 offset:3072
	ds_read_b128 v[200:203], v147 offset:4096
	ds_read_b128 v[204:207], v147 offset:5120
	ds_read_b128 v[208:211], v147 offset:6144
	ds_read_b128 v[212:215], v147 offset:7168
	global_load_lds_dwordx4 v136, s[50:51]
	s_add_i32 m0, s49, 0xe000
	s_nop 0
	global_load_lds_dwordx4 v138, s[50:51]
	s_waitcnt vmcnt(8)
	s_waitcnt lgkmcnt(0)
	s_barrier
	s_setprio 1
	s_waitcnt lgkmcnt(0)
	v_mfma_f32_16x16x32_bf16 v[124:127], v[148:151], v[180:183], v[124:127]
	v_mfma_f32_16x16x32_bf16 v[120:123], v[156:159], v[180:183], v[120:123]
	v_mfma_f32_16x16x32_bf16 v[112:115], v[148:151], v[192:195], v[112:115]
	v_mfma_f32_16x16x32_bf16 v[104:107], v[156:159], v[192:195], v[104:107]
	v_mfma_f32_16x16x32_bf16 v[96:99], v[148:151], v[200:203], v[96:99]
	v_mfma_f32_16x16x32_bf16 v[88:91], v[156:159], v[200:203], v[88:91]
	v_mfma_f32_16x16x32_bf16 v[80:83], v[148:151], v[208:211], v[80:83]
	v_mfma_f32_16x16x32_bf16 v[72:75], v[156:159], v[208:211], v[72:75]
	v_mfma_f32_16x16x32_bf16 v[124:127], v[152:155], v[188:191], v[124:127]
	v_mfma_f32_16x16x32_bf16 v[120:123], v[160:163], v[188:191], v[120:123]
	v_mfma_f32_16x16x32_bf16 v[112:115], v[152:155], v[196:199], v[112:115]
	v_mfma_f32_16x16x32_bf16 v[104:107], v[160:163], v[196:199], v[104:107]
	v_mfma_f32_16x16x32_bf16 v[96:99], v[152:155], v[204:207], v[96:99]
	v_mfma_f32_16x16x32_bf16 v[88:91], v[160:163], v[204:207], v[88:91]
	v_mfma_f32_16x16x32_bf16 v[80:83], v[152:155], v[212:215], v[80:83]
	v_mfma_f32_16x16x32_bf16 v[72:75], v[160:163], v[212:215], v[72:75]
	s_setprio 0
	s_setprio 1
	v_mfma_f32_16x16x32_bf16 v[116:119], v[164:167], v[180:183], v[116:119]
	v_mfma_f32_16x16x32_bf16 v[108:111], v[172:175], v[180:183], v[108:111]
	v_mfma_f32_16x16x32_bf16 v[100:103], v[164:167], v[192:195], v[100:103]
	v_mfma_f32_16x16x32_bf16 v[92:95], v[172:175], v[192:195], v[92:95]
	v_mfma_f32_16x16x32_bf16 v[84:87], v[164:167], v[200:203], v[84:87]
	v_mfma_f32_16x16x32_bf16 v[76:79], v[172:175], v[200:203], v[76:79]
	v_mfma_f32_16x16x32_bf16 v[68:71], v[164:167], v[208:211], v[68:71]
	v_mfma_f32_16x16x32_bf16 v[64:67], v[172:175], v[208:211], v[64:67]
	v_mfma_f32_16x16x32_bf16 v[116:119], v[168:171], v[188:191], v[116:119]
	v_mfma_f32_16x16x32_bf16 v[108:111], v[176:179], v[188:191], v[108:111]
	v_mfma_f32_16x16x32_bf16 v[100:103], v[168:171], v[196:199], v[100:103]
	v_mfma_f32_16x16x32_bf16 v[92:95], v[176:179], v[196:199], v[92:95]
	v_mfma_f32_16x16x32_bf16 v[84:87], v[168:171], v[204:207], v[84:87]
	v_mfma_f32_16x16x32_bf16 v[76:79], v[176:179], v[204:207], v[76:79]
	v_mfma_f32_16x16x32_bf16 v[68:71], v[168:171], v[212:215], v[68:71]
	v_mfma_f32_16x16x32_bf16 v[64:67], v[176:179], v[212:215], v[64:67]
	s_setprio 0
	s_barrier
	s_add_u32 s98, s52, 0x80
	s_addc_u32 s99, s53, 0
	s_add_u32 s100, s54, 0x80
	s_addc_u32 s101, s55, 0
	s_add_i32 s78, s70, s62
	s_mov_b32 m0, s78
	ds_read_b128 v[180:183], v147 offset:16384
	ds_read_b128 v[188:191], v147 offset:17408
	ds_read_b128 v[192:195], v147 offset:18432
	ds_read_b128 v[196:199], v147 offset:19456
	ds_read_b128 v[200:203], v147 offset:20480
	ds_read_b128 v[204:207], v147 offset:21504
	ds_read_b128 v[208:211], v147 offset:22528
	ds_read_b128 v[212:215], v147 offset:23552
	global_load_lds_dwordx4 v130, s[52:53]
	s_add_i32 m0, s78, 0x2000
	s_add_u32 s78, s52, 0x40000
	s_addc_u32 s79, s53, 0
	s_add_i32 s80, s71, s62
	global_load_lds_dwordx4 v134, s[52:53]
	s_mov_b32 m0, s80
	s_nop 0
	global_load_lds_dwordx4 v130, s[78:79]
	s_add_i32 m0, s80, 0x2000
	s_nop 0
	global_load_lds_dwordx4 v134, s[78:79]
	s_mov_b32 m0, s49
	s_nop 0
	global_load_lds_dwordx4 v128, s[54:55]
	s_mov_b32 m0, s63
	s_nop 0
	global_load_lds_dwordx4 v132, s[54:55]
	s_waitcnt vmcnt(8)
	s_waitcnt lgkmcnt(0)
	s_barrier
	s_setprio 1
	s_waitcnt lgkmcnt(0)
	v_mfma_f32_16x16x32_bf16 v[60:63], v[148:151], v[180:183], v[60:63]
	v_mfma_f32_16x16x32_bf16 v[56:59], v[156:159], v[180:183], v[56:59]
	v_mfma_f32_16x16x32_bf16 v[52:55], v[148:151], v[192:195], v[52:55]
	v_mfma_f32_16x16x32_bf16 v[44:47], v[156:159], v[192:195], v[44:47]
	v_mfma_f32_16x16x32_bf16 v[36:39], v[148:151], v[200:203], v[36:39]
	v_mfma_f32_16x16x32_bf16 v[28:31], v[156:159], v[200:203], v[28:31]
	v_mfma_f32_16x16x32_bf16 v[20:23], v[148:151], v[208:211], v[20:23]
	v_mfma_f32_16x16x32_bf16 v[12:15], v[156:159], v[208:211], v[12:15]
	v_mfma_f32_16x16x32_bf16 v[60:63], v[152:155], v[188:191], v[60:63]
	v_mfma_f32_16x16x32_bf16 v[56:59], v[160:163], v[188:191], v[56:59]
	v_mfma_f32_16x16x32_bf16 v[52:55], v[152:155], v[196:199], v[52:55]
	v_mfma_f32_16x16x32_bf16 v[44:47], v[160:163], v[196:199], v[44:47]
	v_mfma_f32_16x16x32_bf16 v[36:39], v[152:155], v[204:207], v[36:39]
	v_mfma_f32_16x16x32_bf16 v[28:31], v[160:163], v[204:207], v[28:31]
	v_mfma_f32_16x16x32_bf16 v[20:23], v[152:155], v[212:215], v[20:23]
	v_mfma_f32_16x16x32_bf16 v[12:15], v[160:163], v[212:215], v[12:15]
	s_setprio 0
	s_setprio 1
	v_mfma_f32_16x16x32_bf16 v[48:51], v[164:167], v[180:183], v[48:51]
	v_mfma_f32_16x16x32_bf16 v[40:43], v[172:175], v[180:183], v[40:43]
	v_mfma_f32_16x16x32_bf16 v[32:35], v[164:167], v[192:195], v[32:35]
	v_mfma_f32_16x16x32_bf16 v[24:27], v[172:175], v[192:195], v[24:27]
	v_mfma_f32_16x16x32_bf16 v[16:19], v[164:167], v[200:203], v[16:19]
	v_mfma_f32_16x16x32_bf16 v[8:11], v[172:175], v[200:203], v[8:11]
	v_mfma_f32_16x16x32_bf16 v[4:7], v[164:167], v[208:211], v[4:7]
	v_mfma_f32_16x16x32_bf16 v[0:3], v[172:175], v[208:211], v[0:3]
	v_mfma_f32_16x16x32_bf16 v[48:51], v[168:171], v[188:191], v[48:51]
	v_mfma_f32_16x16x32_bf16 v[40:43], v[176:179], v[188:191], v[40:43]
	v_mfma_f32_16x16x32_bf16 v[32:35], v[168:171], v[196:199], v[32:35]
	v_mfma_f32_16x16x32_bf16 v[24:27], v[176:179], v[196:199], v[24:27]
	v_mfma_f32_16x16x32_bf16 v[16:19], v[168:171], v[204:207], v[16:19]
	v_mfma_f32_16x16x32_bf16 v[8:11], v[176:179], v[204:207], v[8:11]
	v_mfma_f32_16x16x32_bf16 v[4:7], v[168:171], v[212:215], v[4:7]
	v_mfma_f32_16x16x32_bf16 v[0:3], v[176:179], v[212:215], v[0:3]
	s_setprio 0
	s_barrier
; #define PG8_STAGE(bufoff, gbase, voff) do { _Pragma("unroll") for (int _i = 0; _i < 2; ++_i) \
;         __builtin_amdgcn_global_load_lds((const unsigned*)((const char*)(gbase) + (voff)[_i]), (PG8_LAS unsigned*)(lds + (bufoff) + ldsw + _i * 8192), 16, 0, 0); } while (0)
; #define PG8_LDA(dst, b, h) do { _Pragma("unroll") for (int m = 0; m < 4; ++m) _Pragma("unroll") for (int k = 0; k < 2; ++k) dst[m][k] = *(const PG8_LAS bf16x8*)(lds + PG8_SA(b, h) + aoff + m * 2048 + k * 1024); } while (0)
; #define PG8_LDB(dst, b, h) do { _Pragma("unroll") for (int n = 0; n < 2; ++n) _Pragma("unroll") for (int k = 0; k < 2; ++k) dst[n][k] = *(const PG8_LAS bf16x8*)(lds + PG8_SB(b, h) + boff + n * 2048 + k * 1024); } while (0)
; #define PG8_MMA(ai, bj, At, Bt) do { __builtin_amdgcn_s_setprio(1); _Pragma("unroll") for (int m = 0; m < 4; ++m) _Pragma("unroll") for (int n = 0; n < 2; ++n) _Pragma("unroll") for (int k = 0; k < 2; ++k) \
;         acc[ai][bj][m][n] = __builtin_amdgcn_mfma_f32_16x16x32_bf16(Bt[n][k], At[m][k], acc[ai][bj][m][n], 0, 0, 0); __builtin_amdgcn_s_setprio(0); } while (0)
; #define PG8_WAIT_V(n) asm volatile("s_waitcnt vmcnt(" #n ")" ::: "memory")
; #define PG8_WAIT_L(n) asm volatile("s_waitcnt lgkmcnt(" #n ")" ::: "memory")
; #define PG8_BAR __builtin_amdgcn_s_barrier()
; #define PG8_SCHED __builtin_amdgcn_sched_barrier(0)
; template <class Epi, class Sched, bool ALIGN_EPI = false, bool SP2 = false>
; __device__ __forceinline__ void gemm_phase(PG8_LAS unsigned char* lds, const Gemm g, const Sched S, const Epi E, const int tid) {
;     ...
;             PG8_LDB(B0, 1, 0); PG8_LDB(B1, 1, 1); PG8_SCHED; PG8_LDA(At, 1, 0); PG8_STAGE(PG8_SA(0, 1), a2 + hstepA, voffA);
;             PG8_WAIT_V(8); PG8_WAIT_L(0); PG8_BAR; PG8_MMA(0, 0, At, B0); PG8_MMA(0, 1, At, B1); PG8_BAR; PG8_SCHED;
;             PG8_LDA(At, 1, 1); PG8_STAGE(PG8_SB(1, 0), b3, voffB); PG8_STAGE(PG8_SB(1, 1), b3 + hstepB, voffB); PG8_STAGE(PG8_SA(1, 0), a3, voffA);
;             PG8_WAIT_V(8); PG8_WAIT_L(0); PG8_BAR; PG8_MMA(1, 0, At, B0); PG8_MMA(1, 1, At, B1); PG8_BAR; PG8_SCHED;
	s_add_i32 s78, 0, 0x18000
	s_add_i32 s79, 0, 0x1c000
	v_add_u32_e32 v160, s78, v143
	v_add_u32_e32 v176, s79, v143
	ds_read_b128 v[148:151], v160
	ds_read_b128 v[152:155], v160 offset:1024
	ds_read_b128 v[156:159], v160 offset:2048
	ds_read_b128 v[160:163], v160 offset:3072
	ds_read_b128 v[164:167], v176
	ds_read_b128 v[168:171], v176 offset:1024
	ds_read_b128 v[172:175], v176 offset:2048
	ds_read_b128 v[176:179], v176 offset:3072
	s_add_u32 s54, s54, 0x40000
	s_addc_u32 s55, s55, 0
	s_mov_b32 m0, s64
	ds_read_b128 v[180:183], v147 offset:32768
	ds_read_b128 v[188:191], v147 offset:33792
	ds_read_b128 v[192:195], v147 offset:34816
	ds_read_b128 v[196:199], v147 offset:35840
	ds_read_b128 v[200:203], v147 offset:36864
	ds_read_b128 v[204:207], v147 offset:37888
	ds_read_b128 v[208:211], v147 offset:38912
	ds_read_b128 v[212:215], v147 offset:39936
	global_load_lds_dwordx4 v128, s[54:55]
	s_mov_b32 m0, s65
	s_nop 0
	global_load_lds_dwordx4 v132, s[54:55]
	s_waitcnt vmcnt(8)
	s_waitcnt lgkmcnt(0)
	s_barrier
	s_setprio 1
	s_waitcnt lgkmcnt(0)
	v_mfma_f32_16x16x32_bf16 v[124:127], v[148:151], v[180:183], v[124:127]
	v_mfma_f32_16x16x32_bf16 v[120:123], v[156:159], v[180:183], v[120:123]
	v_mfma_f32_16x16x32_bf16 v[112:115], v[148:151], v[192:195], v[112:115]
	v_mfma_f32_16x16x32_bf16 v[104:107], v[156:159], v[192:195], v[104:107]
	v_mfma_f32_16x16x32_bf16 v[96:99], v[148:151], v[200:203], v[96:99]
	v_mfma_f32_16x16x32_bf16 v[88:91], v[156:159], v[200:203], v[88:91]
	v_mfma_f32_16x16x32_bf16 v[80:83], v[148:151], v[208:211], v[80:83]
	v_mfma_f32_16x16x32_bf16 v[72:75], v[156:159], v[208:211], v[72:75]
	v_mfma_f32_16x16x32_bf16 v[124:127], v[152:155], v[188:191], v[124:127]
	v_mfma_f32_16x16x32_bf16 v[120:123], v[160:163], v[188:191], v[120:123]
	v_mfma_f32_16x16x32_bf16 v[112:115], v[152:155], v[196:199], v[112:115]
	v_mfma_f32_16x16x32_bf16 v[104:107], v[160:163], v[196:199], v[104:107]
	v_mfma_f32_16x16x32_bf16 v[96:99], v[152:155], v[204:207], v[96:99]
	v_mfma_f32_16x16x32_bf16 v[88:91], v[160:163], v[204:207], v[88:91]
	v_mfma_f32_16x16x32_bf16 v[80:83], v[152:155], v[212:215], v[80:83]
	v_mfma_f32_16x16x32_bf16 v[72:75], v[160:163], v[212:215], v[72:75]
	s_setprio 0
	s_setprio 1
	v_mfma_f32_16x16x32_bf16 v[116:119], v[164:167], v[180:183], v[116:119]
	v_mfma_f32_16x16x32_bf16 v[108:111], v[172:175], v[180:183], v[108:111]
	v_mfma_f32_16x16x32_bf16 v[100:103], v[164:167], v[192:195], v[100:103]
	v_mfma_f32_16x16x32_bf16 v[92:95], v[172:175], v[192:195], v[92:95]
	v_mfma_f32_16x16x32_bf16 v[84:87], v[164:167], v[200:203], v[84:87]
	v_mfma_f32_16x16x32_bf16 v[76:79], v[172:175], v[200:203], v[76:79]
	v_mfma_f32_16x16x32_bf16 v[68:71], v[164:167], v[208:211], v[68:71]
	v_mfma_f32_16x16x32_bf16 v[64:67], v[172:175], v[208:211], v[64:67]
	v_mfma_f32_16x16x32_bf16 v[116:119], v[168:171], v[188:191], v[116:119]
	v_mfma_f32_16x16x32_bf16 v[108:111], v[176:179], v[188:191], v[108:111]
	v_mfma_f32_16x16x32_bf16 v[100:103], v[168:171], v[196:199], v[100:103]
	v_mfma_f32_16x16x32_bf16 v[92:95], v[176:179], v[196:199], v[92:95]
	v_mfma_f32_16x16x32_bf16 v[84:87], v[168:171], v[204:207], v[84:87]
	v_mfma_f32_16x16x32_bf16 v[76:79], v[176:179], v[204:207], v[76:79]
	v_mfma_f32_16x16x32_bf16 v[68:71], v[168:171], v[212:215], v[68:71]
	v_mfma_f32_16x16x32_bf16 v[64:67], v[176:179], v[212:215], v[64:67]
	s_setprio 0
	s_barrier
	s_add_i32 s54, s78, s62
	s_mov_b32 m0, s54
	ds_read_b128 v[180:183], v147 offset:49152
	ds_read_b128 v[188:191], v147 offset:50176
	ds_read_b128 v[192:195], v147 offset:51200
	ds_read_b128 v[196:199], v147 offset:52224
	ds_read_b128 v[200:203], v147 offset:53248
	ds_read_b128 v[204:207], v147 offset:54272
	ds_read_b128 v[208:211], v147 offset:55296
	ds_read_b128 v[212:215], v147 offset:56320
	global_load_lds_dwordx4 v130, s[98:99]
	s_add_i32 m0, s54, 0x2000
	s_add_u32 s52, s52, 0x40080
	s_addc_u32 s53, s53, 0
	s_add_i32 s54, s79, s62
	global_load_lds_dwordx4 v134, s[98:99]
	s_mov_b32 m0, s54
	s_nop 0
	global_load_lds_dwordx4 v130, s[52:53]
	s_add_i32 m0, s54, 0x2000
	s_nop 0
	global_load_lds_dwordx4 v134, s[52:53]
	s_mov_b32 m0, s67
	s_nop 0
	global_load_lds_dwordx4 v128, s[100:101]
	s_mov_b32 m0, s69
	s_nop 0
	global_load_lds_dwordx4 v132, s[100:101]
	s_waitcnt vmcnt(8)
	s_waitcnt lgkmcnt(0)
	s_barrier
	s_setprio 1
	s_waitcnt lgkmcnt(0)
	v_mfma_f32_16x16x32_bf16 v[60:63], v[148:151], v[180:183], v[60:63]
	v_mfma_f32_16x16x32_bf16 v[56:59], v[156:159], v[180:183], v[56:59]
	v_mfma_f32_16x16x32_bf16 v[52:55], v[148:151], v[192:195], v[52:55]
	v_mfma_f32_16x16x32_bf16 v[44:47], v[156:159], v[192:195], v[44:47]
	v_mfma_f32_16x16x32_bf16 v[36:39], v[148:151], v[200:203], v[36:39]
	v_mfma_f32_16x16x32_bf16 v[28:31], v[156:159], v[200:203], v[28:31]
	v_mfma_f32_16x16x32_bf16 v[20:23], v[148:151], v[208:211], v[20:23]
	v_mfma_f32_16x16x32_bf16 v[12:15], v[156:159], v[208:211], v[12:15]
	v_mfma_f32_16x16x32_bf16 v[60:63], v[152:155], v[188:191], v[60:63]
	v_mfma_f32_16x16x32_bf16 v[56:59], v[160:163], v[188:191], v[56:59]
	v_mfma_f32_16x16x32_bf16 v[52:55], v[152:155], v[196:199], v[52:55]
	v_mfma_f32_16x16x32_bf16 v[44:47], v[160:163], v[196:199], v[44:47]
	v_mfma_f32_16x16x32_bf16 v[36:39], v[152:155], v[204:207], v[36:39]
	v_mfma_f32_16x16x32_bf16 v[28:31], v[160:163], v[204:207], v[28:31]
	v_mfma_f32_16x16x32_bf16 v[20:23], v[152:155], v[212:215], v[20:23]
	v_mfma_f32_16x16x32_bf16 v[12:15], v[160:163], v[212:215], v[12:15]
	s_setprio 0
	s_setprio 1
	v_mfma_f32_16x16x32_bf16 v[48:51], v[164:167], v[180:183], v[48:51]
	v_mfma_f32_16x16x32_bf16 v[40:43], v[172:175], v[180:183], v[40:43]
	v_mfma_f32_16x16x32_bf16 v[32:35], v[164:167], v[192:195], v[32:35]
	v_mfma_f32_16x16x32_bf16 v[24:27], v[172:175], v[192:195], v[24:27]
	v_mfma_f32_16x16x32_bf16 v[16:19], v[164:167], v[200:203], v[16:19]
	v_mfma_f32_16x16x32_bf16 v[8:11], v[172:175], v[200:203], v[8:11]
	v_mfma_f32_16x16x32_bf16 v[4:7], v[164:167], v[208:211], v[4:7]
	v_mfma_f32_16x16x32_bf16 v[0:3], v[172:175], v[208:211], v[0:3]
	v_mfma_f32_16x16x32_bf16 v[48:51], v[168:171], v[188:191], v[48:51]
	v_mfma_f32_16x16x32_bf16 v[40:43], v[176:179], v[188:191], v[40:43]
	v_mfma_f32_16x16x32_bf16 v[32:35], v[168:171], v[196:199], v[32:35]
	v_mfma_f32_16x16x32_bf16 v[24:27], v[176:179], v[196:199], v[24:27]
	v_mfma_f32_16x16x32_bf16 v[16:19], v[168:171], v[204:207], v[16:19]
	v_mfma_f32_16x16x32_bf16 v[8:11], v[176:179], v[204:207], v[8:11]
	v_mfma_f32_16x16x32_bf16 v[4:7], v[168:171], v[212:215], v[4:7]
	v_mfma_f32_16x16x32_bf16 v[0:3], v[176:179], v[212:215], v[0:3]
	s_setprio 0
	s_barrier
	s_add_i32 s77, s77, 2
	s_add_u32 s50, s50, 0x100
	s_addc_u32 s51, s51, 0
	s_add_u32 s75, s75, 0x100
	s_addc_u32 s76, s76, 0
	s_cmp_gt_u32 s77, 13
	s_cbranch_scc0 .LBB0_220
	s_and_b64 vcc, exec, s[8:9]
	s_cbranch_vccz .LBB0_223
	s_barrier

; #define PG8_STAGE(bufoff, gbase, voff) do { _Pragma("unroll") for (int _i = 0; _i < 2; ++_i) \
;         __builtin_amdgcn_global_load_lds((const unsigned*)((const char*)(gbase) + (voff)[_i]), (PG8_LAS unsigned*)(lds + (bufoff) + ldsw + _i * 8192), 16, 0, 0); } while (0)
; #define PG8_LDA(dst, b, h) do { _Pragma("unroll") for (int m = 0; m < 4; ++m) _Pragma("unroll") for (int k = 0; k < 2; ++k) dst[m][k] = *(const PG8_LAS bf16x8*)(lds + PG8_SA(b, h) + aoff + m * 2048 + k * 1024); } while (0)
; #define PG8_LDB(dst, b, h) do { _Pragma("unroll") for (int n = 0; n < 2; ++n) _Pragma("unroll") for (int k = 0; k < 2; ++k) dst[n][k] = *(const PG8_LAS bf16x8*)(lds + PG8_SB(b, h) + boff + n * 2048 + k * 1024); } while (0)
; #define PG8_MMA(ai, bj, At, Bt) do { __builtin_amdgcn_s_setprio(1); _Pragma("unroll") for (int m = 0; m < 4; ++m) _Pragma("unroll") for (int n = 0; n < 2; ++n) _Pragma("unroll") for (int k = 0; k < 2; ++k) \
;         acc[ai][bj][m][n] = __builtin_amdgcn_mfma_f32_16x16x32_bf16(Bt[n][k], At[m][k], acc[ai][bj][m][n], 0, 0, 0); __builtin_amdgcn_s_setprio(0); } while (0)
; #define PG8_WAIT_V(n) asm volatile("s_waitcnt vmcnt(" #n ")" ::: "memory")
; #define PG8_WAIT_L(n) asm volatile("s_waitcnt lgkmcnt(" #n ")" ::: "memory")
; template <class Epi, class Sched, bool ALIGN_EPI = false, bool SP2 = false>
; __device__ __forceinline__ void gemm_phase(PG8_LAS unsigned char* lds, const Gemm g, const Sched S, const Epi E, const int tid) {
;     ...
;             const bool last = (t == nt - 2);
;             const char* a1 = cA + (size_t)(t + 1) * kstep;
;             const char* a2 = last ? nA : cA + (size_t)(t + 2) * kstep; const char* b2 = last ? nB : cB + (size_t)(t + 2) * kstep;
;             const char* a3 = a2 + kstep; const char* b3 = b2 + kstep;
;             if (last && has_next) S.a_ready(nxt);
;             if constexpr (SP2) {
;             PG8_LDB(B0, 0, 0); PG8_LDB(B1, 0, 1); PG8_SCHED; PG8_LDA(At, 0, 0); PG8_STAGE(PG8_SA(1, 1), a1 + hstepA, voffA);
;             PG8_WAIT_V(8); PG8_WAIT_L(0); PG8_BAR; PG8_MMA(0, 0, At, B0); PG8_MMA(0, 1, At, B1); PG8_BAR; PG8_SCHED;
;             PG8_LDA(At, 0, 1); PG8_STAGE(PG8_SB(0, 0), b2, voffB); PG8_STAGE(PG8_SB(0, 1), b2 + hstepB, voffB); PG8_STAGE(PG8_SA(0, 0), a2, voffA);
;             PG8_WAIT_V(8); PG8_WAIT_L(0); PG8_BAR; PG8_MMA(1, 0, At, B0); PG8_MMA(1, 1, At, B1); PG8_BAR; PG8_SCHED;
.LBB0_297:
	v_add_u32_e32 v162, s64, v149
	v_add_u32_e32 v178, s65, v149
	ds_read_b128 v[144:147], v162
	ds_read_b128 v[154:157], v162 offset:1024
	ds_read_b128 v[158:161], v162 offset:2048
	ds_read_b128 v[162:165], v162 offset:3072
	ds_read_b128 v[166:169], v178
	ds_read_b128 v[170:173], v178 offset:1024
	ds_read_b128 v[174:177], v178 offset:2048
	ds_read_b128 v[178:181], v178 offset:3072
	s_add_u32 s34, s30, 0x100
	s_addc_u32 s35, s31, 0
	s_cmp_eq_u32 s73, 40
	s_cselect_b32 s39, s7, s35
	s_cselect_b32 s38, s6, s34
	s_cselect_b32 s37, s29, s72
	s_cselect_b32 s36, s28, s71
	s_add_i32 m0, s54, 0xc000
	ds_read_b128 v[182:185], v153
	ds_read_b128 v[188:191], v153 offset:1024
	ds_read_b128 v[192:195], v153 offset:2048
	ds_read_b128 v[196:199], v153 offset:3072
	ds_read_b128 v[200:203], v153 offset:4096
	ds_read_b128 v[204:207], v153 offset:5120
	ds_read_b128 v[208:211], v153 offset:6144
	ds_read_b128 v[212:215], v153 offset:7168
	global_load_lds_dwordx4 v136, s[30:31]
	s_add_i32 m0, s54, 0xe000
	s_nop 0
	global_load_lds_dwordx4 v138, s[30:31]
	s_waitcnt vmcnt(8)
	s_waitcnt lgkmcnt(0)
	s_barrier
	s_setprio 1
	s_waitcnt lgkmcnt(0)
	v_mfma_f32_16x16x32_bf16 v[112:115], v[144:147], v[182:185], v[112:115]
	v_mfma_f32_16x16x32_bf16 v[120:123], v[158:161], v[182:185], v[120:123]
	v_mfma_f32_16x16x32_bf16 v[96:99], v[144:147], v[192:195], v[96:99]
	v_mfma_f32_16x16x32_bf16 v[104:107], v[158:161], v[192:195], v[104:107]
	v_mfma_f32_16x16x32_bf16 v[80:83], v[144:147], v[200:203], v[80:83]
	v_mfma_f32_16x16x32_bf16 v[88:91], v[158:161], v[200:203], v[88:91]
	v_mfma_f32_16x16x32_bf16 v[64:67], v[144:147], v[208:211], v[64:67]
	v_mfma_f32_16x16x32_bf16 v[72:75], v[158:161], v[208:211], v[72:75]
	v_mfma_f32_16x16x32_bf16 v[112:115], v[154:157], v[188:191], v[112:115]
	v_mfma_f32_16x16x32_bf16 v[120:123], v[162:165], v[188:191], v[120:123]
	v_mfma_f32_16x16x32_bf16 v[96:99], v[154:157], v[196:199], v[96:99]
	v_mfma_f32_16x16x32_bf16 v[104:107], v[162:165], v[196:199], v[104:107]
	v_mfma_f32_16x16x32_bf16 v[80:83], v[154:157], v[204:207], v[80:83]
	v_mfma_f32_16x16x32_bf16 v[88:91], v[162:165], v[204:207], v[88:91]
	v_mfma_f32_16x16x32_bf16 v[64:67], v[154:157], v[212:215], v[64:67]
	v_mfma_f32_16x16x32_bf16 v[72:75], v[162:165], v[212:215], v[72:75]
	s_setprio 0
	s_setprio 1
	v_mfma_f32_16x16x32_bf16 v[116:119], v[166:169], v[182:185], v[116:119]
	v_mfma_f32_16x16x32_bf16 v[124:127], v[174:177], v[182:185], v[124:127]
	v_mfma_f32_16x16x32_bf16 v[100:103], v[166:169], v[192:195], v[100:103]
	v_mfma_f32_16x16x32_bf16 v[108:111], v[174:177], v[192:195], v[108:111]
	v_mfma_f32_16x16x32_bf16 v[84:87], v[166:169], v[200:203], v[84:87]
	v_mfma_f32_16x16x32_bf16 v[92:95], v[174:177], v[200:203], v[92:95]
	v_mfma_f32_16x16x32_bf16 v[68:71], v[166:169], v[208:211], v[68:71]
	v_mfma_f32_16x16x32_bf16 v[76:79], v[174:177], v[208:211], v[76:79]
	v_mfma_f32_16x16x32_bf16 v[116:119], v[170:173], v[188:191], v[116:119]
	v_mfma_f32_16x16x32_bf16 v[124:127], v[178:181], v[188:191], v[124:127]
	v_mfma_f32_16x16x32_bf16 v[100:103], v[170:173], v[196:199], v[100:103]
	v_mfma_f32_16x16x32_bf16 v[108:111], v[178:181], v[196:199], v[108:111]
	v_mfma_f32_16x16x32_bf16 v[84:87], v[170:173], v[204:207], v[84:87]
	v_mfma_f32_16x16x32_bf16 v[92:95], v[178:181], v[204:207], v[92:95]
	v_mfma_f32_16x16x32_bf16 v[68:71], v[170:173], v[212:215], v[68:71]
	v_mfma_f32_16x16x32_bf16 v[76:79], v[178:181], v[212:215], v[76:79]
	s_setprio 0
	s_barrier
	s_add_u32 s98, s36, 0x80
	s_addc_u32 s99, s37, 0
	s_add_u32 s100, s38, 0x80
	s_addc_u32 s101, s39, 0
	s_add_i32 s30, s64, s51
	s_mov_b32 m0, s30
	ds_read_b128 v[182:185], v153 offset:16384
	ds_read_b128 v[188:191], v153 offset:17408
	ds_read_b128 v[192:195], v153 offset:18432
	ds_read_b128 v[196:199], v153 offset:19456
	ds_read_b128 v[200:203], v153 offset:20480
	ds_read_b128 v[204:207], v153 offset:21504
	ds_read_b128 v[208:211], v153 offset:22528
	ds_read_b128 v[212:215], v153 offset:23552
	global_load_lds_dwordx4 v130, s[36:37]
	s_add_i32 m0, s30, 0x2000
	s_add_u32 s30, s36, 0xb0000
	s_addc_u32 s31, s37, 0
	s_add_i32 s74, s65, s51
	global_load_lds_dwordx4 v134, s[36:37]
	s_mov_b32 m0, s74
	s_nop 0
	global_load_lds_dwordx4 v130, s[30:31]
	s_add_i32 m0, s74, 0x2000
	s_nop 0
	global_load_lds_dwordx4 v134, s[30:31]
	s_mov_b32 m0, s54
	s_nop 0
	global_load_lds_dwordx4 v128, s[38:39]
	s_mov_b32 m0, s55
	s_nop 0
	global_load_lds_dwordx4 v132, s[38:39]
	s_waitcnt vmcnt(8)
	s_waitcnt lgkmcnt(0)
	s_barrier
	s_setprio 1
	s_waitcnt lgkmcnt(0)
	v_mfma_f32_16x16x32_bf16 v[48:51], v[144:147], v[182:185], v[48:51]
	v_mfma_f32_16x16x32_bf16 v[56:59], v[158:161], v[182:185], v[56:59]
	v_mfma_f32_16x16x32_bf16 v[24:27], v[144:147], v[192:195], v[24:27]
	v_mfma_f32_16x16x32_bf16 v[32:35], v[158:161], v[192:195], v[32:35]
	v_mfma_f32_16x16x32_bf16 v[0:3], v[144:147], v[200:203], v[0:3]
	v_mfma_f32_16x16x32_bf16 v[4:7], v[158:161], v[200:203], v[4:7]
	v_mfma_f32_16x16x32_bf16 v[8:11], v[144:147], v[208:211], v[8:11]
	v_mfma_f32_16x16x32_bf16 v[16:19], v[158:161], v[208:211], v[16:19]
	v_mfma_f32_16x16x32_bf16 v[48:51], v[154:157], v[188:191], v[48:51]
	v_mfma_f32_16x16x32_bf16 v[56:59], v[162:165], v[188:191], v[56:59]
	v_mfma_f32_16x16x32_bf16 v[24:27], v[154:157], v[196:199], v[24:27]
	v_mfma_f32_16x16x32_bf16 v[32:35], v[162:165], v[196:199], v[32:35]
	v_mfma_f32_16x16x32_bf16 v[0:3], v[154:157], v[204:207], v[0:3]
	v_mfma_f32_16x16x32_bf16 v[4:7], v[162:165], v[204:207], v[4:7]
	v_mfma_f32_16x16x32_bf16 v[8:11], v[154:157], v[212:215], v[8:11]
	v_mfma_f32_16x16x32_bf16 v[16:19], v[162:165], v[212:215], v[16:19]
	s_setprio 0
	s_setprio 1
	v_mfma_f32_16x16x32_bf16 v[52:55], v[166:169], v[182:185], v[52:55]
	v_mfma_f32_16x16x32_bf16 v[60:63], v[174:177], v[182:185], v[60:63]
	v_mfma_f32_16x16x32_bf16 v[28:31], v[166:169], v[192:195], v[28:31]
	v_mfma_f32_16x16x32_bf16 v[36:39], v[174:177], v[192:195], v[36:39]
	v_mfma_f32_16x16x32_bf16 v[40:43], v[166:169], v[200:203], v[40:43]
	v_mfma_f32_16x16x32_bf16 v[44:47], v[174:177], v[200:203], v[44:47]
	v_mfma_f32_16x16x32_bf16 v[12:15], v[166:169], v[208:211], v[12:15]
	v_mfma_f32_16x16x32_bf16 v[20:23], v[174:177], v[208:211], v[20:23]
	v_mfma_f32_16x16x32_bf16 v[52:55], v[170:173], v[188:191], v[52:55]
	v_mfma_f32_16x16x32_bf16 v[60:63], v[178:181], v[188:191], v[60:63]
	v_mfma_f32_16x16x32_bf16 v[28:31], v[170:173], v[196:199], v[28:31]
	v_mfma_f32_16x16x32_bf16 v[36:39], v[178:181], v[196:199], v[36:39]
	v_mfma_f32_16x16x32_bf16 v[40:43], v[170:173], v[204:207], v[40:43]
	v_mfma_f32_16x16x32_bf16 v[44:47], v[178:181], v[204:207], v[44:47]
	v_mfma_f32_16x16x32_bf16 v[12:15], v[170:173], v[212:215], v[12:15]
	v_mfma_f32_16x16x32_bf16 v[20:23], v[178:181], v[212:215], v[20:23]
	s_setprio 0
	s_barrier
; #define PG8_STAGE(bufoff, gbase, voff) do { _Pragma("unroll") for (int _i = 0; _i < 2; ++_i) \
;         __builtin_amdgcn_global_load_lds((const unsigned*)((const char*)(gbase) + (voff)[_i]), (PG8_LAS unsigned*)(lds + (bufoff) + ldsw + _i * 8192), 16, 0, 0); } while (0)
; #define PG8_LDA(dst, b, h) do { _Pragma("unroll") for (int m = 0; m < 4; ++m) _Pragma("unroll") for (int k = 0; k < 2; ++k) dst[m][k] = *(const PG8_LAS bf16x8*)(lds + PG8_SA(b, h) + aoff + m * 2048 + k * 1024); } while (0)
; #define PG8_LDB(dst, b, h) do { _Pragma("unroll") for (int n = 0; n < 2; ++n) _Pragma("unroll") for (int k = 0; k < 2; ++k) dst[n][k] = *(const PG8_LAS bf16x8*)(lds + PG8_SB(b, h) + boff + n * 2048 + k * 1024); } while (0)
; #define PG8_MMA(ai, bj, At, Bt) do { __builtin_amdgcn_s_setprio(1); _Pragma("unroll") for (int m = 0; m < 4; ++m) _Pragma("unroll") for (int n = 0; n < 2; ++n) _Pragma("unroll") for (int k = 0; k < 2; ++k) \
;         acc[ai][bj][m][n] = __builtin_amdgcn_mfma_f32_16x16x32_bf16(Bt[n][k], At[m][k], acc[ai][bj][m][n], 0, 0, 0); __builtin_amdgcn_s_setprio(0); } while (0)
; #define PG8_WAIT_V(n) asm volatile("s_waitcnt vmcnt(" #n ")" ::: "memory")
; #define PG8_WAIT_L(n) asm volatile("s_waitcnt lgkmcnt(" #n ")" ::: "memory")
; #define PG8_BAR __builtin_amdgcn_s_barrier()
; #define PG8_SCHED __builtin_amdgcn_sched_barrier(0)
; template <class Epi, class Sched, bool ALIGN_EPI = false, bool SP2 = false>
; __device__ __forceinline__ void gemm_phase(PG8_LAS unsigned char* lds, const Gemm g, const Sched S, const Epi E, const int tid) {
;     ...
;             PG8_LDB(B0, 1, 0); PG8_LDB(B1, 1, 1); PG8_SCHED; PG8_LDA(At, 1, 0); PG8_STAGE(PG8_SA(0, 1), a2 + hstepA, voffA);
;             PG8_WAIT_V(8); PG8_WAIT_L(0); PG8_BAR; PG8_MMA(0, 0, At, B0); PG8_MMA(0, 1, At, B1); PG8_BAR; PG8_SCHED;
;             PG8_LDA(At, 1, 1); PG8_STAGE(PG8_SB(1, 0), b3, voffB); PG8_STAGE(PG8_SB(1, 1), b3 + hstepB, voffB); PG8_STAGE(PG8_SA(1, 0), a3, voffA);
;             PG8_WAIT_V(8); PG8_WAIT_L(0); PG8_BAR; PG8_MMA(1, 0, At, B0); PG8_MMA(1, 1, At, B1); PG8_BAR; PG8_SCHED;
	s_add_i32 s74, 0, 0x18000
	s_add_i32 s75, 0, 0x1c000
	v_add_u32_e32 v162, s74, v149
	v_add_u32_e32 v178, s75, v149
	ds_read_b128 v[144:147], v162
	ds_read_b128 v[154:157], v162 offset:1024
	ds_read_b128 v[158:161], v162 offset:2048
	ds_read_b128 v[162:165], v162 offset:3072
	ds_read_b128 v[166:169], v178
	ds_read_b128 v[170:173], v178 offset:1024
	ds_read_b128 v[174:177], v178 offset:2048
	ds_read_b128 v[178:181], v178 offset:3072
	s_add_u32 s30, s38, 0xb0000
	s_addc_u32 s31, s39, 0
	s_mov_b32 m0, s56
	ds_read_b128 v[182:185], v153 offset:32768
	ds_read_b128 v[188:191], v153 offset:33792
	ds_read_b128 v[192:195], v153 offset:34816
	ds_read_b128 v[196:199], v153 offset:35840
	ds_read_b128 v[200:203], v153 offset:36864
	ds_read_b128 v[204:207], v153 offset:37888
	ds_read_b128 v[208:211], v153 offset:38912
	ds_read_b128 v[212:215], v153 offset:39936
	global_load_lds_dwordx4 v128, s[30:31]
	s_mov_b32 m0, s57
	s_nop 0
	global_load_lds_dwordx4 v132, s[30:31]
	s_waitcnt vmcnt(8)
	s_waitcnt lgkmcnt(0)
	s_barrier
	s_setprio 1
	s_waitcnt lgkmcnt(0)
	v_mfma_f32_16x16x32_bf16 v[112:115], v[144:147], v[182:185], v[112:115]
	v_mfma_f32_16x16x32_bf16 v[120:123], v[158:161], v[182:185], v[120:123]
	v_mfma_f32_16x16x32_bf16 v[96:99], v[144:147], v[192:195], v[96:99]
	v_mfma_f32_16x16x32_bf16 v[104:107], v[158:161], v[192:195], v[104:107]
	v_mfma_f32_16x16x32_bf16 v[80:83], v[144:147], v[200:203], v[80:83]
	v_mfma_f32_16x16x32_bf16 v[88:91], v[158:161], v[200:203], v[88:91]
	v_mfma_f32_16x16x32_bf16 v[64:67], v[144:147], v[208:211], v[64:67]
	v_mfma_f32_16x16x32_bf16 v[72:75], v[158:161], v[208:211], v[72:75]
	v_mfma_f32_16x16x32_bf16 v[112:115], v[154:157], v[188:191], v[112:115]
	v_mfma_f32_16x16x32_bf16 v[120:123], v[162:165], v[188:191], v[120:123]
	v_mfma_f32_16x16x32_bf16 v[96:99], v[154:157], v[196:199], v[96:99]
	v_mfma_f32_16x16x32_bf16 v[104:107], v[162:165], v[196:199], v[104:107]
	v_mfma_f32_16x16x32_bf16 v[80:83], v[154:157], v[204:207], v[80:83]
	v_mfma_f32_16x16x32_bf16 v[88:91], v[162:165], v[204:207], v[88:91]
	v_mfma_f32_16x16x32_bf16 v[64:67], v[154:157], v[212:215], v[64:67]
	v_mfma_f32_16x16x32_bf16 v[72:75], v[162:165], v[212:215], v[72:75]
	s_setprio 0
	s_setprio 1
	v_mfma_f32_16x16x32_bf16 v[116:119], v[166:169], v[182:185], v[116:119]
	v_mfma_f32_16x16x32_bf16 v[124:127], v[174:177], v[182:185], v[124:127]
	v_mfma_f32_16x16x32_bf16 v[100:103], v[166:169], v[192:195], v[100:103]
	v_mfma_f32_16x16x32_bf16 v[108:111], v[174:177], v[192:195], v[108:111]
	v_mfma_f32_16x16x32_bf16 v[84:87], v[166:169], v[200:203], v[84:87]
	v_mfma_f32_16x16x32_bf16 v[92:95], v[174:177], v[200:203], v[92:95]
	v_mfma_f32_16x16x32_bf16 v[68:71], v[166:169], v[208:211], v[68:71]
	v_mfma_f32_16x16x32_bf16 v[76:79], v[174:177], v[208:211], v[76:79]
	v_mfma_f32_16x16x32_bf16 v[116:119], v[170:173], v[188:191], v[116:119]
	v_mfma_f32_16x16x32_bf16 v[124:127], v[178:181], v[188:191], v[124:127]
	v_mfma_f32_16x16x32_bf16 v[100:103], v[170:173], v[196:199], v[100:103]
	v_mfma_f32_16x16x32_bf16 v[108:111], v[178:181], v[196:199], v[108:111]
	v_mfma_f32_16x16x32_bf16 v[84:87], v[170:173], v[204:207], v[84:87]
	v_mfma_f32_16x16x32_bf16 v[92:95], v[178:181], v[204:207], v[92:95]
	v_mfma_f32_16x16x32_bf16 v[68:71], v[170:173], v[212:215], v[68:71]
	v_mfma_f32_16x16x32_bf16 v[76:79], v[178:181], v[212:215], v[76:79]
	s_setprio 0
	s_barrier
	s_add_i32 s30, s74, s51
	s_mov_b32 m0, s30
	ds_read_b128 v[182:185], v153 offset:49152
	ds_read_b128 v[188:191], v153 offset:50176
	ds_read_b128 v[192:195], v153 offset:51200
	ds_read_b128 v[196:199], v153 offset:52224
	ds_read_b128 v[200:203], v153 offset:53248
	ds_read_b128 v[204:207], v153 offset:54272
	ds_read_b128 v[208:211], v153 offset:55296
	ds_read_b128 v[212:215], v153 offset:56320
	global_load_lds_dwordx4 v130, s[98:99]
	s_add_i32 m0, s30, 0x2000
	s_add_u32 s30, s36, 0xb0080
	s_addc_u32 s31, s37, 0
	s_add_i32 s36, s75, s51
	global_load_lds_dwordx4 v134, s[98:99]
	s_mov_b32 m0, s36
	s_nop 0
	global_load_lds_dwordx4 v130, s[30:31]
	s_add_i32 m0, s36, 0x2000
	s_nop 0
	global_load_lds_dwordx4 v134, s[30:31]
	s_mov_b32 m0, s59
	s_nop 0
	global_load_lds_dwordx4 v128, s[100:101]
	s_mov_b32 m0, s60
	s_nop 0
	global_load_lds_dwordx4 v132, s[100:101]
	s_waitcnt vmcnt(8)
	s_waitcnt lgkmcnt(0)
	s_barrier
	s_setprio 1
	s_waitcnt lgkmcnt(0)
	v_mfma_f32_16x16x32_bf16 v[48:51], v[144:147], v[182:185], v[48:51]
	v_mfma_f32_16x16x32_bf16 v[56:59], v[158:161], v[182:185], v[56:59]
	v_mfma_f32_16x16x32_bf16 v[24:27], v[144:147], v[192:195], v[24:27]
	v_mfma_f32_16x16x32_bf16 v[32:35], v[158:161], v[192:195], v[32:35]
	v_mfma_f32_16x16x32_bf16 v[0:3], v[144:147], v[200:203], v[0:3]
	v_mfma_f32_16x16x32_bf16 v[4:7], v[158:161], v[200:203], v[4:7]
	v_mfma_f32_16x16x32_bf16 v[8:11], v[144:147], v[208:211], v[8:11]
	v_mfma_f32_16x16x32_bf16 v[16:19], v[158:161], v[208:211], v[16:19]
	v_mfma_f32_16x16x32_bf16 v[48:51], v[154:157], v[188:191], v[48:51]
	v_mfma_f32_16x16x32_bf16 v[56:59], v[162:165], v[188:191], v[56:59]
	v_mfma_f32_16x16x32_bf16 v[24:27], v[154:157], v[196:199], v[24:27]
	v_mfma_f32_16x16x32_bf16 v[32:35], v[162:165], v[196:199], v[32:35]
	v_mfma_f32_16x16x32_bf16 v[0:3], v[154:157], v[204:207], v[0:3]
	v_mfma_f32_16x16x32_bf16 v[4:7], v[162:165], v[204:207], v[4:7]
	v_mfma_f32_16x16x32_bf16 v[8:11], v[154:157], v[212:215], v[8:11]
	v_mfma_f32_16x16x32_bf16 v[16:19], v[162:165], v[212:215], v[16:19]
	s_setprio 0
	s_setprio 1
	v_mfma_f32_16x16x32_bf16 v[52:55], v[166:169], v[182:185], v[52:55]
	v_mfma_f32_16x16x32_bf16 v[60:63], v[174:177], v[182:185], v[60:63]
	v_mfma_f32_16x16x32_bf16 v[28:31], v[166:169], v[192:195], v[28:31]
	v_mfma_f32_16x16x32_bf16 v[36:39], v[174:177], v[192:195], v[36:39]
	v_mfma_f32_16x16x32_bf16 v[40:43], v[166:169], v[200:203], v[40:43]
	v_mfma_f32_16x16x32_bf16 v[44:47], v[174:177], v[200:203], v[44:47]
	v_mfma_f32_16x16x32_bf16 v[12:15], v[166:169], v[208:211], v[12:15]
	v_mfma_f32_16x16x32_bf16 v[20:23], v[174:177], v[208:211], v[20:23]
	v_mfma_f32_16x16x32_bf16 v[52:55], v[170:173], v[188:191], v[52:55]
	v_mfma_f32_16x16x32_bf16 v[60:63], v[178:181], v[188:191], v[60:63]
	v_mfma_f32_16x16x32_bf16 v[28:31], v[170:173], v[196:199], v[28:31]
	v_mfma_f32_16x16x32_bf16 v[36:39], v[178:181], v[196:199], v[36:39]
	v_mfma_f32_16x16x32_bf16 v[40:43], v[170:173], v[204:207], v[40:43]
	v_mfma_f32_16x16x32_bf16 v[44:47], v[178:181], v[204:207], v[44:47]
	v_mfma_f32_16x16x32_bf16 v[12:15], v[170:173], v[212:215], v[12:15]
	v_mfma_f32_16x16x32_bf16 v[20:23], v[178:181], v[212:215], v[20:23]
	s_setprio 0
	s_barrier
	s_add_i32 s73, s73, 2
	s_add_u32 s71, s71, 0x100
	s_addc_u32 s72, s72, 0
	s_cmp_gt_u32 s73, 41
	s_mov_b64 s[30:31], s[34:35]
	s_cbranch_scc0 .LBB0_297
	s_and_b64 vcc, exec, s[24:25]
	s_cbranch_vccz .LBB0_300
	s_barrier

; #define PG8_STAGE(bufoff, gbase, voff) do { _Pragma("unroll") for (int _i = 0; _i < 2; ++_i) \
;         __builtin_amdgcn_global_load_lds((const unsigned*)((const char*)(gbase) + (voff)[_i]), (PG8_LAS unsigned*)(lds + (bufoff) + ldsw + _i * 8192), 16, 0, 0); } while (0)
; #define PG8_LDA(dst, b, h) do { _Pragma("unroll") for (int m = 0; m < 4; ++m) _Pragma("unroll") for (int k = 0; k < 2; ++k) dst[m][k] = *(const PG8_LAS bf16x8*)(lds + PG8_SA(b, h) + aoff + m * 2048 + k * 1024); } while (0)
; #define PG8_LDB(dst, b, h) do { _Pragma("unroll") for (int n = 0; n < 2; ++n) _Pragma("unroll") for (int k = 0; k < 2; ++k) dst[n][k] = *(const PG8_LAS bf16x8*)(lds + PG8_SB(b, h) + boff + n * 2048 + k * 1024); } while (0)
; #define PG8_MMA(ai, bj, At, Bt) do { __builtin_amdgcn_s_setprio(1); _Pragma("unroll") for (int m = 0; m < 4; ++m) _Pragma("unroll") for (int n = 0; n < 2; ++n) _Pragma("unroll") for (int k = 0; k < 2; ++k) \
;         acc[ai][bj][m][n] = __builtin_amdgcn_mfma_f32_16x16x32_bf16(Bt[n][k], At[m][k], acc[ai][bj][m][n], 0, 0, 0); __builtin_amdgcn_s_setprio(0); } while (0)
; #define PG8_WAIT_V(n) asm volatile("s_waitcnt vmcnt(" #n ")" ::: "memory")
; #define PG8_WAIT_L(n) asm volatile("s_waitcnt lgkmcnt(" #n ")" ::: "memory")
; template <class Epi, class Sched, bool ALIGN_EPI = false, bool SP2 = false>
; __device__ __forceinline__ void gemm_phase(PG8_LAS unsigned char* lds, const Gemm g, const Sched S, const Epi E, const int tid) {
;     ...
;             const bool last = (t == nt - 2);
;             const char* a1 = cA + (size_t)(t + 1) * kstep;
;             const char* a2 = last ? nA : cA + (size_t)(t + 2) * kstep; const char* b2 = last ? nB : cB + (size_t)(t + 2) * kstep;
;             const char* a3 = a2 + kstep; const char* b3 = b2 + kstep;
;             if (last && has_next) S.a_ready(nxt);
;             if constexpr (SP2) {
;             PG8_LDB(B0, 0, 0); PG8_LDB(B1, 0, 1); PG8_SCHED; PG8_LDA(At, 0, 0); PG8_STAGE(PG8_SA(1, 1), a1 + hstepA, voffA);
;             PG8_WAIT_V(8); PG8_WAIT_L(0); PG8_BAR; PG8_MMA(0, 0, At, B0); PG8_MMA(0, 1, At, B1); PG8_BAR; PG8_SCHED;
;             PG8_LDA(At, 0, 1); PG8_STAGE(PG8_SB(0, 0), b2, voffB); PG8_STAGE(PG8_SB(0, 1), b2 + hstepB, voffB); PG8_STAGE(PG8_SA(0, 0), a2, voffA);
;             PG8_WAIT_V(8); PG8_WAIT_L(0); PG8_BAR; PG8_MMA(1, 0, At, B0); PG8_MMA(1, 1, At, B1); PG8_BAR; PG8_SCHED;
.LBB0_402:
	ds_read_b128 v[146:149], v169
	ds_read_b128 v[150:153], v169 offset:1024
	ds_read_b128 v[154:157], v169 offset:2048
	ds_read_b128 v[174:177], v169 offset:3072
	ds_read_b128 v[178:181], v170
	ds_read_b128 v[182:185], v170 offset:1024
	ds_read_b128 v[188:191], v170 offset:2048
	ds_read_b128 v[192:195], v170 offset:3072
	s_add_u32 s34, s30, 0xfffc0080
	s_addc_u32 s35, s31, -1
	s_cmp_eq_u32 s74, 12
	s_cselect_b32 s37, s25, s35
	s_cselect_b32 s36, s70, s34
	s_cselect_b32 s35, s23, s73
	s_cselect_b32 s34, s71, s72
	s_add_i32 m0, s52, 0xc000
	ds_read_b128 v[196:199], v171
	ds_read_b128 v[200:203], v171 offset:1024
	ds_read_b128 v[204:207], v171 offset:2048
	ds_read_b128 v[208:211], v171 offset:3072
	ds_read_b128 v[212:215], v171 offset:4096
	ds_read_b128 v[216:219], v171 offset:5120
	ds_read_b128 v[220:223], v171 offset:6144
	ds_read_b128 v[224:227], v171 offset:7168
	global_load_lds_dwordx4 v138, s[30:31]
	s_add_i32 m0, s52, 0xe000
	s_nop 0
	global_load_lds_dwordx4 v140, s[30:31]
	s_waitcnt vmcnt(8)
	s_waitcnt lgkmcnt(0)
	s_barrier
	s_setprio 1
	s_waitcnt lgkmcnt(0)
	v_mfma_f32_16x16x32_bf16 v[124:127], v[146:149], v[196:199], v[124:127]
	v_mfma_f32_16x16x32_bf16 v[120:123], v[154:157], v[196:199], v[120:123]
	v_mfma_f32_16x16x32_bf16 v[116:119], v[146:149], v[204:207], v[116:119]
	v_mfma_f32_16x16x32_bf16 v[112:115], v[154:157], v[204:207], v[112:115]
	v_mfma_f32_16x16x32_bf16 v[108:111], v[146:149], v[212:215], v[108:111]
	v_mfma_f32_16x16x32_bf16 v[104:107], v[154:157], v[212:215], v[104:107]
	v_mfma_f32_16x16x32_bf16 v[100:103], v[146:149], v[220:223], v[100:103]
	v_mfma_f32_16x16x32_bf16 v[96:99], v[154:157], v[220:223], v[96:99]
	v_mfma_f32_16x16x32_bf16 v[124:127], v[150:153], v[200:203], v[124:127]
	v_mfma_f32_16x16x32_bf16 v[120:123], v[174:177], v[200:203], v[120:123]
	v_mfma_f32_16x16x32_bf16 v[116:119], v[150:153], v[208:211], v[116:119]
	v_mfma_f32_16x16x32_bf16 v[112:115], v[174:177], v[208:211], v[112:115]
	v_mfma_f32_16x16x32_bf16 v[108:111], v[150:153], v[216:219], v[108:111]
	v_mfma_f32_16x16x32_bf16 v[104:107], v[174:177], v[216:219], v[104:107]
	v_mfma_f32_16x16x32_bf16 v[100:103], v[150:153], v[224:227], v[100:103]
	v_mfma_f32_16x16x32_bf16 v[96:99], v[174:177], v[224:227], v[96:99]
	s_setprio 0
	s_setprio 1
	v_mfma_f32_16x16x32_bf16 v[60:63], v[178:181], v[196:199], v[60:63]
	v_mfma_f32_16x16x32_bf16 v[56:59], v[188:191], v[196:199], v[56:59]
	v_mfma_f32_16x16x32_bf16 v[52:55], v[178:181], v[204:207], v[52:55]
	v_mfma_f32_16x16x32_bf16 v[48:51], v[188:191], v[204:207], v[48:51]
	v_mfma_f32_16x16x32_bf16 v[44:47], v[178:181], v[212:215], v[44:47]
	v_mfma_f32_16x16x32_bf16 v[40:43], v[188:191], v[212:215], v[40:43]
	v_mfma_f32_16x16x32_bf16 v[36:39], v[178:181], v[220:223], v[36:39]
	v_mfma_f32_16x16x32_bf16 v[32:35], v[188:191], v[220:223], v[32:35]
	v_mfma_f32_16x16x32_bf16 v[60:63], v[182:185], v[200:203], v[60:63]
	v_mfma_f32_16x16x32_bf16 v[56:59], v[192:195], v[200:203], v[56:59]
	v_mfma_f32_16x16x32_bf16 v[52:55], v[182:185], v[208:211], v[52:55]
	v_mfma_f32_16x16x32_bf16 v[48:51], v[192:195], v[208:211], v[48:51]
	v_mfma_f32_16x16x32_bf16 v[44:47], v[182:185], v[216:219], v[44:47]
	v_mfma_f32_16x16x32_bf16 v[40:43], v[192:195], v[216:219], v[40:43]
	v_mfma_f32_16x16x32_bf16 v[36:39], v[182:185], v[224:227], v[36:39]
	v_mfma_f32_16x16x32_bf16 v[32:35], v[192:195], v[224:227], v[32:35]
	s_setprio 0
	s_barrier
	s_add_u32 s98, s34, 0x80
	s_addc_u32 s99, s35, 0
	s_add_u32 s100, s36, 0x80
	s_addc_u32 s101, s37, 0
	s_add_i32 s75, s63, s33
	s_mov_b32 m0, s75
	ds_read_b128 v[196:199], v171 offset:16384
	ds_read_b128 v[200:203], v171 offset:17408
	ds_read_b128 v[204:207], v171 offset:18432
	ds_read_b128 v[208:211], v171 offset:19456
	ds_read_b128 v[212:215], v171 offset:20480
	ds_read_b128 v[216:219], v171 offset:21504
	ds_read_b128 v[220:223], v171 offset:22528
	ds_read_b128 v[224:227], v171 offset:23552
	global_load_lds_dwordx4 v134, s[34:35]
	s_add_i32 m0, s75, 0x2000
	s_add_u32 s76, s34, 0x40000
	s_addc_u32 s77, s35, 0
	s_add_i32 s75, s64, s33
	global_load_lds_dwordx4 v130, s[34:35]
	s_mov_b32 m0, s75
	s_nop 0
	global_load_lds_dwordx4 v134, s[76:77]
	s_add_i32 m0, s75, 0x2000
	s_nop 0
	global_load_lds_dwordx4 v130, s[76:77]
	s_mov_b32 m0, s52
	s_nop 0
	global_load_lds_dwordx4 v136, s[36:37]
	s_mov_b32 m0, s54
	s_nop 0
	global_load_lds_dwordx4 v132, s[36:37]
	s_waitcnt vmcnt(8)
	s_waitcnt lgkmcnt(0)
	s_barrier
	s_setprio 1
	s_waitcnt lgkmcnt(0)
	v_mfma_f32_16x16x32_bf16 v[92:95], v[146:149], v[196:199], v[92:95]
	v_mfma_f32_16x16x32_bf16 v[88:91], v[154:157], v[196:199], v[88:91]
	v_mfma_f32_16x16x32_bf16 v[84:87], v[146:149], v[204:207], v[84:87]
	v_mfma_f32_16x16x32_bf16 v[80:83], v[154:157], v[204:207], v[80:83]
	v_mfma_f32_16x16x32_bf16 v[76:79], v[146:149], v[212:215], v[76:79]
	v_mfma_f32_16x16x32_bf16 v[72:75], v[154:157], v[212:215], v[72:75]
	v_mfma_f32_16x16x32_bf16 v[68:71], v[146:149], v[220:223], v[68:71]
	v_mfma_f32_16x16x32_bf16 v[64:67], v[154:157], v[220:223], v[64:67]
	v_mfma_f32_16x16x32_bf16 v[92:95], v[150:153], v[200:203], v[92:95]
	v_mfma_f32_16x16x32_bf16 v[88:91], v[174:177], v[200:203], v[88:91]
	v_mfma_f32_16x16x32_bf16 v[84:87], v[150:153], v[208:211], v[84:87]
	v_mfma_f32_16x16x32_bf16 v[80:83], v[174:177], v[208:211], v[80:83]
	v_mfma_f32_16x16x32_bf16 v[76:79], v[150:153], v[216:219], v[76:79]
	v_mfma_f32_16x16x32_bf16 v[72:75], v[174:177], v[216:219], v[72:75]
	v_mfma_f32_16x16x32_bf16 v[68:71], v[150:153], v[224:227], v[68:71]
	v_mfma_f32_16x16x32_bf16 v[64:67], v[174:177], v[224:227], v[64:67]
	s_setprio 0
	s_setprio 1
	v_mfma_f32_16x16x32_bf16 v[28:31], v[178:181], v[196:199], v[28:31]
	v_mfma_f32_16x16x32_bf16 v[24:27], v[188:191], v[196:199], v[24:27]
	v_mfma_f32_16x16x32_bf16 v[20:23], v[178:181], v[204:207], v[20:23]
	v_mfma_f32_16x16x32_bf16 v[16:19], v[188:191], v[204:207], v[16:19]
	v_mfma_f32_16x16x32_bf16 v[12:15], v[178:181], v[212:215], v[12:15]
	v_mfma_f32_16x16x32_bf16 v[8:11], v[188:191], v[212:215], v[8:11]
	v_mfma_f32_16x16x32_bf16 v[4:7], v[178:181], v[220:223], v[4:7]
	v_mfma_f32_16x16x32_bf16 v[0:3], v[188:191], v[220:223], v[0:3]
	v_mfma_f32_16x16x32_bf16 v[28:31], v[182:185], v[200:203], v[28:31]
	v_mfma_f32_16x16x32_bf16 v[24:27], v[192:195], v[200:203], v[24:27]
	v_mfma_f32_16x16x32_bf16 v[20:23], v[182:185], v[208:211], v[20:23]
	v_mfma_f32_16x16x32_bf16 v[16:19], v[192:195], v[208:211], v[16:19]
	v_mfma_f32_16x16x32_bf16 v[12:15], v[182:185], v[216:219], v[12:15]
	v_mfma_f32_16x16x32_bf16 v[8:11], v[192:195], v[216:219], v[8:11]
	v_mfma_f32_16x16x32_bf16 v[4:7], v[182:185], v[224:227], v[4:7]
	v_mfma_f32_16x16x32_bf16 v[0:3], v[192:195], v[224:227], v[0:3]
	s_setprio 0
	s_barrier
; #define PG8_STAGE(bufoff, gbase, voff) do { _Pragma("unroll") for (int _i = 0; _i < 2; ++_i) \
;         __builtin_amdgcn_global_load_lds((const unsigned*)((const char*)(gbase) + (voff)[_i]), (PG8_LAS unsigned*)(lds + (bufoff) + ldsw + _i * 8192), 16, 0, 0); } while (0)
; #define PG8_LDA(dst, b, h) do { _Pragma("unroll") for (int m = 0; m < 4; ++m) _Pragma("unroll") for (int k = 0; k < 2; ++k) dst[m][k] = *(const PG8_LAS bf16x8*)(lds + PG8_SA(b, h) + aoff + m * 2048 + k * 1024); } while (0)
; #define PG8_LDB(dst, b, h) do { _Pragma("unroll") for (int n = 0; n < 2; ++n) _Pragma("unroll") for (int k = 0; k < 2; ++k) dst[n][k] = *(const PG8_LAS bf16x8*)(lds + PG8_SB(b, h) + boff + n * 2048 + k * 1024); } while (0)
; #define PG8_MMA(ai, bj, At, Bt) do { __builtin_amdgcn_s_setprio(1); _Pragma("unroll") for (int m = 0; m < 4; ++m) _Pragma("unroll") for (int n = 0; n < 2; ++n) _Pragma("unroll") for (int k = 0; k < 2; ++k) \
;         acc[ai][bj][m][n] = __builtin_amdgcn_mfma_f32_16x16x32_bf16(Bt[n][k], At[m][k], acc[ai][bj][m][n], 0, 0, 0); __builtin_amdgcn_s_setprio(0); } while (0)
; #define PG8_WAIT_V(n) asm volatile("s_waitcnt vmcnt(" #n ")" ::: "memory")
; #define PG8_WAIT_L(n) asm volatile("s_waitcnt lgkmcnt(" #n ")" ::: "memory")
; #define PG8_BAR __builtin_amdgcn_s_barrier()
; #define PG8_SCHED __builtin_amdgcn_sched_barrier(0)
; template <class Epi, class Sched, bool ALIGN_EPI = false, bool SP2 = false>
; __device__ __forceinline__ void gemm_phase(PG8_LAS unsigned char* lds, const Gemm g, const Sched S, const Epi E, const int tid) {
;     ...
;             PG8_LDB(B0, 1, 0); PG8_LDB(B1, 1, 1); PG8_SCHED; PG8_LDA(At, 1, 0); PG8_STAGE(PG8_SA(0, 1), a2 + hstepA, voffA);
;             PG8_WAIT_V(8); PG8_WAIT_L(0); PG8_BAR; PG8_MMA(0, 0, At, B0); PG8_MMA(0, 1, At, B1); PG8_BAR; PG8_SCHED;
;             PG8_LDA(At, 1, 1); PG8_STAGE(PG8_SB(1, 0), b3, voffB); PG8_STAGE(PG8_SB(1, 1), b3 + hstepB, voffB); PG8_STAGE(PG8_SA(1, 0), a3, voffA);
;             PG8_WAIT_V(8); PG8_WAIT_L(0); PG8_BAR; PG8_MMA(1, 0, At, B0); PG8_MMA(1, 1, At, B1); PG8_BAR; PG8_SCHED;
	s_add_i32 s75, 0, 0x18000
	v_add_u32_e32 v173, s75, v160
	s_add_i32 s76, 0, 0x1c000
	ds_read_b128 v[146:149], v173
	ds_read_b128 v[150:153], v173 offset:1024
	ds_read_b128 v[154:157], v173 offset:2048
	ds_read_b128 v[174:177], v173 offset:3072
	v_add_u32_e32 v173, s76, v160
	ds_read_b128 v[178:181], v173
	ds_read_b128 v[182:185], v173 offset:1024
	ds_read_b128 v[188:191], v173 offset:2048
	ds_read_b128 v[192:195], v173 offset:3072
	s_add_u32 s36, s36, 0x40000
	s_addc_u32 s37, s37, 0
	s_mov_b32 m0, s55
	ds_read_b128 v[196:199], v171 offset:32768
	ds_read_b128 v[200:203], v171 offset:33792
	ds_read_b128 v[204:207], v171 offset:34816
	ds_read_b128 v[208:211], v171 offset:35840
	ds_read_b128 v[212:215], v171 offset:36864
	ds_read_b128 v[216:219], v171 offset:37888
	ds_read_b128 v[220:223], v171 offset:38912
	ds_read_b128 v[224:227], v171 offset:39936
	global_load_lds_dwordx4 v136, s[36:37]
	s_mov_b32 m0, s57
	s_nop 0
	global_load_lds_dwordx4 v132, s[36:37]
	s_waitcnt vmcnt(8)
	s_waitcnt lgkmcnt(0)
	s_barrier
	s_setprio 1
	s_waitcnt lgkmcnt(0)
	v_mfma_f32_16x16x32_bf16 v[124:127], v[146:149], v[196:199], v[124:127]
	v_mfma_f32_16x16x32_bf16 v[120:123], v[154:157], v[196:199], v[120:123]
	v_mfma_f32_16x16x32_bf16 v[116:119], v[146:149], v[204:207], v[116:119]
	v_mfma_f32_16x16x32_bf16 v[112:115], v[154:157], v[204:207], v[112:115]
	v_mfma_f32_16x16x32_bf16 v[108:111], v[146:149], v[212:215], v[108:111]
	v_mfma_f32_16x16x32_bf16 v[104:107], v[154:157], v[212:215], v[104:107]
	v_mfma_f32_16x16x32_bf16 v[100:103], v[146:149], v[220:223], v[100:103]
	v_mfma_f32_16x16x32_bf16 v[96:99], v[154:157], v[220:223], v[96:99]
	v_mfma_f32_16x16x32_bf16 v[124:127], v[150:153], v[200:203], v[124:127]
	v_mfma_f32_16x16x32_bf16 v[120:123], v[174:177], v[200:203], v[120:123]
	v_mfma_f32_16x16x32_bf16 v[116:119], v[150:153], v[208:211], v[116:119]
	v_mfma_f32_16x16x32_bf16 v[112:115], v[174:177], v[208:211], v[112:115]
	v_mfma_f32_16x16x32_bf16 v[108:111], v[150:153], v[216:219], v[108:111]
	v_mfma_f32_16x16x32_bf16 v[104:107], v[174:177], v[216:219], v[104:107]
	v_mfma_f32_16x16x32_bf16 v[100:103], v[150:153], v[224:227], v[100:103]
	v_mfma_f32_16x16x32_bf16 v[96:99], v[174:177], v[224:227], v[96:99]
	s_setprio 0
	s_setprio 1
	v_mfma_f32_16x16x32_bf16 v[60:63], v[178:181], v[196:199], v[60:63]
	v_mfma_f32_16x16x32_bf16 v[56:59], v[188:191], v[196:199], v[56:59]
	v_mfma_f32_16x16x32_bf16 v[52:55], v[178:181], v[204:207], v[52:55]
	v_mfma_f32_16x16x32_bf16 v[48:51], v[188:191], v[204:207], v[48:51]
	v_mfma_f32_16x16x32_bf16 v[44:47], v[178:181], v[212:215], v[44:47]
	v_mfma_f32_16x16x32_bf16 v[40:43], v[188:191], v[212:215], v[40:43]
	v_mfma_f32_16x16x32_bf16 v[36:39], v[178:181], v[220:223], v[36:39]
	v_mfma_f32_16x16x32_bf16 v[32:35], v[188:191], v[220:223], v[32:35]
	v_mfma_f32_16x16x32_bf16 v[60:63], v[182:185], v[200:203], v[60:63]
	v_mfma_f32_16x16x32_bf16 v[56:59], v[192:195], v[200:203], v[56:59]
	v_mfma_f32_16x16x32_bf16 v[52:55], v[182:185], v[208:211], v[52:55]
	v_mfma_f32_16x16x32_bf16 v[48:51], v[192:195], v[208:211], v[48:51]
	v_mfma_f32_16x16x32_bf16 v[44:47], v[182:185], v[216:219], v[44:47]
	v_mfma_f32_16x16x32_bf16 v[40:43], v[192:195], v[216:219], v[40:43]
	v_mfma_f32_16x16x32_bf16 v[36:39], v[182:185], v[224:227], v[36:39]
	v_mfma_f32_16x16x32_bf16 v[32:35], v[192:195], v[224:227], v[32:35]
	s_setprio 0
	s_barrier
	s_add_i32 s36, s75, s33
	s_mov_b32 m0, s36
	ds_read_b128 v[196:199], v171 offset:49152
	ds_read_b128 v[200:203], v171 offset:50176
	ds_read_b128 v[204:207], v171 offset:51200
	ds_read_b128 v[208:211], v171 offset:52224
	ds_read_b128 v[212:215], v171 offset:53248
	ds_read_b128 v[216:219], v171 offset:54272
	ds_read_b128 v[220:223], v171 offset:55296
	ds_read_b128 v[224:227], v171 offset:56320
	global_load_lds_dwordx4 v134, s[98:99]
	s_add_i32 m0, s36, 0x2000
	s_add_u32 s34, s34, 0x40080
	s_addc_u32 s35, s35, 0
	s_add_i32 s36, s76, s33
	global_load_lds_dwordx4 v130, s[98:99]
	s_mov_b32 m0, s36
	s_nop 0
	global_load_lds_dwordx4 v134, s[34:35]
	s_add_i32 m0, s36, 0x2000
	s_nop 0
	global_load_lds_dwordx4 v130, s[34:35]
	s_mov_b32 m0, s58
	s_nop 0
	global_load_lds_dwordx4 v136, s[100:101]
	s_mov_b32 m0, s59
	s_nop 0
	global_load_lds_dwordx4 v132, s[100:101]
	s_waitcnt vmcnt(8)
	s_waitcnt lgkmcnt(0)
	s_barrier
	s_setprio 1
	s_waitcnt lgkmcnt(0)
	v_mfma_f32_16x16x32_bf16 v[92:95], v[146:149], v[196:199], v[92:95]
	v_mfma_f32_16x16x32_bf16 v[88:91], v[154:157], v[196:199], v[88:91]
	v_mfma_f32_16x16x32_bf16 v[84:87], v[146:149], v[204:207], v[84:87]
	v_mfma_f32_16x16x32_bf16 v[80:83], v[154:157], v[204:207], v[80:83]
	v_mfma_f32_16x16x32_bf16 v[76:79], v[146:149], v[212:215], v[76:79]
	v_mfma_f32_16x16x32_bf16 v[72:75], v[154:157], v[212:215], v[72:75]
	v_mfma_f32_16x16x32_bf16 v[68:71], v[146:149], v[220:223], v[68:71]
	v_mfma_f32_16x16x32_bf16 v[64:67], v[154:157], v[220:223], v[64:67]
	v_mfma_f32_16x16x32_bf16 v[92:95], v[150:153], v[200:203], v[92:95]
	v_mfma_f32_16x16x32_bf16 v[88:91], v[174:177], v[200:203], v[88:91]
	v_mfma_f32_16x16x32_bf16 v[84:87], v[150:153], v[208:211], v[84:87]
	v_mfma_f32_16x16x32_bf16 v[80:83], v[174:177], v[208:211], v[80:83]
	v_mfma_f32_16x16x32_bf16 v[76:79], v[150:153], v[216:219], v[76:79]
	v_mfma_f32_16x16x32_bf16 v[72:75], v[174:177], v[216:219], v[72:75]
	v_mfma_f32_16x16x32_bf16 v[68:71], v[150:153], v[224:227], v[68:71]
	v_mfma_f32_16x16x32_bf16 v[64:67], v[174:177], v[224:227], v[64:67]
	s_setprio 0
	s_setprio 1
	v_mfma_f32_16x16x32_bf16 v[28:31], v[178:181], v[196:199], v[28:31]
	v_mfma_f32_16x16x32_bf16 v[24:27], v[188:191], v[196:199], v[24:27]
	v_mfma_f32_16x16x32_bf16 v[20:23], v[178:181], v[204:207], v[20:23]
	v_mfma_f32_16x16x32_bf16 v[16:19], v[188:191], v[204:207], v[16:19]
	v_mfma_f32_16x16x32_bf16 v[12:15], v[178:181], v[212:215], v[12:15]
	v_mfma_f32_16x16x32_bf16 v[8:11], v[188:191], v[212:215], v[8:11]
	v_mfma_f32_16x16x32_bf16 v[4:7], v[178:181], v[220:223], v[4:7]
	v_mfma_f32_16x16x32_bf16 v[0:3], v[188:191], v[220:223], v[0:3]
	v_mfma_f32_16x16x32_bf16 v[28:31], v[182:185], v[200:203], v[28:31]
	v_mfma_f32_16x16x32_bf16 v[24:27], v[192:195], v[200:203], v[24:27]
	v_mfma_f32_16x16x32_bf16 v[20:23], v[182:185], v[208:211], v[20:23]
	v_mfma_f32_16x16x32_bf16 v[16:19], v[192:195], v[208:211], v[16:19]
	v_mfma_f32_16x16x32_bf16 v[12:15], v[182:185], v[216:219], v[12:15]
	v_mfma_f32_16x16x32_bf16 v[8:11], v[192:195], v[216:219], v[8:11]
	v_mfma_f32_16x16x32_bf16 v[4:7], v[182:185], v[224:227], v[4:7]
	v_mfma_f32_16x16x32_bf16 v[0:3], v[192:195], v[224:227], v[0:3]
	s_setprio 0
	s_barrier
	s_add_i32 s74, s74, 2
	s_add_u32 s30, s30, 0x100
	s_addc_u32 s31, s31, 0
	s_add_u32 s72, s72, 0x100
	s_addc_u32 s73, s73, 0
	s_cmp_gt_u32 s74, 13
	s_cbranch_scc0 .LBB0_402
	s_and_b64 vcc, exec, s[18:19]
	s_cbranch_vccz .LBB0_405
	s_barrier

; #define PG8_STAGE(bufoff, gbase, voff) do { _Pragma("unroll") for (int _i = 0; _i < 2; ++_i) \
;         __builtin_amdgcn_global_load_lds((const unsigned*)((const char*)(gbase) + (voff)[_i]), (PG8_LAS unsigned*)(lds + (bufoff) + ldsw + _i * 8192), 16, 0, 0); } while (0)
; #define PG8_LDA(dst, b, h) do { _Pragma("unroll") for (int m = 0; m < 4; ++m) _Pragma("unroll") for (int k = 0; k < 2; ++k) dst[m][k] = *(const PG8_LAS bf16x8*)(lds + PG8_SA(b, h) + aoff + m * 2048 + k * 1024); } while (0)
; #define PG8_LDB(dst, b, h) do { _Pragma("unroll") for (int n = 0; n < 2; ++n) _Pragma("unroll") for (int k = 0; k < 2; ++k) dst[n][k] = *(const PG8_LAS bf16x8*)(lds + PG8_SB(b, h) + boff + n * 2048 + k * 1024); } while (0)
; #define PG8_MMA(ai, bj, At, Bt) do { __builtin_amdgcn_s_setprio(1); _Pragma("unroll") for (int m = 0; m < 4; ++m) _Pragma("unroll") for (int n = 0; n < 2; ++n) _Pragma("unroll") for (int k = 0; k < 2; ++k) \
;         acc[ai][bj][m][n] = __builtin_amdgcn_mfma_f32_16x16x32_bf16(Bt[n][k], At[m][k], acc[ai][bj][m][n], 0, 0, 0); __builtin_amdgcn_s_setprio(0); } while (0)
; #define PG8_WAIT_V(n) asm volatile("s_waitcnt vmcnt(" #n ")" ::: "memory")
; #define PG8_WAIT_L(n) asm volatile("s_waitcnt lgkmcnt(" #n ")" ::: "memory")
; template <class Epi, class Sched, bool ALIGN_EPI = false, bool SP2 = false>
; __device__ __forceinline__ void gemm_phase(PG8_LAS unsigned char* lds, const Gemm g, const Sched S, const Epi E, const int tid) {
;     ...
;             const bool last = (t == nt - 2);
;             const char* a1 = cA + (size_t)(t + 1) * kstep;
;             const char* a2 = last ? nA : cA + (size_t)(t + 2) * kstep; const char* b2 = last ? nB : cB + (size_t)(t + 2) * kstep;
;             const char* a3 = a2 + kstep; const char* b3 = b2 + kstep;
;             if (last && has_next) S.a_ready(nxt);
;             if constexpr (SP2) {
;             PG8_LDB(B0, 0, 0); PG8_LDB(B1, 0, 1); PG8_SCHED; PG8_LDA(At, 0, 0); PG8_STAGE(PG8_SA(1, 1), a1 + hstepA, voffA);
;             PG8_WAIT_V(8); PG8_WAIT_L(0); PG8_BAR; PG8_MMA(0, 0, At, B0); PG8_MMA(0, 1, At, B1); PG8_BAR; PG8_SCHED;
;             PG8_LDA(At, 0, 1); PG8_STAGE(PG8_SB(0, 0), b2, voffB); PG8_STAGE(PG8_SB(0, 1), b2 + hstepB, voffB); PG8_STAGE(PG8_SA(0, 0), a2, voffA);
;             PG8_WAIT_V(8); PG8_WAIT_L(0); PG8_BAR; PG8_MMA(1, 0, At, B0); PG8_MMA(1, 1, At, B1); PG8_BAR; PG8_SCHED;
.LBB0_672:
	v_add_u32_e32 v162, s69, v149
	v_add_u32_e32 v178, s70, v149
	ds_read_b128 v[144:147], v162
	ds_read_b128 v[154:157], v162 offset:1024
	ds_read_b128 v[158:161], v162 offset:2048
	ds_read_b128 v[162:165], v162 offset:3072
	ds_read_b128 v[166:169], v178
	ds_read_b128 v[170:173], v178 offset:1024
	ds_read_b128 v[174:177], v178 offset:2048
	ds_read_b128 v[178:181], v178 offset:3072
	s_add_u32 s6, s38, 0x100
	s_addc_u32 s7, s39, 0
	s_cmp_eq_u32 s75, 12
	s_cselect_b32 s47, s31, s7
	s_cselect_b32 s46, s30, s6
	s_cselect_b32 s41, s29, s74
	s_cselect_b32 s40, s37, s73
	s_add_i32 m0, s58, 0xc000
	ds_read_b128 v[182:185], v153
	ds_read_b128 v[188:191], v153 offset:1024
	ds_read_b128 v[192:195], v153 offset:2048
	ds_read_b128 v[196:199], v153 offset:3072
	ds_read_b128 v[200:203], v153 offset:4096
	ds_read_b128 v[204:207], v153 offset:5120
	ds_read_b128 v[208:211], v153 offset:6144
	ds_read_b128 v[212:215], v153 offset:7168
	global_load_lds_dwordx4 v136, s[38:39]
	s_add_i32 m0, s58, 0xe000
	s_nop 0
	global_load_lds_dwordx4 v138, s[38:39]
	s_waitcnt vmcnt(8)
	s_waitcnt lgkmcnt(0)
	s_barrier
	s_setprio 1
	s_waitcnt lgkmcnt(0)
	v_mfma_f32_16x16x32_bf16 v[112:115], v[144:147], v[182:185], v[112:115]
	v_mfma_f32_16x16x32_bf16 v[120:123], v[158:161], v[182:185], v[120:123]
	v_mfma_f32_16x16x32_bf16 v[96:99], v[144:147], v[192:195], v[96:99]
	v_mfma_f32_16x16x32_bf16 v[104:107], v[158:161], v[192:195], v[104:107]
	v_mfma_f32_16x16x32_bf16 v[80:83], v[144:147], v[200:203], v[80:83]
	v_mfma_f32_16x16x32_bf16 v[88:91], v[158:161], v[200:203], v[88:91]
	v_mfma_f32_16x16x32_bf16 v[64:67], v[144:147], v[208:211], v[64:67]
	v_mfma_f32_16x16x32_bf16 v[72:75], v[158:161], v[208:211], v[72:75]
	v_mfma_f32_16x16x32_bf16 v[112:115], v[154:157], v[188:191], v[112:115]
	v_mfma_f32_16x16x32_bf16 v[120:123], v[162:165], v[188:191], v[120:123]
	v_mfma_f32_16x16x32_bf16 v[96:99], v[154:157], v[196:199], v[96:99]
	v_mfma_f32_16x16x32_bf16 v[104:107], v[162:165], v[196:199], v[104:107]
	v_mfma_f32_16x16x32_bf16 v[80:83], v[154:157], v[204:207], v[80:83]
	v_mfma_f32_16x16x32_bf16 v[88:91], v[162:165], v[204:207], v[88:91]
	v_mfma_f32_16x16x32_bf16 v[64:67], v[154:157], v[212:215], v[64:67]
	v_mfma_f32_16x16x32_bf16 v[72:75], v[162:165], v[212:215], v[72:75]
	s_setprio 0
	s_setprio 1
	v_mfma_f32_16x16x32_bf16 v[116:119], v[166:169], v[182:185], v[116:119]
	v_mfma_f32_16x16x32_bf16 v[124:127], v[174:177], v[182:185], v[124:127]
	v_mfma_f32_16x16x32_bf16 v[100:103], v[166:169], v[192:195], v[100:103]
	v_mfma_f32_16x16x32_bf16 v[108:111], v[174:177], v[192:195], v[108:111]
	v_mfma_f32_16x16x32_bf16 v[84:87], v[166:169], v[200:203], v[84:87]
	v_mfma_f32_16x16x32_bf16 v[92:95], v[174:177], v[200:203], v[92:95]
	v_mfma_f32_16x16x32_bf16 v[68:71], v[166:169], v[208:211], v[68:71]
	v_mfma_f32_16x16x32_bf16 v[76:79], v[174:177], v[208:211], v[76:79]
	v_mfma_f32_16x16x32_bf16 v[116:119], v[170:173], v[188:191], v[116:119]
	v_mfma_f32_16x16x32_bf16 v[124:127], v[178:181], v[188:191], v[124:127]
	v_mfma_f32_16x16x32_bf16 v[100:103], v[170:173], v[196:199], v[100:103]
	v_mfma_f32_16x16x32_bf16 v[108:111], v[178:181], v[196:199], v[108:111]
	v_mfma_f32_16x16x32_bf16 v[84:87], v[170:173], v[204:207], v[84:87]
	v_mfma_f32_16x16x32_bf16 v[92:95], v[178:181], v[204:207], v[92:95]
	v_mfma_f32_16x16x32_bf16 v[68:71], v[170:173], v[212:215], v[68:71]
	v_mfma_f32_16x16x32_bf16 v[76:79], v[178:181], v[212:215], v[76:79]
	s_setprio 0
	s_barrier
	s_add_u32 s98, s40, 0x80
	s_addc_u32 s99, s41, 0
	s_add_u32 s100, s46, 0x80
	s_addc_u32 s101, s47, 0
	s_add_i32 s38, s69, s33
	s_mov_b32 m0, s38
	ds_read_b128 v[182:185], v153 offset:16384
	ds_read_b128 v[188:191], v153 offset:17408
	ds_read_b128 v[192:195], v153 offset:18432
	ds_read_b128 v[196:199], v153 offset:19456
	ds_read_b128 v[200:203], v153 offset:20480
	ds_read_b128 v[204:207], v153 offset:21504
	ds_read_b128 v[208:211], v153 offset:22528
	ds_read_b128 v[212:215], v153 offset:23552
	global_load_lds_dwordx4 v130, s[40:41]
	s_add_i32 m0, s38, 0x2000
	s_add_u32 s38, s40, 0x40000
	s_addc_u32 s39, s41, 0
	s_add_i32 s76, s70, s33
	global_load_lds_dwordx4 v134, s[40:41]
	s_mov_b32 m0, s76
	s_nop 0
	global_load_lds_dwordx4 v130, s[38:39]
	s_add_i32 m0, s76, 0x2000
	s_nop 0
	global_load_lds_dwordx4 v134, s[38:39]
	s_mov_b32 m0, s58
	s_nop 0
	global_load_lds_dwordx4 v128, s[46:47]
	s_mov_b32 m0, s59
	s_nop 0
	global_load_lds_dwordx4 v132, s[46:47]
	s_waitcnt vmcnt(8)
	s_waitcnt lgkmcnt(0)
	s_barrier
	s_setprio 1
	s_waitcnt lgkmcnt(0)
	v_mfma_f32_16x16x32_bf16 v[48:51], v[144:147], v[182:185], v[48:51]
	v_mfma_f32_16x16x32_bf16 v[56:59], v[158:161], v[182:185], v[56:59]
	v_mfma_f32_16x16x32_bf16 v[24:27], v[144:147], v[192:195], v[24:27]
	v_mfma_f32_16x16x32_bf16 v[32:35], v[158:161], v[192:195], v[32:35]
	v_mfma_f32_16x16x32_bf16 v[0:3], v[144:147], v[200:203], v[0:3]
	v_mfma_f32_16x16x32_bf16 v[4:7], v[158:161], v[200:203], v[4:7]
	v_mfma_f32_16x16x32_bf16 v[8:11], v[144:147], v[208:211], v[8:11]
	v_mfma_f32_16x16x32_bf16 v[16:19], v[158:161], v[208:211], v[16:19]
	v_mfma_f32_16x16x32_bf16 v[48:51], v[154:157], v[188:191], v[48:51]
	v_mfma_f32_16x16x32_bf16 v[56:59], v[162:165], v[188:191], v[56:59]
	v_mfma_f32_16x16x32_bf16 v[24:27], v[154:157], v[196:199], v[24:27]
	v_mfma_f32_16x16x32_bf16 v[32:35], v[162:165], v[196:199], v[32:35]
	v_mfma_f32_16x16x32_bf16 v[0:3], v[154:157], v[204:207], v[0:3]
	v_mfma_f32_16x16x32_bf16 v[4:7], v[162:165], v[204:207], v[4:7]
	v_mfma_f32_16x16x32_bf16 v[8:11], v[154:157], v[212:215], v[8:11]
	v_mfma_f32_16x16x32_bf16 v[16:19], v[162:165], v[212:215], v[16:19]
	s_setprio 0
	s_setprio 1
	v_mfma_f32_16x16x32_bf16 v[52:55], v[166:169], v[182:185], v[52:55]
	v_mfma_f32_16x16x32_bf16 v[60:63], v[174:177], v[182:185], v[60:63]
	v_mfma_f32_16x16x32_bf16 v[28:31], v[166:169], v[192:195], v[28:31]
	v_mfma_f32_16x16x32_bf16 v[36:39], v[174:177], v[192:195], v[36:39]
	v_mfma_f32_16x16x32_bf16 v[40:43], v[166:169], v[200:203], v[40:43]
	v_mfma_f32_16x16x32_bf16 v[44:47], v[174:177], v[200:203], v[44:47]
	v_mfma_f32_16x16x32_bf16 v[12:15], v[166:169], v[208:211], v[12:15]
	v_mfma_f32_16x16x32_bf16 v[20:23], v[174:177], v[208:211], v[20:23]
	v_mfma_f32_16x16x32_bf16 v[52:55], v[170:173], v[188:191], v[52:55]
	v_mfma_f32_16x16x32_bf16 v[60:63], v[178:181], v[188:191], v[60:63]
	v_mfma_f32_16x16x32_bf16 v[28:31], v[170:173], v[196:199], v[28:31]
	v_mfma_f32_16x16x32_bf16 v[36:39], v[178:181], v[196:199], v[36:39]
	v_mfma_f32_16x16x32_bf16 v[40:43], v[170:173], v[204:207], v[40:43]
	v_mfma_f32_16x16x32_bf16 v[44:47], v[178:181], v[204:207], v[44:47]
	v_mfma_f32_16x16x32_bf16 v[12:15], v[170:173], v[212:215], v[12:15]
	v_mfma_f32_16x16x32_bf16 v[20:23], v[178:181], v[212:215], v[20:23]
	s_setprio 0
	s_barrier
; #define PG8_STAGE(bufoff, gbase, voff) do { _Pragma("unroll") for (int _i = 0; _i < 2; ++_i) \
;         __builtin_amdgcn_global_load_lds((const unsigned*)((const char*)(gbase) + (voff)[_i]), (PG8_LAS unsigned*)(lds + (bufoff) + ldsw + _i * 8192), 16, 0, 0); } while (0)
; #define PG8_LDA(dst, b, h) do { _Pragma("unroll") for (int m = 0; m < 4; ++m) _Pragma("unroll") for (int k = 0; k < 2; ++k) dst[m][k] = *(const PG8_LAS bf16x8*)(lds + PG8_SA(b, h) + aoff + m * 2048 + k * 1024); } while (0)
; #define PG8_LDB(dst, b, h) do { _Pragma("unroll") for (int n = 0; n < 2; ++n) _Pragma("unroll") for (int k = 0; k < 2; ++k) dst[n][k] = *(const PG8_LAS bf16x8*)(lds + PG8_SB(b, h) + boff + n * 2048 + k * 1024); } while (0)
; #define PG8_MMA(ai, bj, At, Bt) do { __builtin_amdgcn_s_setprio(1); _Pragma("unroll") for (int m = 0; m < 4; ++m) _Pragma("unroll") for (int n = 0; n < 2; ++n) _Pragma("unroll") for (int k = 0; k < 2; ++k) \
;         acc[ai][bj][m][n] = __builtin_amdgcn_mfma_f32_16x16x32_bf16(Bt[n][k], At[m][k], acc[ai][bj][m][n], 0, 0, 0); __builtin_amdgcn_s_setprio(0); } while (0)
; #define PG8_WAIT_V(n) asm volatile("s_waitcnt vmcnt(" #n ")" ::: "memory")
; #define PG8_WAIT_L(n) asm volatile("s_waitcnt lgkmcnt(" #n ")" ::: "memory")
; #define PG8_BAR __builtin_amdgcn_s_barrier()
; #define PG8_SCHED __builtin_amdgcn_sched_barrier(0)
; template <class Epi, class Sched, bool ALIGN_EPI = false, bool SP2 = false>
; __device__ __forceinline__ void gemm_phase(PG8_LAS unsigned char* lds, const Gemm g, const Sched S, const Epi E, const int tid) {
;     ...
;             PG8_LDB(B0, 1, 0); PG8_LDB(B1, 1, 1); PG8_SCHED; PG8_LDA(At, 1, 0); PG8_STAGE(PG8_SA(0, 1), a2 + hstepA, voffA);
;             PG8_WAIT_V(8); PG8_WAIT_L(0); PG8_BAR; PG8_MMA(0, 0, At, B0); PG8_MMA(0, 1, At, B1); PG8_BAR; PG8_SCHED;
;             PG8_LDA(At, 1, 1); PG8_STAGE(PG8_SB(1, 0), b3, voffB); PG8_STAGE(PG8_SB(1, 1), b3 + hstepB, voffB); PG8_STAGE(PG8_SA(1, 0), a3, voffA);
;             PG8_WAIT_V(8); PG8_WAIT_L(0); PG8_BAR; PG8_MMA(1, 0, At, B0); PG8_MMA(1, 1, At, B1); PG8_BAR; PG8_SCHED;
	s_add_i32 s76, 0, 0x18000
	s_add_i32 s77, 0, 0x1c000
	v_add_u32_e32 v162, s76, v149
	v_add_u32_e32 v178, s77, v149
	ds_read_b128 v[144:147], v162
	ds_read_b128 v[154:157], v162 offset:1024
	ds_read_b128 v[158:161], v162 offset:2048
	ds_read_b128 v[162:165], v162 offset:3072
	ds_read_b128 v[166:169], v178
	ds_read_b128 v[170:173], v178 offset:1024
	ds_read_b128 v[174:177], v178 offset:2048
	ds_read_b128 v[178:181], v178 offset:3072
	s_add_u32 s38, s46, 0xc0000
	s_addc_u32 s39, s47, 0
	s_mov_b32 m0, s60
	ds_read_b128 v[182:185], v153 offset:32768
	ds_read_b128 v[188:191], v153 offset:33792
	ds_read_b128 v[192:195], v153 offset:34816
	ds_read_b128 v[196:199], v153 offset:35840
	ds_read_b128 v[200:203], v153 offset:36864
	ds_read_b128 v[204:207], v153 offset:37888
	ds_read_b128 v[208:211], v153 offset:38912
	ds_read_b128 v[212:215], v153 offset:39936
	global_load_lds_dwordx4 v128, s[38:39]
	s_mov_b32 m0, s61
	s_nop 0
	global_load_lds_dwordx4 v132, s[38:39]
	s_waitcnt vmcnt(8)
	s_waitcnt lgkmcnt(0)
	s_barrier
	s_setprio 1
	s_waitcnt lgkmcnt(0)
	v_mfma_f32_16x16x32_bf16 v[112:115], v[144:147], v[182:185], v[112:115]
	v_mfma_f32_16x16x32_bf16 v[120:123], v[158:161], v[182:185], v[120:123]
	v_mfma_f32_16x16x32_bf16 v[96:99], v[144:147], v[192:195], v[96:99]
	v_mfma_f32_16x16x32_bf16 v[104:107], v[158:161], v[192:195], v[104:107]
	v_mfma_f32_16x16x32_bf16 v[80:83], v[144:147], v[200:203], v[80:83]
	v_mfma_f32_16x16x32_bf16 v[88:91], v[158:161], v[200:203], v[88:91]
	v_mfma_f32_16x16x32_bf16 v[64:67], v[144:147], v[208:211], v[64:67]
	v_mfma_f32_16x16x32_bf16 v[72:75], v[158:161], v[208:211], v[72:75]
	v_mfma_f32_16x16x32_bf16 v[112:115], v[154:157], v[188:191], v[112:115]
	v_mfma_f32_16x16x32_bf16 v[120:123], v[162:165], v[188:191], v[120:123]
	v_mfma_f32_16x16x32_bf16 v[96:99], v[154:157], v[196:199], v[96:99]
	v_mfma_f32_16x16x32_bf16 v[104:107], v[162:165], v[196:199], v[104:107]
	v_mfma_f32_16x16x32_bf16 v[80:83], v[154:157], v[204:207], v[80:83]
	v_mfma_f32_16x16x32_bf16 v[88:91], v[162:165], v[204:207], v[88:91]
	v_mfma_f32_16x16x32_bf16 v[64:67], v[154:157], v[212:215], v[64:67]
	v_mfma_f32_16x16x32_bf16 v[72:75], v[162:165], v[212:215], v[72:75]
	s_setprio 0
	s_setprio 1
	v_mfma_f32_16x16x32_bf16 v[116:119], v[166:169], v[182:185], v[116:119]
	v_mfma_f32_16x16x32_bf16 v[124:127], v[174:177], v[182:185], v[124:127]
	v_mfma_f32_16x16x32_bf16 v[100:103], v[166:169], v[192:195], v[100:103]
	v_mfma_f32_16x16x32_bf16 v[108:111], v[174:177], v[192:195], v[108:111]
	v_mfma_f32_16x16x32_bf16 v[84:87], v[166:169], v[200:203], v[84:87]
	v_mfma_f32_16x16x32_bf16 v[92:95], v[174:177], v[200:203], v[92:95]
	v_mfma_f32_16x16x32_bf16 v[68:71], v[166:169], v[208:211], v[68:71]
	v_mfma_f32_16x16x32_bf16 v[76:79], v[174:177], v[208:211], v[76:79]
	v_mfma_f32_16x16x32_bf16 v[116:119], v[170:173], v[188:191], v[116:119]
	v_mfma_f32_16x16x32_bf16 v[124:127], v[178:181], v[188:191], v[124:127]
	v_mfma_f32_16x16x32_bf16 v[100:103], v[170:173], v[196:199], v[100:103]
	v_mfma_f32_16x16x32_bf16 v[108:111], v[178:181], v[196:199], v[108:111]
	v_mfma_f32_16x16x32_bf16 v[84:87], v[170:173], v[204:207], v[84:87]
	v_mfma_f32_16x16x32_bf16 v[92:95], v[178:181], v[204:207], v[92:95]
	v_mfma_f32_16x16x32_bf16 v[68:71], v[170:173], v[212:215], v[68:71]
	v_mfma_f32_16x16x32_bf16 v[76:79], v[178:181], v[212:215], v[76:79]
	s_setprio 0
	s_barrier
	s_add_i32 s38, s76, s33
	s_mov_b32 m0, s38
	ds_read_b128 v[182:185], v153 offset:49152
	ds_read_b128 v[188:191], v153 offset:50176
	ds_read_b128 v[192:195], v153 offset:51200
	ds_read_b128 v[196:199], v153 offset:52224
	ds_read_b128 v[200:203], v153 offset:53248
	ds_read_b128 v[204:207], v153 offset:54272
	ds_read_b128 v[208:211], v153 offset:55296
	ds_read_b128 v[212:215], v153 offset:56320
	global_load_lds_dwordx4 v130, s[98:99]
	s_add_i32 m0, s38, 0x2000
	s_add_u32 s38, s40, 0x40080
	s_addc_u32 s39, s41, 0
	s_add_i32 s40, s77, s33
	global_load_lds_dwordx4 v134, s[98:99]
	s_mov_b32 m0, s40
	s_nop 0
	global_load_lds_dwordx4 v130, s[38:39]
	s_add_i32 m0, s40, 0x2000
	s_nop 0
	global_load_lds_dwordx4 v134, s[38:39]
	s_mov_b32 m0, s63
	s_nop 0
	global_load_lds_dwordx4 v128, s[100:101]
	s_mov_b32 m0, s64
	s_nop 0
	global_load_lds_dwordx4 v132, s[100:101]
	s_waitcnt vmcnt(8)
	s_waitcnt lgkmcnt(0)
	s_barrier
	s_setprio 1
	s_waitcnt lgkmcnt(0)
	v_mfma_f32_16x16x32_bf16 v[48:51], v[144:147], v[182:185], v[48:51]
	v_mfma_f32_16x16x32_bf16 v[56:59], v[158:161], v[182:185], v[56:59]
	v_mfma_f32_16x16x32_bf16 v[24:27], v[144:147], v[192:195], v[24:27]
	v_mfma_f32_16x16x32_bf16 v[32:35], v[158:161], v[192:195], v[32:35]
	v_mfma_f32_16x16x32_bf16 v[0:3], v[144:147], v[200:203], v[0:3]
	v_mfma_f32_16x16x32_bf16 v[4:7], v[158:161], v[200:203], v[4:7]
	v_mfma_f32_16x16x32_bf16 v[8:11], v[144:147], v[208:211], v[8:11]
	v_mfma_f32_16x16x32_bf16 v[16:19], v[158:161], v[208:211], v[16:19]
	v_mfma_f32_16x16x32_bf16 v[48:51], v[154:157], v[188:191], v[48:51]
	v_mfma_f32_16x16x32_bf16 v[56:59], v[162:165], v[188:191], v[56:59]
	v_mfma_f32_16x16x32_bf16 v[24:27], v[154:157], v[196:199], v[24:27]
	v_mfma_f32_16x16x32_bf16 v[32:35], v[162:165], v[196:199], v[32:35]
	v_mfma_f32_16x16x32_bf16 v[0:3], v[154:157], v[204:207], v[0:3]
	v_mfma_f32_16x16x32_bf16 v[4:7], v[162:165], v[204:207], v[4:7]
	v_mfma_f32_16x16x32_bf16 v[8:11], v[154:157], v[212:215], v[8:11]
	v_mfma_f32_16x16x32_bf16 v[16:19], v[162:165], v[212:215], v[16:19]
	s_setprio 0
	s_setprio 1
	v_mfma_f32_16x16x32_bf16 v[52:55], v[166:169], v[182:185], v[52:55]
	v_mfma_f32_16x16x32_bf16 v[60:63], v[174:177], v[182:185], v[60:63]
	v_mfma_f32_16x16x32_bf16 v[28:31], v[166:169], v[192:195], v[28:31]
	v_mfma_f32_16x16x32_bf16 v[36:39], v[174:177], v[192:195], v[36:39]
	v_mfma_f32_16x16x32_bf16 v[40:43], v[166:169], v[200:203], v[40:43]
	v_mfma_f32_16x16x32_bf16 v[44:47], v[174:177], v[200:203], v[44:47]
	v_mfma_f32_16x16x32_bf16 v[12:15], v[166:169], v[208:211], v[12:15]
	v_mfma_f32_16x16x32_bf16 v[20:23], v[174:177], v[208:211], v[20:23]
	v_mfma_f32_16x16x32_bf16 v[52:55], v[170:173], v[188:191], v[52:55]
	v_mfma_f32_16x16x32_bf16 v[60:63], v[178:181], v[188:191], v[60:63]
	v_mfma_f32_16x16x32_bf16 v[28:31], v[170:173], v[196:199], v[28:31]
	v_mfma_f32_16x16x32_bf16 v[36:39], v[178:181], v[196:199], v[36:39]
	v_mfma_f32_16x16x32_bf16 v[40:43], v[170:173], v[204:207], v[40:43]
	v_mfma_f32_16x16x32_bf16 v[44:47], v[178:181], v[204:207], v[44:47]
	v_mfma_f32_16x16x32_bf16 v[12:15], v[170:173], v[212:215], v[12:15]
	v_mfma_f32_16x16x32_bf16 v[20:23], v[178:181], v[212:215], v[20:23]
	s_setprio 0
	s_barrier
	s_add_i32 s75, s75, 2
	s_add_u32 s73, s73, 0x100
	s_addc_u32 s74, s74, 0
	s_cmp_gt_u32 s75, 13
	s_mov_b64 s[38:39], s[6:7]
	s_cbranch_scc0 .LBB0_672
	s_and_b64 vcc, exec, s[24:25]
	s_cbranch_vccz .LBB0_675
	s_barrier

; #define PG8_STAGE(bufoff, gbase, voff) do { _Pragma("unroll") for (int _i = 0; _i < 2; ++_i) \
;         __builtin_amdgcn_global_load_lds((const unsigned*)((const char*)(gbase) + (voff)[_i]), (PG8_LAS unsigned*)(lds + (bufoff) + ldsw + _i * 8192), 16, 0, 0); } while (0)
; #define PG8_LDA(dst, b, h) do { _Pragma("unroll") for (int m = 0; m < 4; ++m) _Pragma("unroll") for (int k = 0; k < 2; ++k) dst[m][k] = *(const PG8_LAS bf16x8*)(lds + PG8_SA(b, h) + aoff + m * 2048 + k * 1024); } while (0)
; #define PG8_LDB(dst, b, h) do { _Pragma("unroll") for (int n = 0; n < 2; ++n) _Pragma("unroll") for (int k = 0; k < 2; ++k) dst[n][k] = *(const PG8_LAS bf16x8*)(lds + PG8_SB(b, h) + boff + n * 2048 + k * 1024); } while (0)
; #define PG8_MMA(ai, bj, At, Bt) do { __builtin_amdgcn_s_setprio(1); _Pragma("unroll") for (int m = 0; m < 4; ++m) _Pragma("unroll") for (int n = 0; n < 2; ++n) _Pragma("unroll") for (int k = 0; k < 2; ++k) \
;         acc[ai][bj][m][n] = __builtin_amdgcn_mfma_f32_16x16x32_bf16(Bt[n][k], At[m][k], acc[ai][bj][m][n], 0, 0, 0); __builtin_amdgcn_s_setprio(0); } while (0)
; #define PG8_WAIT_V(n) asm volatile("s_waitcnt vmcnt(" #n ")" ::: "memory")
; #define PG8_WAIT_L(n) asm volatile("s_waitcnt lgkmcnt(" #n ")" ::: "memory")
; template <class Epi, class Sched, bool ALIGN_EPI = false, bool SP2 = false>
; __device__ __forceinline__ void gemm_phase(PG8_LAS unsigned char* lds, const Gemm g, const Sched S, const Epi E, const int tid) {
;     ...
;             const bool last = (t == nt - 2);
;             const char* a1 = cA + (size_t)(t + 1) * kstep;
;             const char* a2 = last ? nA : cA + (size_t)(t + 2) * kstep; const char* b2 = last ? nB : cB + (size_t)(t + 2) * kstep;
;             const char* a3 = a2 + kstep; const char* b3 = b2 + kstep;
;             if (last && has_next) S.a_ready(nxt);
;             if constexpr (SP2) {
;             PG8_LDB(B0, 0, 0); PG8_LDB(B1, 0, 1); PG8_SCHED; PG8_LDA(At, 0, 0); PG8_STAGE(PG8_SA(1, 1), a1 + hstepA, voffA);
;             PG8_WAIT_V(8); PG8_WAIT_L(0); PG8_BAR; PG8_MMA(0, 0, At, B0); PG8_MMA(0, 1, At, B1); PG8_BAR; PG8_SCHED;
;             PG8_LDA(At, 0, 1); PG8_STAGE(PG8_SB(0, 0), b2, voffB); PG8_STAGE(PG8_SB(0, 1), b2 + hstepB, voffB); PG8_STAGE(PG8_SA(0, 0), a2, voffA);
;             PG8_WAIT_V(8); PG8_WAIT_L(0); PG8_BAR; PG8_MMA(1, 0, At, B0); PG8_MMA(1, 1, At, B1); PG8_BAR; PG8_SCHED;
.LBB0_757:
	ds_read_b128 v[128:131], v206
	ds_read_b128 v[132:135], v206 offset:1024
	ds_read_b128 v[136:139], v206 offset:2048
	ds_read_b128 v[156:159], v206 offset:3072
	ds_read_b128 v[160:163], v207
	ds_read_b128 v[164:167], v207 offset:1024
	ds_read_b128 v[168:171], v207 offset:2048
	ds_read_b128 v[172:175], v207 offset:3072
	s_add_u32 s38, s36, 0xfffc0080
	s_addc_u32 s39, s37, -1
	s_cmp_eq_u32 s61, 12
	s_cselect_b32 s41, s5, s39
	s_cselect_b32 s40, s29, s38
	s_cselect_b32 s39, s27, s60
	s_cselect_b32 s38, s58, s59
	s_add_i32 m0, s47, 0xc000
	ds_read_b128 v[210:213], v208
	ds_read_b128 v[214:217], v208 offset:1024
	ds_read_b128 v[218:221], v208 offset:2048
	ds_read_b128 v[222:225], v208 offset:3072
	ds_read_b128 v[226:229], v208 offset:4096
	ds_read_b128 v[230:233], v208 offset:5120
	ds_read_b128 v[234:237], v208 offset:6144
	ds_read_b128 v[238:241], v208 offset:7168
	global_load_lds_dwordx4 v148, s[36:37]
	s_add_i32 m0, s47, 0xe000
	s_nop 0
	global_load_lds_dwordx4 v150, s[36:37]
	s_waitcnt vmcnt(8)
	s_waitcnt lgkmcnt(0)
	s_barrier
	s_setprio 1
	s_waitcnt lgkmcnt(0)
	v_mfma_f32_16x16x32_bf16 v[124:127], v[128:131], v[210:213], v[124:127]
	v_mfma_f32_16x16x32_bf16 v[120:123], v[136:139], v[210:213], v[120:123]
	v_mfma_f32_16x16x32_bf16 v[112:115], v[128:131], v[218:221], v[112:115]
	v_mfma_f32_16x16x32_bf16 v[104:107], v[136:139], v[218:221], v[104:107]
	v_mfma_f32_16x16x32_bf16 v[96:99], v[128:131], v[226:229], v[96:99]
	v_mfma_f32_16x16x32_bf16 v[88:91], v[136:139], v[226:229], v[88:91]
	v_mfma_f32_16x16x32_bf16 v[80:83], v[128:131], v[234:237], v[80:83]
	v_mfma_f32_16x16x32_bf16 v[72:75], v[136:139], v[234:237], v[72:75]
	v_mfma_f32_16x16x32_bf16 v[124:127], v[132:135], v[214:217], v[124:127]
	v_mfma_f32_16x16x32_bf16 v[120:123], v[156:159], v[214:217], v[120:123]
	v_mfma_f32_16x16x32_bf16 v[112:115], v[132:135], v[222:225], v[112:115]
	v_mfma_f32_16x16x32_bf16 v[104:107], v[156:159], v[222:225], v[104:107]
	v_mfma_f32_16x16x32_bf16 v[96:99], v[132:135], v[230:233], v[96:99]
	v_mfma_f32_16x16x32_bf16 v[88:91], v[156:159], v[230:233], v[88:91]
	v_mfma_f32_16x16x32_bf16 v[80:83], v[132:135], v[238:241], v[80:83]
	v_mfma_f32_16x16x32_bf16 v[72:75], v[156:159], v[238:241], v[72:75]
	s_setprio 0
	s_setprio 1
	v_mfma_f32_16x16x32_bf16 v[116:119], v[160:163], v[210:213], v[116:119]
	v_mfma_f32_16x16x32_bf16 v[108:111], v[168:171], v[210:213], v[108:111]
	v_mfma_f32_16x16x32_bf16 v[100:103], v[160:163], v[218:221], v[100:103]
	v_mfma_f32_16x16x32_bf16 v[92:95], v[168:171], v[218:221], v[92:95]
	v_mfma_f32_16x16x32_bf16 v[84:87], v[160:163], v[226:229], v[84:87]
	v_mfma_f32_16x16x32_bf16 v[76:79], v[168:171], v[226:229], v[76:79]
	v_mfma_f32_16x16x32_bf16 v[68:71], v[160:163], v[234:237], v[68:71]
	v_mfma_f32_16x16x32_bf16 v[64:67], v[168:171], v[234:237], v[64:67]
	v_mfma_f32_16x16x32_bf16 v[116:119], v[164:167], v[214:217], v[116:119]
	v_mfma_f32_16x16x32_bf16 v[108:111], v[172:175], v[214:217], v[108:111]
	v_mfma_f32_16x16x32_bf16 v[100:103], v[164:167], v[222:225], v[100:103]
	v_mfma_f32_16x16x32_bf16 v[92:95], v[172:175], v[222:225], v[92:95]
	v_mfma_f32_16x16x32_bf16 v[84:87], v[164:167], v[230:233], v[84:87]
	v_mfma_f32_16x16x32_bf16 v[76:79], v[172:175], v[230:233], v[76:79]
	v_mfma_f32_16x16x32_bf16 v[68:71], v[164:167], v[238:241], v[68:71]
	v_mfma_f32_16x16x32_bf16 v[64:67], v[172:175], v[238:241], v[64:67]
	s_setprio 0
	s_barrier
	s_add_u32 s98, s38, 0x80
	s_addc_u32 s99, s39, 0
	s_add_u32 s100, s40, 0x80
	s_addc_u32 s101, s41, 0
	s_add_i32 s62, s55, s46
	s_mov_b32 m0, s62
	ds_read_b128 v[210:213], v208 offset:16384
	ds_read_b128 v[214:217], v208 offset:17408
	ds_read_b128 v[218:221], v208 offset:18432
	ds_read_b128 v[222:225], v208 offset:19456
	ds_read_b128 v[226:229], v208 offset:20480
	ds_read_b128 v[230:233], v208 offset:21504
	ds_read_b128 v[234:237], v208 offset:22528
	ds_read_b128 v[238:241], v208 offset:23552
	global_load_lds_dwordx4 v142, s[38:39]
	s_add_i32 m0, s62, 0x2000
	s_add_u32 s62, s38, 0x40000
	s_addc_u32 s63, s39, 0
	s_add_i32 s64, s56, s46
	global_load_lds_dwordx4 v146, s[38:39]
	s_mov_b32 m0, s64
	s_nop 0
	global_load_lds_dwordx4 v142, s[62:63]
	s_add_i32 m0, s64, 0x2000
	s_nop 0
	global_load_lds_dwordx4 v146, s[62:63]
	s_mov_b32 m0, s47
	s_nop 0
	global_load_lds_dwordx4 v140, s[40:41]
	s_mov_b32 m0, s48
	s_nop 0
	global_load_lds_dwordx4 v144, s[40:41]
	s_waitcnt vmcnt(8)
	s_waitcnt lgkmcnt(0)
	s_barrier
	s_setprio 1
	s_waitcnt lgkmcnt(0)
	v_mfma_f32_16x16x32_bf16 v[60:63], v[128:131], v[210:213], v[60:63]
	v_mfma_f32_16x16x32_bf16 v[56:59], v[136:139], v[210:213], v[56:59]
	v_mfma_f32_16x16x32_bf16 v[48:51], v[128:131], v[218:221], v[48:51]
	v_mfma_f32_16x16x32_bf16 v[40:43], v[136:139], v[218:221], v[40:43]
	v_mfma_f32_16x16x32_bf16 v[32:35], v[128:131], v[226:229], v[32:35]
	v_mfma_f32_16x16x32_bf16 v[24:27], v[136:139], v[226:229], v[24:27]
	v_mfma_f32_16x16x32_bf16 v[16:19], v[128:131], v[234:237], v[16:19]
	v_mfma_f32_16x16x32_bf16 v[8:11], v[136:139], v[234:237], v[8:11]
	v_mfma_f32_16x16x32_bf16 v[60:63], v[132:135], v[214:217], v[60:63]
	v_mfma_f32_16x16x32_bf16 v[56:59], v[156:159], v[214:217], v[56:59]
	v_mfma_f32_16x16x32_bf16 v[48:51], v[132:135], v[222:225], v[48:51]
	v_mfma_f32_16x16x32_bf16 v[40:43], v[156:159], v[222:225], v[40:43]
	v_mfma_f32_16x16x32_bf16 v[32:35], v[132:135], v[230:233], v[32:35]
	v_mfma_f32_16x16x32_bf16 v[24:27], v[156:159], v[230:233], v[24:27]
	v_mfma_f32_16x16x32_bf16 v[16:19], v[132:135], v[238:241], v[16:19]
	v_mfma_f32_16x16x32_bf16 v[8:11], v[156:159], v[238:241], v[8:11]
	s_setprio 0
	s_setprio 1
	v_mfma_f32_16x16x32_bf16 v[52:55], v[160:163], v[210:213], v[52:55]
	v_mfma_f32_16x16x32_bf16 v[44:47], v[168:171], v[210:213], v[44:47]
	v_mfma_f32_16x16x32_bf16 v[36:39], v[160:163], v[218:221], v[36:39]
	v_mfma_f32_16x16x32_bf16 v[28:31], v[168:171], v[218:221], v[28:31]
	v_mfma_f32_16x16x32_bf16 v[20:23], v[160:163], v[226:229], v[20:23]
	v_mfma_f32_16x16x32_bf16 v[12:15], v[168:171], v[226:229], v[12:15]
	v_mfma_f32_16x16x32_bf16 v[4:7], v[160:163], v[234:237], v[4:7]
	v_mfma_f32_16x16x32_bf16 v[0:3], v[168:171], v[234:237], v[0:3]
	v_mfma_f32_16x16x32_bf16 v[52:55], v[164:167], v[214:217], v[52:55]
	v_mfma_f32_16x16x32_bf16 v[44:47], v[172:175], v[214:217], v[44:47]
	v_mfma_f32_16x16x32_bf16 v[36:39], v[164:167], v[222:225], v[36:39]
	v_mfma_f32_16x16x32_bf16 v[28:31], v[172:175], v[222:225], v[28:31]
	v_mfma_f32_16x16x32_bf16 v[20:23], v[164:167], v[230:233], v[20:23]
	v_mfma_f32_16x16x32_bf16 v[12:15], v[172:175], v[230:233], v[12:15]
	v_mfma_f32_16x16x32_bf16 v[4:7], v[164:167], v[238:241], v[4:7]
	v_mfma_f32_16x16x32_bf16 v[0:3], v[172:175], v[238:241], v[0:3]
	s_setprio 0
	s_barrier
; #define PG8_STAGE(bufoff, gbase, voff) do { _Pragma("unroll") for (int _i = 0; _i < 2; ++_i) \
;         __builtin_amdgcn_global_load_lds((const unsigned*)((const char*)(gbase) + (voff)[_i]), (PG8_LAS unsigned*)(lds + (bufoff) + ldsw + _i * 8192), 16, 0, 0); } while (0)
; #define PG8_LDA(dst, b, h) do { _Pragma("unroll") for (int m = 0; m < 4; ++m) _Pragma("unroll") for (int k = 0; k < 2; ++k) dst[m][k] = *(const PG8_LAS bf16x8*)(lds + PG8_SA(b, h) + aoff + m * 2048 + k * 1024); } while (0)
; #define PG8_LDB(dst, b, h) do { _Pragma("unroll") for (int n = 0; n < 2; ++n) _Pragma("unroll") for (int k = 0; k < 2; ++k) dst[n][k] = *(const PG8_LAS bf16x8*)(lds + PG8_SB(b, h) + boff + n * 2048 + k * 1024); } while (0)
; #define PG8_MMA(ai, bj, At, Bt) do { __builtin_amdgcn_s_setprio(1); _Pragma("unroll") for (int m = 0; m < 4; ++m) _Pragma("unroll") for (int n = 0; n < 2; ++n) _Pragma("unroll") for (int k = 0; k < 2; ++k) \
;         acc[ai][bj][m][n] = __builtin_amdgcn_mfma_f32_16x16x32_bf16(Bt[n][k], At[m][k], acc[ai][bj][m][n], 0, 0, 0); __builtin_amdgcn_s_setprio(0); } while (0)
; #define PG8_WAIT_V(n) asm volatile("s_waitcnt vmcnt(" #n ")" ::: "memory")
; #define PG8_WAIT_L(n) asm volatile("s_waitcnt lgkmcnt(" #n ")" ::: "memory")
; #define PG8_BAR __builtin_amdgcn_s_barrier()
; #define PG8_SCHED __builtin_amdgcn_sched_barrier(0)
; template <class Epi, class Sched, bool ALIGN_EPI = false, bool SP2 = false>
; __device__ __forceinline__ void gemm_phase(PG8_LAS unsigned char* lds, const Gemm g, const Sched S, const Epi E, const int tid) {
;     ...
;             PG8_LDB(B0, 1, 0); PG8_LDB(B1, 1, 1); PG8_SCHED; PG8_LDA(At, 1, 0); PG8_STAGE(PG8_SA(0, 1), a2 + hstepA, voffA);
;             PG8_WAIT_V(8); PG8_WAIT_L(0); PG8_BAR; PG8_MMA(0, 0, At, B0); PG8_MMA(0, 1, At, B1); PG8_BAR; PG8_SCHED;
;             PG8_LDA(At, 1, 1); PG8_STAGE(PG8_SB(1, 0), b3, voffB); PG8_STAGE(PG8_SB(1, 1), b3 + hstepB, voffB); PG8_STAGE(PG8_SA(1, 0), a3, voffA);
;             PG8_WAIT_V(8); PG8_WAIT_L(0); PG8_BAR; PG8_MMA(1, 0, At, B0); PG8_MMA(1, 1, At, B1); PG8_BAR; PG8_SCHED;
	s_add_i32 s62, 0, 0x18000
	s_add_i32 s63, 0, 0x1c000
	v_add_u32_e32 v156, s62, v204
	v_add_u32_e32 v172, s63, v204
	ds_read_b128 v[128:131], v156
	ds_read_b128 v[132:135], v156 offset:1024
	ds_read_b128 v[136:139], v156 offset:2048
	ds_read_b128 v[156:159], v156 offset:3072
	ds_read_b128 v[160:163], v172
	ds_read_b128 v[164:167], v172 offset:1024
	ds_read_b128 v[168:171], v172 offset:2048
	ds_read_b128 v[172:175], v172 offset:3072
	s_add_u32 s40, s40, 0x40000
	s_addc_u32 s41, s41, 0
	s_mov_b32 m0, s49
	ds_read_b128 v[210:213], v208 offset:32768
	ds_read_b128 v[214:217], v208 offset:33792
	ds_read_b128 v[218:221], v208 offset:34816
	ds_read_b128 v[222:225], v208 offset:35840
	ds_read_b128 v[226:229], v208 offset:36864
	ds_read_b128 v[230:233], v208 offset:37888
	ds_read_b128 v[234:237], v208 offset:38912
	ds_read_b128 v[238:241], v208 offset:39936
	global_load_lds_dwordx4 v140, s[40:41]
	s_mov_b32 m0, s50
	s_nop 0
	global_load_lds_dwordx4 v144, s[40:41]
	s_waitcnt vmcnt(8)
	s_waitcnt lgkmcnt(0)
	s_barrier
	s_setprio 1
	s_waitcnt lgkmcnt(0)
	v_mfma_f32_16x16x32_bf16 v[124:127], v[128:131], v[210:213], v[124:127]
	v_mfma_f32_16x16x32_bf16 v[120:123], v[136:139], v[210:213], v[120:123]
	v_mfma_f32_16x16x32_bf16 v[112:115], v[128:131], v[218:221], v[112:115]
	v_mfma_f32_16x16x32_bf16 v[104:107], v[136:139], v[218:221], v[104:107]
	v_mfma_f32_16x16x32_bf16 v[96:99], v[128:131], v[226:229], v[96:99]
	v_mfma_f32_16x16x32_bf16 v[88:91], v[136:139], v[226:229], v[88:91]
	v_mfma_f32_16x16x32_bf16 v[80:83], v[128:131], v[234:237], v[80:83]
	v_mfma_f32_16x16x32_bf16 v[72:75], v[136:139], v[234:237], v[72:75]
	v_mfma_f32_16x16x32_bf16 v[124:127], v[132:135], v[214:217], v[124:127]
	v_mfma_f32_16x16x32_bf16 v[120:123], v[156:159], v[214:217], v[120:123]
	v_mfma_f32_16x16x32_bf16 v[112:115], v[132:135], v[222:225], v[112:115]
	v_mfma_f32_16x16x32_bf16 v[104:107], v[156:159], v[222:225], v[104:107]
	v_mfma_f32_16x16x32_bf16 v[96:99], v[132:135], v[230:233], v[96:99]
	v_mfma_f32_16x16x32_bf16 v[88:91], v[156:159], v[230:233], v[88:91]
	v_mfma_f32_16x16x32_bf16 v[80:83], v[132:135], v[238:241], v[80:83]
	v_mfma_f32_16x16x32_bf16 v[72:75], v[156:159], v[238:241], v[72:75]
	s_setprio 0
	s_setprio 1
	v_mfma_f32_16x16x32_bf16 v[116:119], v[160:163], v[210:213], v[116:119]
	v_mfma_f32_16x16x32_bf16 v[108:111], v[168:171], v[210:213], v[108:111]
	v_mfma_f32_16x16x32_bf16 v[100:103], v[160:163], v[218:221], v[100:103]
	v_mfma_f32_16x16x32_bf16 v[92:95], v[168:171], v[218:221], v[92:95]
	v_mfma_f32_16x16x32_bf16 v[84:87], v[160:163], v[226:229], v[84:87]
	v_mfma_f32_16x16x32_bf16 v[76:79], v[168:171], v[226:229], v[76:79]
	v_mfma_f32_16x16x32_bf16 v[68:71], v[160:163], v[234:237], v[68:71]
	v_mfma_f32_16x16x32_bf16 v[64:67], v[168:171], v[234:237], v[64:67]
	v_mfma_f32_16x16x32_bf16 v[116:119], v[164:167], v[214:217], v[116:119]
	v_mfma_f32_16x16x32_bf16 v[108:111], v[172:175], v[214:217], v[108:111]
	v_mfma_f32_16x16x32_bf16 v[100:103], v[164:167], v[222:225], v[100:103]
	v_mfma_f32_16x16x32_bf16 v[92:95], v[172:175], v[222:225], v[92:95]
	v_mfma_f32_16x16x32_bf16 v[84:87], v[164:167], v[230:233], v[84:87]
	v_mfma_f32_16x16x32_bf16 v[76:79], v[172:175], v[230:233], v[76:79]
	v_mfma_f32_16x16x32_bf16 v[68:71], v[164:167], v[238:241], v[68:71]
	v_mfma_f32_16x16x32_bf16 v[64:67], v[172:175], v[238:241], v[64:67]
	s_setprio 0
	s_barrier
	s_add_i32 s40, s62, s46
	s_mov_b32 m0, s40
	ds_read_b128 v[210:213], v208 offset:49152
	ds_read_b128 v[214:217], v208 offset:50176
	ds_read_b128 v[218:221], v208 offset:51200
	ds_read_b128 v[222:225], v208 offset:52224
	ds_read_b128 v[226:229], v208 offset:53248
	ds_read_b128 v[230:233], v208 offset:54272
	ds_read_b128 v[234:237], v208 offset:55296
	ds_read_b128 v[238:241], v208 offset:56320
	global_load_lds_dwordx4 v142, s[98:99]
	s_add_i32 m0, s40, 0x2000
	s_add_u32 s38, s38, 0x40080
	s_addc_u32 s39, s39, 0
	s_add_i32 s40, s63, s46
	global_load_lds_dwordx4 v146, s[98:99]
	s_mov_b32 m0, s40
	s_nop 0
	global_load_lds_dwordx4 v142, s[38:39]
	s_add_i32 m0, s40, 0x2000
	s_nop 0
	global_load_lds_dwordx4 v146, s[38:39]
	s_mov_b32 m0, s52
	s_nop 0
	global_load_lds_dwordx4 v140, s[100:101]
	s_mov_b32 m0, s53
	s_nop 0
	global_load_lds_dwordx4 v144, s[100:101]
	s_waitcnt vmcnt(8)
	s_waitcnt lgkmcnt(0)
	s_barrier
	s_setprio 1
	s_waitcnt lgkmcnt(0)
	v_mfma_f32_16x16x32_bf16 v[60:63], v[128:131], v[210:213], v[60:63]
	v_mfma_f32_16x16x32_bf16 v[56:59], v[136:139], v[210:213], v[56:59]
	v_mfma_f32_16x16x32_bf16 v[48:51], v[128:131], v[218:221], v[48:51]
	v_mfma_f32_16x16x32_bf16 v[40:43], v[136:139], v[218:221], v[40:43]
	v_mfma_f32_16x16x32_bf16 v[32:35], v[128:131], v[226:229], v[32:35]
	v_mfma_f32_16x16x32_bf16 v[24:27], v[136:139], v[226:229], v[24:27]
	v_mfma_f32_16x16x32_bf16 v[16:19], v[128:131], v[234:237], v[16:19]
	v_mfma_f32_16x16x32_bf16 v[8:11], v[136:139], v[234:237], v[8:11]
	v_mfma_f32_16x16x32_bf16 v[60:63], v[132:135], v[214:217], v[60:63]
	v_mfma_f32_16x16x32_bf16 v[56:59], v[156:159], v[214:217], v[56:59]
	v_mfma_f32_16x16x32_bf16 v[48:51], v[132:135], v[222:225], v[48:51]
	v_mfma_f32_16x16x32_bf16 v[40:43], v[156:159], v[222:225], v[40:43]
	v_mfma_f32_16x16x32_bf16 v[32:35], v[132:135], v[230:233], v[32:35]
	v_mfma_f32_16x16x32_bf16 v[24:27], v[156:159], v[230:233], v[24:27]
	v_mfma_f32_16x16x32_bf16 v[16:19], v[132:135], v[238:241], v[16:19]
	v_mfma_f32_16x16x32_bf16 v[8:11], v[156:159], v[238:241], v[8:11]
	s_setprio 0
	s_setprio 1
	v_mfma_f32_16x16x32_bf16 v[52:55], v[160:163], v[210:213], v[52:55]
	v_mfma_f32_16x16x32_bf16 v[44:47], v[168:171], v[210:213], v[44:47]
	v_mfma_f32_16x16x32_bf16 v[36:39], v[160:163], v[218:221], v[36:39]
	v_mfma_f32_16x16x32_bf16 v[28:31], v[168:171], v[218:221], v[28:31]
	v_mfma_f32_16x16x32_bf16 v[20:23], v[160:163], v[226:229], v[20:23]
	v_mfma_f32_16x16x32_bf16 v[12:15], v[168:171], v[226:229], v[12:15]
	v_mfma_f32_16x16x32_bf16 v[4:7], v[160:163], v[234:237], v[4:7]
	v_mfma_f32_16x16x32_bf16 v[0:3], v[168:171], v[234:237], v[0:3]
	v_mfma_f32_16x16x32_bf16 v[52:55], v[164:167], v[214:217], v[52:55]
	v_mfma_f32_16x16x32_bf16 v[44:47], v[172:175], v[214:217], v[44:47]
	v_mfma_f32_16x16x32_bf16 v[36:39], v[164:167], v[222:225], v[36:39]
	v_mfma_f32_16x16x32_bf16 v[28:31], v[172:175], v[222:225], v[28:31]
	v_mfma_f32_16x16x32_bf16 v[20:23], v[164:167], v[230:233], v[20:23]
	v_mfma_f32_16x16x32_bf16 v[12:15], v[172:175], v[230:233], v[12:15]
	v_mfma_f32_16x16x32_bf16 v[4:7], v[164:167], v[238:241], v[4:7]
	v_mfma_f32_16x16x32_bf16 v[0:3], v[172:175], v[238:241], v[0:3]
	s_setprio 0
	s_barrier
	s_add_i32 s61, s61, 2
	s_add_u32 s36, s36, 0x100
	s_addc_u32 s37, s37, 0
	s_add_u32 s59, s59, 0x100
	s_addc_u32 s60, s60, 0
	s_cmp_gt_u32 s61, 13
	s_cbranch_scc0 .LBB0_757
	s_and_b64 vcc, exec, s[20:21]
	s_cbranch_vccz .LBB0_760
	s_barrier

; #define PG8_STAGE(bufoff, gbase, voff) do { _Pragma("unroll") for (int _i = 0; _i < 2; ++_i) \
;         __builtin_amdgcn_global_load_lds((const unsigned*)((const char*)(gbase) + (voff)[_i]), (PG8_LAS unsigned*)(lds + (bufoff) + ldsw + _i * 8192), 16, 0, 0); } while (0)
; #define PG8_LDA(dst, b, h) do { _Pragma("unroll") for (int m = 0; m < 4; ++m) _Pragma("unroll") for (int k = 0; k < 2; ++k) dst[m][k] = *(const PG8_LAS bf16x8*)(lds + PG8_SA(b, h) + aoff + m * 2048 + k * 1024); } while (0)
; #define PG8_LDB(dst, b, h) do { _Pragma("unroll") for (int n = 0; n < 2; ++n) _Pragma("unroll") for (int k = 0; k < 2; ++k) dst[n][k] = *(const PG8_LAS bf16x8*)(lds + PG8_SB(b, h) + boff + n * 2048 + k * 1024); } while (0)
; #define PG8_MMA(ai, bj, At, Bt) do { __builtin_amdgcn_s_setprio(1); _Pragma("unroll") for (int m = 0; m < 4; ++m) _Pragma("unroll") for (int n = 0; n < 2; ++n) _Pragma("unroll") for (int k = 0; k < 2; ++k) \
;         acc[ai][bj][m][n] = __builtin_amdgcn_mfma_f32_16x16x32_bf16(Bt[n][k], At[m][k], acc[ai][bj][m][n], 0, 0, 0); __builtin_amdgcn_s_setprio(0); } while (0)
; #define PG8_WAIT_V(n) asm volatile("s_waitcnt vmcnt(" #n ")" ::: "memory")
; #define PG8_WAIT_L(n) asm volatile("s_waitcnt lgkmcnt(" #n ")" ::: "memory")
; template <class Epi, class Sched, bool ALIGN_EPI = false, bool SP2 = false>
; __device__ __forceinline__ void gemm_phase(PG8_LAS unsigned char* lds, const Gemm g, const Sched S, const Epi E, const int tid) {
;     ...
;             const bool last = (t == nt - 2);
;             const char* a1 = cA + (size_t)(t + 1) * kstep;
;             const char* a2 = last ? nA : cA + (size_t)(t + 2) * kstep; const char* b2 = last ? nB : cB + (size_t)(t + 2) * kstep;
;             const char* a3 = a2 + kstep; const char* b3 = b2 + kstep;
;             if (last && has_next) S.a_ready(nxt);
;             if constexpr (SP2) {
;             PG8_LDB(B0, 0, 0); PG8_LDB(B1, 0, 1); PG8_SCHED; PG8_LDA(At, 0, 0); PG8_STAGE(PG8_SA(1, 1), a1 + hstepA, voffA);
;             PG8_WAIT_V(8); PG8_WAIT_L(0); PG8_BAR; PG8_MMA(0, 0, At, B0); PG8_MMA(0, 1, At, B1); PG8_BAR; PG8_SCHED;
;             PG8_LDA(At, 0, 1); PG8_STAGE(PG8_SB(0, 0), b2, voffB); PG8_STAGE(PG8_SB(0, 1), b2 + hstepB, voffB); PG8_STAGE(PG8_SA(0, 0), a2, voffA);
;             PG8_WAIT_V(8); PG8_WAIT_L(0); PG8_BAR; PG8_MMA(1, 0, At, B0); PG8_MMA(1, 1, At, B1); PG8_BAR; PG8_SCHED;
.LBB0_886:
	v_add_u32_e32 v162, s66, v149
	v_add_u32_e32 v178, s67, v149
	ds_read_b128 v[136:139], v162
	ds_read_b128 v[154:157], v162 offset:1024
	ds_read_b128 v[158:161], v162 offset:2048
	ds_read_b128 v[162:165], v162 offset:3072
	ds_read_b128 v[166:169], v178
	ds_read_b128 v[170:173], v178 offset:1024
	ds_read_b128 v[174:177], v178 offset:2048
	ds_read_b128 v[178:181], v178 offset:3072
	s_add_u32 s46, s48, 0xfffc0080
	s_addc_u32 s47, s49, -1
	s_cmp_eq_u32 s75, 12
	s_cselect_b32 s51, s31, s47
	s_cselect_b32 s50, s39, s46
	s_cselect_b32 s47, s29, s74
	s_cselect_b32 s46, s41, s69
	s_add_i32 m0, s56, 0xc000
	ds_read_b128 v[182:185], v153
	ds_read_b128 v[188:191], v153 offset:1024
	ds_read_b128 v[192:195], v153 offset:2048
	ds_read_b128 v[196:199], v153 offset:3072
	ds_read_b128 v[200:203], v153 offset:4096
	ds_read_b128 v[204:207], v153 offset:5120
	ds_read_b128 v[208:211], v153 offset:6144
	ds_read_b128 v[212:215], v153 offset:7168
	global_load_lds_dwordx4 v128, s[48:49]
	s_add_i32 m0, s56, 0xe000
	s_nop 0
	global_load_lds_dwordx4 v130, s[48:49]
	s_waitcnt vmcnt(8)
	s_waitcnt lgkmcnt(0)
	s_barrier
	s_setprio 1
	s_waitcnt lgkmcnt(0)
	v_mfma_f32_16x16x32_bf16 v[112:115], v[136:139], v[182:185], v[112:115]
	v_mfma_f32_16x16x32_bf16 v[120:123], v[158:161], v[182:185], v[120:123]
	v_mfma_f32_16x16x32_bf16 v[96:99], v[136:139], v[192:195], v[96:99]
	v_mfma_f32_16x16x32_bf16 v[104:107], v[158:161], v[192:195], v[104:107]
	v_mfma_f32_16x16x32_bf16 v[80:83], v[136:139], v[200:203], v[80:83]
	v_mfma_f32_16x16x32_bf16 v[88:91], v[158:161], v[200:203], v[88:91]
	v_mfma_f32_16x16x32_bf16 v[64:67], v[136:139], v[208:211], v[64:67]
	v_mfma_f32_16x16x32_bf16 v[72:75], v[158:161], v[208:211], v[72:75]
	v_mfma_f32_16x16x32_bf16 v[112:115], v[154:157], v[188:191], v[112:115]
	v_mfma_f32_16x16x32_bf16 v[120:123], v[162:165], v[188:191], v[120:123]
	v_mfma_f32_16x16x32_bf16 v[96:99], v[154:157], v[196:199], v[96:99]
	v_mfma_f32_16x16x32_bf16 v[104:107], v[162:165], v[196:199], v[104:107]
	v_mfma_f32_16x16x32_bf16 v[80:83], v[154:157], v[204:207], v[80:83]
	v_mfma_f32_16x16x32_bf16 v[88:91], v[162:165], v[204:207], v[88:91]
	v_mfma_f32_16x16x32_bf16 v[64:67], v[154:157], v[212:215], v[64:67]
	v_mfma_f32_16x16x32_bf16 v[72:75], v[162:165], v[212:215], v[72:75]
	s_setprio 0
	s_setprio 1
	v_mfma_f32_16x16x32_bf16 v[116:119], v[166:169], v[182:185], v[116:119]
	v_mfma_f32_16x16x32_bf16 v[124:127], v[174:177], v[182:185], v[124:127]
	v_mfma_f32_16x16x32_bf16 v[100:103], v[166:169], v[192:195], v[100:103]
	v_mfma_f32_16x16x32_bf16 v[108:111], v[174:177], v[192:195], v[108:111]
	v_mfma_f32_16x16x32_bf16 v[84:87], v[166:169], v[200:203], v[84:87]
	v_mfma_f32_16x16x32_bf16 v[92:95], v[174:177], v[200:203], v[92:95]
	v_mfma_f32_16x16x32_bf16 v[68:71], v[166:169], v[208:211], v[68:71]
	v_mfma_f32_16x16x32_bf16 v[76:79], v[174:177], v[208:211], v[76:79]
	v_mfma_f32_16x16x32_bf16 v[116:119], v[170:173], v[188:191], v[116:119]
	v_mfma_f32_16x16x32_bf16 v[124:127], v[178:181], v[188:191], v[124:127]
	v_mfma_f32_16x16x32_bf16 v[100:103], v[170:173], v[196:199], v[100:103]
	v_mfma_f32_16x16x32_bf16 v[108:111], v[178:181], v[196:199], v[108:111]
	v_mfma_f32_16x16x32_bf16 v[84:87], v[170:173], v[204:207], v[84:87]
	v_mfma_f32_16x16x32_bf16 v[92:95], v[178:181], v[204:207], v[92:95]
	v_mfma_f32_16x16x32_bf16 v[68:71], v[170:173], v[212:215], v[68:71]
	v_mfma_f32_16x16x32_bf16 v[76:79], v[178:181], v[212:215], v[76:79]
	s_setprio 0
	s_barrier
	s_add_u32 s98, s46, 0x80
	s_addc_u32 s99, s47, 0
	s_add_u32 s100, s50, 0x80
	s_addc_u32 s101, s51, 0
	s_add_i32 s70, s66, s53
	s_mov_b32 m0, s70
	ds_read_b128 v[182:185], v153 offset:16384
	ds_read_b128 v[188:191], v153 offset:17408
	ds_read_b128 v[192:195], v153 offset:18432
	ds_read_b128 v[196:199], v153 offset:19456
	ds_read_b128 v[200:203], v153 offset:20480
	ds_read_b128 v[204:207], v153 offset:21504
	ds_read_b128 v[208:211], v153 offset:22528
	ds_read_b128 v[212:215], v153 offset:23552
	global_load_lds_dwordx4 v142, s[46:47]
	s_add_i32 m0, s70, 0x2000
	s_add_u32 s76, s46, 0x40000
	s_addc_u32 s77, s47, 0
	s_add_i32 s70, s67, s53
	global_load_lds_dwordx4 v146, s[46:47]
	s_mov_b32 m0, s70
	s_nop 0
	global_load_lds_dwordx4 v142, s[76:77]
	s_add_i32 m0, s70, 0x2000
	s_nop 0
	global_load_lds_dwordx4 v146, s[76:77]
	s_mov_b32 m0, s56
	s_nop 0
	global_load_lds_dwordx4 v140, s[50:51]
	s_mov_b32 m0, s57
	s_nop 0
	global_load_lds_dwordx4 v144, s[50:51]
	s_waitcnt vmcnt(8)
	s_waitcnt lgkmcnt(0)
	s_barrier
	s_setprio 1
	s_waitcnt lgkmcnt(0)
	v_mfma_f32_16x16x32_bf16 v[48:51], v[136:139], v[182:185], v[48:51]
	v_mfma_f32_16x16x32_bf16 v[56:59], v[158:161], v[182:185], v[56:59]
	v_mfma_f32_16x16x32_bf16 v[16:19], v[136:139], v[192:195], v[16:19]
	v_mfma_f32_16x16x32_bf16 v[24:27], v[158:161], v[192:195], v[24:27]
	v_mfma_f32_16x16x32_bf16 v[32:35], v[136:139], v[200:203], v[32:35]
	v_mfma_f32_16x16x32_bf16 v[40:43], v[158:161], v[200:203], v[40:43]
	v_mfma_f32_16x16x32_bf16 v[0:3], v[136:139], v[208:211], v[0:3]
	v_mfma_f32_16x16x32_bf16 v[8:11], v[158:161], v[208:211], v[8:11]
	v_mfma_f32_16x16x32_bf16 v[48:51], v[154:157], v[188:191], v[48:51]
	v_mfma_f32_16x16x32_bf16 v[56:59], v[162:165], v[188:191], v[56:59]
	v_mfma_f32_16x16x32_bf16 v[16:19], v[154:157], v[196:199], v[16:19]
	v_mfma_f32_16x16x32_bf16 v[24:27], v[162:165], v[196:199], v[24:27]
	v_mfma_f32_16x16x32_bf16 v[32:35], v[154:157], v[204:207], v[32:35]
	v_mfma_f32_16x16x32_bf16 v[40:43], v[162:165], v[204:207], v[40:43]
	v_mfma_f32_16x16x32_bf16 v[0:3], v[154:157], v[212:215], v[0:3]
	v_mfma_f32_16x16x32_bf16 v[8:11], v[162:165], v[212:215], v[8:11]
	s_setprio 0
	s_setprio 1
	v_mfma_f32_16x16x32_bf16 v[52:55], v[166:169], v[182:185], v[52:55]
	v_mfma_f32_16x16x32_bf16 v[60:63], v[174:177], v[182:185], v[60:63]
	v_mfma_f32_16x16x32_bf16 v[20:23], v[166:169], v[192:195], v[20:23]
	v_mfma_f32_16x16x32_bf16 v[28:31], v[174:177], v[192:195], v[28:31]
	v_mfma_f32_16x16x32_bf16 v[36:39], v[166:169], v[200:203], v[36:39]
	v_mfma_f32_16x16x32_bf16 v[44:47], v[174:177], v[200:203], v[44:47]
	v_mfma_f32_16x16x32_bf16 v[4:7], v[166:169], v[208:211], v[4:7]
	v_mfma_f32_16x16x32_bf16 v[12:15], v[174:177], v[208:211], v[12:15]
	v_mfma_f32_16x16x32_bf16 v[52:55], v[170:173], v[188:191], v[52:55]
	v_mfma_f32_16x16x32_bf16 v[60:63], v[178:181], v[188:191], v[60:63]
	v_mfma_f32_16x16x32_bf16 v[20:23], v[170:173], v[196:199], v[20:23]
	v_mfma_f32_16x16x32_bf16 v[28:31], v[178:181], v[196:199], v[28:31]
	v_mfma_f32_16x16x32_bf16 v[36:39], v[170:173], v[204:207], v[36:39]
	v_mfma_f32_16x16x32_bf16 v[44:47], v[178:181], v[204:207], v[44:47]
	v_mfma_f32_16x16x32_bf16 v[4:7], v[170:173], v[212:215], v[4:7]
	v_mfma_f32_16x16x32_bf16 v[12:15], v[178:181], v[212:215], v[12:15]
	s_setprio 0
	s_barrier
; #define PG8_STAGE(bufoff, gbase, voff) do { _Pragma("unroll") for (int _i = 0; _i < 2; ++_i) \
;         __builtin_amdgcn_global_load_lds((const unsigned*)((const char*)(gbase) + (voff)[_i]), (PG8_LAS unsigned*)(lds + (bufoff) + ldsw + _i * 8192), 16, 0, 0); } while (0)
; #define PG8_LDA(dst, b, h) do { _Pragma("unroll") for (int m = 0; m < 4; ++m) _Pragma("unroll") for (int k = 0; k < 2; ++k) dst[m][k] = *(const PG8_LAS bf16x8*)(lds + PG8_SA(b, h) + aoff + m * 2048 + k * 1024); } while (0)
; #define PG8_LDB(dst, b, h) do { _Pragma("unroll") for (int n = 0; n < 2; ++n) _Pragma("unroll") for (int k = 0; k < 2; ++k) dst[n][k] = *(const PG8_LAS bf16x8*)(lds + PG8_SB(b, h) + boff + n * 2048 + k * 1024); } while (0)
; #define PG8_MMA(ai, bj, At, Bt) do { __builtin_amdgcn_s_setprio(1); _Pragma("unroll") for (int m = 0; m < 4; ++m) _Pragma("unroll") for (int n = 0; n < 2; ++n) _Pragma("unroll") for (int k = 0; k < 2; ++k) \
;         acc[ai][bj][m][n] = __builtin_amdgcn_mfma_f32_16x16x32_bf16(Bt[n][k], At[m][k], acc[ai][bj][m][n], 0, 0, 0); __builtin_amdgcn_s_setprio(0); } while (0)
; #define PG8_WAIT_V(n) asm volatile("s_waitcnt vmcnt(" #n ")" ::: "memory")
; #define PG8_WAIT_L(n) asm volatile("s_waitcnt lgkmcnt(" #n ")" ::: "memory")
; #define PG8_BAR __builtin_amdgcn_s_barrier()
; #define PG8_SCHED __builtin_amdgcn_sched_barrier(0)
; template <class Epi, class Sched, bool ALIGN_EPI = false, bool SP2 = false>
; __device__ __forceinline__ void gemm_phase(PG8_LAS unsigned char* lds, const Gemm g, const Sched S, const Epi E, const int tid) {
;     ...
;             PG8_LDB(B0, 1, 0); PG8_LDB(B1, 1, 1); PG8_SCHED; PG8_LDA(At, 1, 0); PG8_STAGE(PG8_SA(0, 1), a2 + hstepA, voffA);
;             PG8_WAIT_V(8); PG8_WAIT_L(0); PG8_BAR; PG8_MMA(0, 0, At, B0); PG8_MMA(0, 1, At, B1); PG8_BAR; PG8_SCHED;
;             PG8_LDA(At, 1, 1); PG8_STAGE(PG8_SB(1, 0), b3, voffB); PG8_STAGE(PG8_SB(1, 1), b3 + hstepB, voffB); PG8_STAGE(PG8_SA(1, 0), a3, voffA);
;             PG8_WAIT_V(8); PG8_WAIT_L(0); PG8_BAR; PG8_MMA(1, 0, At, B0); PG8_MMA(1, 1, At, B1); PG8_BAR; PG8_SCHED;
	s_add_i32 s70, 0, 0x18000
	s_add_i32 s76, 0, 0x1c000
	v_add_u32_e32 v162, s70, v149
	v_add_u32_e32 v178, s76, v149
	ds_read_b128 v[136:139], v162
	ds_read_b128 v[154:157], v162 offset:1024
	ds_read_b128 v[158:161], v162 offset:2048
	ds_read_b128 v[162:165], v162 offset:3072
	ds_read_b128 v[166:169], v178
	ds_read_b128 v[170:173], v178 offset:1024
	ds_read_b128 v[174:177], v178 offset:2048
	ds_read_b128 v[178:181], v178 offset:3072
	s_add_u32 s50, s50, 0x40000
	s_addc_u32 s51, s51, 0
	s_mov_b32 m0, s58
	ds_read_b128 v[182:185], v153 offset:32768
	ds_read_b128 v[188:191], v153 offset:33792
	ds_read_b128 v[192:195], v153 offset:34816
	ds_read_b128 v[196:199], v153 offset:35840
	ds_read_b128 v[200:203], v153 offset:36864
	ds_read_b128 v[204:207], v153 offset:37888
	ds_read_b128 v[208:211], v153 offset:38912
	ds_read_b128 v[212:215], v153 offset:39936
	global_load_lds_dwordx4 v140, s[50:51]
	s_mov_b32 m0, s59
	s_nop 0
	global_load_lds_dwordx4 v144, s[50:51]
	s_waitcnt vmcnt(8)
	s_waitcnt lgkmcnt(0)
	s_barrier
	s_setprio 1
	s_waitcnt lgkmcnt(0)
	v_mfma_f32_16x16x32_bf16 v[112:115], v[136:139], v[182:185], v[112:115]
	v_mfma_f32_16x16x32_bf16 v[120:123], v[158:161], v[182:185], v[120:123]
	v_mfma_f32_16x16x32_bf16 v[96:99], v[136:139], v[192:195], v[96:99]
	v_mfma_f32_16x16x32_bf16 v[104:107], v[158:161], v[192:195], v[104:107]
	v_mfma_f32_16x16x32_bf16 v[80:83], v[136:139], v[200:203], v[80:83]
	v_mfma_f32_16x16x32_bf16 v[88:91], v[158:161], v[200:203], v[88:91]
	v_mfma_f32_16x16x32_bf16 v[64:67], v[136:139], v[208:211], v[64:67]
	v_mfma_f32_16x16x32_bf16 v[72:75], v[158:161], v[208:211], v[72:75]
	v_mfma_f32_16x16x32_bf16 v[112:115], v[154:157], v[188:191], v[112:115]
	v_mfma_f32_16x16x32_bf16 v[120:123], v[162:165], v[188:191], v[120:123]
	v_mfma_f32_16x16x32_bf16 v[96:99], v[154:157], v[196:199], v[96:99]
	v_mfma_f32_16x16x32_bf16 v[104:107], v[162:165], v[196:199], v[104:107]
	v_mfma_f32_16x16x32_bf16 v[80:83], v[154:157], v[204:207], v[80:83]
	v_mfma_f32_16x16x32_bf16 v[88:91], v[162:165], v[204:207], v[88:91]
	v_mfma_f32_16x16x32_bf16 v[64:67], v[154:157], v[212:215], v[64:67]
	v_mfma_f32_16x16x32_bf16 v[72:75], v[162:165], v[212:215], v[72:75]
	s_setprio 0
	s_setprio 1
	v_mfma_f32_16x16x32_bf16 v[116:119], v[166:169], v[182:185], v[116:119]
	v_mfma_f32_16x16x32_bf16 v[124:127], v[174:177], v[182:185], v[124:127]
	v_mfma_f32_16x16x32_bf16 v[100:103], v[166:169], v[192:195], v[100:103]
	v_mfma_f32_16x16x32_bf16 v[108:111], v[174:177], v[192:195], v[108:111]
	v_mfma_f32_16x16x32_bf16 v[84:87], v[166:169], v[200:203], v[84:87]
	v_mfma_f32_16x16x32_bf16 v[92:95], v[174:177], v[200:203], v[92:95]
	v_mfma_f32_16x16x32_bf16 v[68:71], v[166:169], v[208:211], v[68:71]
	v_mfma_f32_16x16x32_bf16 v[76:79], v[174:177], v[208:211], v[76:79]
	v_mfma_f32_16x16x32_bf16 v[116:119], v[170:173], v[188:191], v[116:119]
	v_mfma_f32_16x16x32_bf16 v[124:127], v[178:181], v[188:191], v[124:127]
	v_mfma_f32_16x16x32_bf16 v[100:103], v[170:173], v[196:199], v[100:103]
	v_mfma_f32_16x16x32_bf16 v[108:111], v[178:181], v[196:199], v[108:111]
	v_mfma_f32_16x16x32_bf16 v[84:87], v[170:173], v[204:207], v[84:87]
	v_mfma_f32_16x16x32_bf16 v[92:95], v[178:181], v[204:207], v[92:95]
	v_mfma_f32_16x16x32_bf16 v[68:71], v[170:173], v[212:215], v[68:71]
	v_mfma_f32_16x16x32_bf16 v[76:79], v[178:181], v[212:215], v[76:79]
	s_setprio 0
	s_barrier
	s_add_i32 s50, s70, s53
	s_mov_b32 m0, s50
	ds_read_b128 v[182:185], v153 offset:49152
	ds_read_b128 v[188:191], v153 offset:50176
	ds_read_b128 v[192:195], v153 offset:51200
	ds_read_b128 v[196:199], v153 offset:52224
	ds_read_b128 v[200:203], v153 offset:53248
	ds_read_b128 v[204:207], v153 offset:54272
	ds_read_b128 v[208:211], v153 offset:55296
	ds_read_b128 v[212:215], v153 offset:56320
	global_load_lds_dwordx4 v142, s[98:99]
	s_add_i32 m0, s50, 0x2000
	s_add_u32 s46, s46, 0x40080
	s_addc_u32 s47, s47, 0
	s_add_i32 s50, s76, s53
	global_load_lds_dwordx4 v146, s[98:99]
	s_mov_b32 m0, s50
	s_nop 0
	global_load_lds_dwordx4 v142, s[46:47]
	s_add_i32 m0, s50, 0x2000
	s_nop 0
	global_load_lds_dwordx4 v146, s[46:47]
	s_mov_b32 m0, s61
	s_nop 0
	global_load_lds_dwordx4 v140, s[100:101]
	s_mov_b32 m0, s62
	s_nop 0
	global_load_lds_dwordx4 v144, s[100:101]
	s_waitcnt vmcnt(8)
	s_waitcnt lgkmcnt(0)
	s_barrier
	s_setprio 1
	s_waitcnt lgkmcnt(0)
	v_mfma_f32_16x16x32_bf16 v[48:51], v[136:139], v[182:185], v[48:51]
	v_mfma_f32_16x16x32_bf16 v[56:59], v[158:161], v[182:185], v[56:59]
	v_mfma_f32_16x16x32_bf16 v[16:19], v[136:139], v[192:195], v[16:19]
	v_mfma_f32_16x16x32_bf16 v[24:27], v[158:161], v[192:195], v[24:27]
	v_mfma_f32_16x16x32_bf16 v[32:35], v[136:139], v[200:203], v[32:35]
	v_mfma_f32_16x16x32_bf16 v[40:43], v[158:161], v[200:203], v[40:43]
	v_mfma_f32_16x16x32_bf16 v[0:3], v[136:139], v[208:211], v[0:3]
	v_mfma_f32_16x16x32_bf16 v[8:11], v[158:161], v[208:211], v[8:11]
	v_mfma_f32_16x16x32_bf16 v[48:51], v[154:157], v[188:191], v[48:51]
	v_mfma_f32_16x16x32_bf16 v[56:59], v[162:165], v[188:191], v[56:59]
	v_mfma_f32_16x16x32_bf16 v[16:19], v[154:157], v[196:199], v[16:19]
	v_mfma_f32_16x16x32_bf16 v[24:27], v[162:165], v[196:199], v[24:27]
	v_mfma_f32_16x16x32_bf16 v[32:35], v[154:157], v[204:207], v[32:35]
	v_mfma_f32_16x16x32_bf16 v[40:43], v[162:165], v[204:207], v[40:43]
	v_mfma_f32_16x16x32_bf16 v[0:3], v[154:157], v[212:215], v[0:3]
	v_mfma_f32_16x16x32_bf16 v[8:11], v[162:165], v[212:215], v[8:11]
	s_setprio 0
	s_setprio 1
	v_mfma_f32_16x16x32_bf16 v[52:55], v[166:169], v[182:185], v[52:55]
	v_mfma_f32_16x16x32_bf16 v[60:63], v[174:177], v[182:185], v[60:63]
	v_mfma_f32_16x16x32_bf16 v[20:23], v[166:169], v[192:195], v[20:23]
	v_mfma_f32_16x16x32_bf16 v[28:31], v[174:177], v[192:195], v[28:31]
	v_mfma_f32_16x16x32_bf16 v[36:39], v[166:169], v[200:203], v[36:39]
	v_mfma_f32_16x16x32_bf16 v[44:47], v[174:177], v[200:203], v[44:47]
	v_mfma_f32_16x16x32_bf16 v[4:7], v[166:169], v[208:211], v[4:7]
	v_mfma_f32_16x16x32_bf16 v[12:15], v[174:177], v[208:211], v[12:15]
	v_mfma_f32_16x16x32_bf16 v[52:55], v[170:173], v[188:191], v[52:55]
	v_mfma_f32_16x16x32_bf16 v[60:63], v[178:181], v[188:191], v[60:63]
	v_mfma_f32_16x16x32_bf16 v[20:23], v[170:173], v[196:199], v[20:23]
	v_mfma_f32_16x16x32_bf16 v[28:31], v[178:181], v[196:199], v[28:31]
	v_mfma_f32_16x16x32_bf16 v[36:39], v[170:173], v[204:207], v[36:39]
	v_mfma_f32_16x16x32_bf16 v[44:47], v[178:181], v[204:207], v[44:47]
	v_mfma_f32_16x16x32_bf16 v[4:7], v[170:173], v[212:215], v[4:7]
	v_mfma_f32_16x16x32_bf16 v[12:15], v[178:181], v[212:215], v[12:15]
	s_setprio 0
	s_barrier
	s_add_i32 s75, s75, 2
	s_add_u32 s48, s48, 0x100
	s_addc_u32 s49, s49, 0
	s_add_u32 s69, s69, 0x100
	s_addc_u32 s74, s74, 0
	s_cmp_gt_u32 s75, 13
	s_cbranch_scc0 .LBB0_886
	s_and_b64 vcc, exec, s[26:27]
	s_cbranch_vccz .LBB0_889
	s_barrier

; #define PG8_STAGE(bufoff, gbase, voff) do { _Pragma("unroll") for (int _i = 0; _i < 2; ++_i) \
;         __builtin_amdgcn_global_load_lds((const unsigned*)((const char*)(gbase) + (voff)[_i]), (PG8_LAS unsigned*)(lds + (bufoff) + ldsw + _i * 8192), 16, 0, 0); } while (0)
; #define PG8_LDA(dst, b, h) do { _Pragma("unroll") for (int m = 0; m < 4; ++m) _Pragma("unroll") for (int k = 0; k < 2; ++k) dst[m][k] = *(const PG8_LAS bf16x8*)(lds + PG8_SA(b, h) + aoff + m * 2048 + k * 1024); } while (0)
; #define PG8_LDB(dst, b, h) do { _Pragma("unroll") for (int n = 0; n < 2; ++n) _Pragma("unroll") for (int k = 0; k < 2; ++k) dst[n][k] = *(const PG8_LAS bf16x8*)(lds + PG8_SB(b, h) + boff + n * 2048 + k * 1024); } while (0)
; #define PG8_MMA(ai, bj, At, Bt) do { __builtin_amdgcn_s_setprio(1); _Pragma("unroll") for (int m = 0; m < 4; ++m) _Pragma("unroll") for (int n = 0; n < 2; ++n) _Pragma("unroll") for (int k = 0; k < 2; ++k) \
;         acc[ai][bj][m][n] = __builtin_amdgcn_mfma_f32_16x16x32_bf16(Bt[n][k], At[m][k], acc[ai][bj][m][n], 0, 0, 0); __builtin_amdgcn_s_setprio(0); } while (0)
; #define PG8_WAIT_V(n) asm volatile("s_waitcnt vmcnt(" #n ")" ::: "memory")
; #define PG8_WAIT_L(n) asm volatile("s_waitcnt lgkmcnt(" #n ")" ::: "memory")
; template <class Epi, class Sched, bool ALIGN_EPI = false, bool SP2 = false>
; __device__ __forceinline__ void gemm_phase(PG8_LAS unsigned char* lds, const Gemm g, const Sched S, const Epi E, const int tid) {
;     ...
;             const bool last = (t == nt - 2);
;             const char* a1 = cA + (size_t)(t + 1) * kstep;
;             const char* a2 = last ? nA : cA + (size_t)(t + 2) * kstep; const char* b2 = last ? nB : cB + (size_t)(t + 2) * kstep;
;             const char* a3 = a2 + kstep; const char* b3 = b2 + kstep;
;             if (last && has_next) S.a_ready(nxt);
;             if constexpr (SP2) {
;             PG8_LDB(B0, 0, 0); PG8_LDB(B1, 0, 1); PG8_SCHED; PG8_LDA(At, 0, 0); PG8_STAGE(PG8_SA(1, 1), a1 + hstepA, voffA);
;             PG8_WAIT_V(8); PG8_WAIT_L(0); PG8_BAR; PG8_MMA(0, 0, At, B0); PG8_MMA(0, 1, At, B1); PG8_BAR; PG8_SCHED;
;             PG8_LDA(At, 0, 1); PG8_STAGE(PG8_SB(0, 0), b2, voffB); PG8_STAGE(PG8_SB(0, 1), b2 + hstepB, voffB); PG8_STAGE(PG8_SA(0, 0), a2, voffA);
;             PG8_WAIT_V(8); PG8_WAIT_L(0); PG8_BAR; PG8_MMA(1, 0, At, B0); PG8_MMA(1, 1, At, B1); PG8_BAR; PG8_SCHED;
.LBB0_991:
	ds_read_b128 v[144:147], v159
	ds_read_b128 v[148:151], v159 offset:1024
	ds_read_b128 v[162:165], v159 offset:2048
	ds_read_b128 v[166:169], v159 offset:3072
	ds_read_b128 v[170:173], v160
	ds_read_b128 v[174:177], v160 offset:1024
	ds_read_b128 v[178:181], v160 offset:2048
	ds_read_b128 v[182:185], v160 offset:3072
	s_add_u32 s34, s30, 0xfffc0080
	s_addc_u32 s35, s31, -1
	s_cmp_eq_u32 s65, 12
	s_cselect_b32 s37, s23, s35
	s_cselect_b32 s36, s61, s34
	s_cselect_b32 s35, s21, s64
	s_cselect_b32 s34, s62, s63
	s_add_i32 m0, s29, 0xc000
	ds_read_b128 v[188:191], v161
	ds_read_b128 v[192:195], v161 offset:1024
	ds_read_b128 v[196:199], v161 offset:2048
	ds_read_b128 v[200:203], v161 offset:3072
	ds_read_b128 v[204:207], v161 offset:4096
	ds_read_b128 v[208:211], v161 offset:5120
	ds_read_b128 v[212:215], v161 offset:6144
	ds_read_b128 v[216:219], v161 offset:7168
	global_load_lds_dwordx4 v136, s[30:31]
	s_add_i32 m0, s29, 0xe000
	s_nop 0
	global_load_lds_dwordx4 v138, s[30:31]
	s_waitcnt vmcnt(8)
	s_waitcnt lgkmcnt(0)
	s_barrier
	s_setprio 1
	s_waitcnt lgkmcnt(0)
	v_mfma_f32_16x16x32_bf16 v[124:127], v[144:147], v[188:191], v[124:127]
	v_mfma_f32_16x16x32_bf16 v[120:123], v[162:165], v[188:191], v[120:123]
	v_mfma_f32_16x16x32_bf16 v[108:111], v[144:147], v[196:199], v[108:111]
	v_mfma_f32_16x16x32_bf16 v[104:107], v[162:165], v[196:199], v[104:107]
	v_mfma_f32_16x16x32_bf16 v[92:95], v[144:147], v[204:207], v[92:95]
	v_mfma_f32_16x16x32_bf16 v[88:91], v[162:165], v[204:207], v[88:91]
	v_mfma_f32_16x16x32_bf16 v[76:79], v[144:147], v[212:215], v[76:79]
	v_mfma_f32_16x16x32_bf16 v[72:75], v[162:165], v[212:215], v[72:75]
	v_mfma_f32_16x16x32_bf16 v[124:127], v[148:151], v[192:195], v[124:127]
	v_mfma_f32_16x16x32_bf16 v[120:123], v[166:169], v[192:195], v[120:123]
	v_mfma_f32_16x16x32_bf16 v[108:111], v[148:151], v[200:203], v[108:111]
	v_mfma_f32_16x16x32_bf16 v[104:107], v[166:169], v[200:203], v[104:107]
	v_mfma_f32_16x16x32_bf16 v[92:95], v[148:151], v[208:211], v[92:95]
	v_mfma_f32_16x16x32_bf16 v[88:91], v[166:169], v[208:211], v[88:91]
	v_mfma_f32_16x16x32_bf16 v[76:79], v[148:151], v[216:219], v[76:79]
	v_mfma_f32_16x16x32_bf16 v[72:75], v[166:169], v[216:219], v[72:75]
	s_setprio 0
	s_setprio 1
	v_mfma_f32_16x16x32_bf16 v[116:119], v[170:173], v[188:191], v[116:119]
	v_mfma_f32_16x16x32_bf16 v[112:115], v[178:181], v[188:191], v[112:115]
	v_mfma_f32_16x16x32_bf16 v[100:103], v[170:173], v[196:199], v[100:103]
	v_mfma_f32_16x16x32_bf16 v[96:99], v[178:181], v[196:199], v[96:99]
	v_mfma_f32_16x16x32_bf16 v[84:87], v[170:173], v[204:207], v[84:87]
	v_mfma_f32_16x16x32_bf16 v[80:83], v[178:181], v[204:207], v[80:83]
	v_mfma_f32_16x16x32_bf16 v[68:71], v[170:173], v[212:215], v[68:71]
	v_mfma_f32_16x16x32_bf16 v[64:67], v[178:181], v[212:215], v[64:67]
	v_mfma_f32_16x16x32_bf16 v[116:119], v[174:177], v[192:195], v[116:119]
	v_mfma_f32_16x16x32_bf16 v[112:115], v[182:185], v[192:195], v[112:115]
	v_mfma_f32_16x16x32_bf16 v[100:103], v[174:177], v[200:203], v[100:103]
	v_mfma_f32_16x16x32_bf16 v[96:99], v[182:185], v[200:203], v[96:99]
	v_mfma_f32_16x16x32_bf16 v[84:87], v[174:177], v[208:211], v[84:87]
	v_mfma_f32_16x16x32_bf16 v[80:83], v[182:185], v[208:211], v[80:83]
	v_mfma_f32_16x16x32_bf16 v[68:71], v[174:177], v[216:219], v[68:71]
	v_mfma_f32_16x16x32_bf16 v[64:67], v[182:185], v[216:219], v[64:67]
	s_setprio 0
	s_barrier
	s_add_u32 s98, s34, 0x80
	s_addc_u32 s99, s35, 0
	s_add_u32 s100, s36, 0x80
	s_addc_u32 s101, s37, 0
	s_add_i32 s66, s55, s19
	s_mov_b32 m0, s66
	ds_read_b128 v[188:191], v161 offset:16384
	ds_read_b128 v[192:195], v161 offset:17408
	ds_read_b128 v[196:199], v161 offset:18432
	ds_read_b128 v[200:203], v161 offset:19456
	ds_read_b128 v[204:207], v161 offset:20480
	ds_read_b128 v[208:211], v161 offset:21504
	ds_read_b128 v[212:215], v161 offset:22528
	ds_read_b128 v[216:219], v161 offset:23552
	global_load_lds_dwordx4 v132, s[34:35]
	s_add_i32 m0, s66, 0x2000
	s_add_u32 s66, s34, 0x40000
	s_addc_u32 s67, s35, 0
	s_add_i32 s69, s56, s19
	global_load_lds_dwordx4 v128, s[34:35]
	s_mov_b32 m0, s69
	s_nop 0
	global_load_lds_dwordx4 v132, s[66:67]
	s_add_i32 m0, s69, 0x2000
	s_nop 0
	global_load_lds_dwordx4 v128, s[66:67]
	s_mov_b32 m0, s29
	s_nop 0
	global_load_lds_dwordx4 v134, s[36:37]
	s_mov_b32 m0, s50
	s_nop 0
	global_load_lds_dwordx4 v130, s[36:37]
	s_waitcnt vmcnt(8)
	s_waitcnt lgkmcnt(0)
	s_barrier
	s_setprio 1
	s_waitcnt lgkmcnt(0)
	v_mfma_f32_16x16x32_bf16 v[60:63], v[144:147], v[188:191], v[60:63]
	v_mfma_f32_16x16x32_bf16 v[56:59], v[162:165], v[188:191], v[56:59]
	v_mfma_f32_16x16x32_bf16 v[44:47], v[144:147], v[196:199], v[44:47]
	v_mfma_f32_16x16x32_bf16 v[40:43], v[162:165], v[196:199], v[40:43]
	v_mfma_f32_16x16x32_bf16 v[28:31], v[144:147], v[204:207], v[28:31]
	v_mfma_f32_16x16x32_bf16 v[24:27], v[162:165], v[204:207], v[24:27]
	v_mfma_f32_16x16x32_bf16 v[12:15], v[144:147], v[212:215], v[12:15]
	v_mfma_f32_16x16x32_bf16 v[8:11], v[162:165], v[212:215], v[8:11]
	v_mfma_f32_16x16x32_bf16 v[60:63], v[148:151], v[192:195], v[60:63]
	v_mfma_f32_16x16x32_bf16 v[56:59], v[166:169], v[192:195], v[56:59]
	v_mfma_f32_16x16x32_bf16 v[44:47], v[148:151], v[200:203], v[44:47]
	v_mfma_f32_16x16x32_bf16 v[40:43], v[166:169], v[200:203], v[40:43]
	v_mfma_f32_16x16x32_bf16 v[28:31], v[148:151], v[208:211], v[28:31]
	v_mfma_f32_16x16x32_bf16 v[24:27], v[166:169], v[208:211], v[24:27]
	v_mfma_f32_16x16x32_bf16 v[12:15], v[148:151], v[216:219], v[12:15]
	v_mfma_f32_16x16x32_bf16 v[8:11], v[166:169], v[216:219], v[8:11]
	s_setprio 0
	s_setprio 1
	v_mfma_f32_16x16x32_bf16 v[52:55], v[170:173], v[188:191], v[52:55]
	v_mfma_f32_16x16x32_bf16 v[48:51], v[178:181], v[188:191], v[48:51]
	v_mfma_f32_16x16x32_bf16 v[36:39], v[170:173], v[196:199], v[36:39]
	v_mfma_f32_16x16x32_bf16 v[32:35], v[178:181], v[196:199], v[32:35]
	v_mfma_f32_16x16x32_bf16 v[20:23], v[170:173], v[204:207], v[20:23]
	v_mfma_f32_16x16x32_bf16 v[16:19], v[178:181], v[204:207], v[16:19]
	v_mfma_f32_16x16x32_bf16 v[4:7], v[170:173], v[212:215], v[4:7]
	v_mfma_f32_16x16x32_bf16 v[0:3], v[178:181], v[212:215], v[0:3]
	v_mfma_f32_16x16x32_bf16 v[52:55], v[174:177], v[192:195], v[52:55]
	v_mfma_f32_16x16x32_bf16 v[48:51], v[182:185], v[192:195], v[48:51]
	v_mfma_f32_16x16x32_bf16 v[36:39], v[174:177], v[200:203], v[36:39]
	v_mfma_f32_16x16x32_bf16 v[32:35], v[182:185], v[200:203], v[32:35]
	v_mfma_f32_16x16x32_bf16 v[20:23], v[174:177], v[208:211], v[20:23]
	v_mfma_f32_16x16x32_bf16 v[16:19], v[182:185], v[208:211], v[16:19]
	v_mfma_f32_16x16x32_bf16 v[4:7], v[174:177], v[216:219], v[4:7]
	v_mfma_f32_16x16x32_bf16 v[0:3], v[182:185], v[216:219], v[0:3]
	s_setprio 0
	s_barrier
; #define PG8_STAGE(bufoff, gbase, voff) do { _Pragma("unroll") for (int _i = 0; _i < 2; ++_i) \
;         __builtin_amdgcn_global_load_lds((const unsigned*)((const char*)(gbase) + (voff)[_i]), (PG8_LAS unsigned*)(lds + (bufoff) + ldsw + _i * 8192), 16, 0, 0); } while (0)
; #define PG8_LDA(dst, b, h) do { _Pragma("unroll") for (int m = 0; m < 4; ++m) _Pragma("unroll") for (int k = 0; k < 2; ++k) dst[m][k] = *(const PG8_LAS bf16x8*)(lds + PG8_SA(b, h) + aoff + m * 2048 + k * 1024); } while (0)
; #define PG8_LDB(dst, b, h) do { _Pragma("unroll") for (int n = 0; n < 2; ++n) _Pragma("unroll") for (int k = 0; k < 2; ++k) dst[n][k] = *(const PG8_LAS bf16x8*)(lds + PG8_SB(b, h) + boff + n * 2048 + k * 1024); } while (0)
; #define PG8_MMA(ai, bj, At, Bt) do { __builtin_amdgcn_s_setprio(1); _Pragma("unroll") for (int m = 0; m < 4; ++m) _Pragma("unroll") for (int n = 0; n < 2; ++n) _Pragma("unroll") for (int k = 0; k < 2; ++k) \
;         acc[ai][bj][m][n] = __builtin_amdgcn_mfma_f32_16x16x32_bf16(Bt[n][k], At[m][k], acc[ai][bj][m][n], 0, 0, 0); __builtin_amdgcn_s_setprio(0); } while (0)
; #define PG8_WAIT_V(n) asm volatile("s_waitcnt vmcnt(" #n ")" ::: "memory")
; #define PG8_WAIT_L(n) asm volatile("s_waitcnt lgkmcnt(" #n ")" ::: "memory")
; #define PG8_BAR __builtin_amdgcn_s_barrier()
; #define PG8_SCHED __builtin_amdgcn_sched_barrier(0)
; template <class Epi, class Sched, bool ALIGN_EPI = false, bool SP2 = false>
; __device__ __forceinline__ void gemm_phase(PG8_LAS unsigned char* lds, const Gemm g, const Sched S, const Epi E, const int tid) {
;     ...
;         for (int t = 0; t < nt; t += 2) {
;     ...
;             PG8_LDB(B0, 1, 0); PG8_LDB(B1, 1, 1); PG8_SCHED; PG8_LDA(At, 1, 0); PG8_STAGE(PG8_SA(0, 1), a2 + hstepA, voffA);
;             PG8_WAIT_V(8); PG8_WAIT_L(0); PG8_BAR; PG8_MMA(0, 0, At, B0); PG8_MMA(0, 1, At, B1); PG8_BAR; PG8_SCHED;
;             PG8_LDA(At, 1, 1); PG8_STAGE(PG8_SB(1, 0), b3, voffB); PG8_STAGE(PG8_SB(1, 1), b3 + hstepB, voffB); PG8_STAGE(PG8_SA(1, 0), a3, voffA);
;             PG8_WAIT_V(8); PG8_WAIT_L(0); PG8_BAR; PG8_MMA(1, 0, At, B0); PG8_MMA(1, 1, At, B1); PG8_BAR; PG8_SCHED;
	s_add_i32 s66, 0, 0x18000
	s_add_i32 s67, 0, 0x1c000
	v_add_u32_e32 v166, s66, v156
	v_add_u32_e32 v182, s67, v156
	ds_read_b128 v[144:147], v166
	ds_read_b128 v[148:151], v166 offset:1024
	ds_read_b128 v[162:165], v166 offset:2048
	ds_read_b128 v[166:169], v166 offset:3072
	ds_read_b128 v[170:173], v182
	ds_read_b128 v[174:177], v182 offset:1024
	ds_read_b128 v[178:181], v182 offset:2048
	ds_read_b128 v[182:185], v182 offset:3072
	s_add_u32 s36, s36, 0x40000
	s_addc_u32 s37, s37, 0
	s_mov_b32 m0, s51
	ds_read_b128 v[188:191], v161 offset:32768
	ds_read_b128 v[192:195], v161 offset:33792
	ds_read_b128 v[196:199], v161 offset:34816
	ds_read_b128 v[200:203], v161 offset:35840
	ds_read_b128 v[204:207], v161 offset:36864
	ds_read_b128 v[208:211], v161 offset:37888
	ds_read_b128 v[212:215], v161 offset:38912
	ds_read_b128 v[216:219], v161 offset:39936
	global_load_lds_dwordx4 v134, s[36:37]
	s_mov_b32 m0, s52
	s_nop 0
	global_load_lds_dwordx4 v130, s[36:37]
	s_waitcnt vmcnt(8)
	s_waitcnt lgkmcnt(0)
	s_barrier
	s_setprio 1
	s_waitcnt lgkmcnt(0)
	v_mfma_f32_16x16x32_bf16 v[124:127], v[144:147], v[188:191], v[124:127]
	v_mfma_f32_16x16x32_bf16 v[120:123], v[162:165], v[188:191], v[120:123]
	v_mfma_f32_16x16x32_bf16 v[108:111], v[144:147], v[196:199], v[108:111]
	v_mfma_f32_16x16x32_bf16 v[104:107], v[162:165], v[196:199], v[104:107]
	v_mfma_f32_16x16x32_bf16 v[92:95], v[144:147], v[204:207], v[92:95]
	v_mfma_f32_16x16x32_bf16 v[88:91], v[162:165], v[204:207], v[88:91]
	v_mfma_f32_16x16x32_bf16 v[76:79], v[144:147], v[212:215], v[76:79]
	v_mfma_f32_16x16x32_bf16 v[72:75], v[162:165], v[212:215], v[72:75]
	v_mfma_f32_16x16x32_bf16 v[124:127], v[148:151], v[192:195], v[124:127]
	v_mfma_f32_16x16x32_bf16 v[120:123], v[166:169], v[192:195], v[120:123]
	v_mfma_f32_16x16x32_bf16 v[108:111], v[148:151], v[200:203], v[108:111]
	v_mfma_f32_16x16x32_bf16 v[104:107], v[166:169], v[200:203], v[104:107]
	v_mfma_f32_16x16x32_bf16 v[92:95], v[148:151], v[208:211], v[92:95]
	v_mfma_f32_16x16x32_bf16 v[88:91], v[166:169], v[208:211], v[88:91]
	v_mfma_f32_16x16x32_bf16 v[76:79], v[148:151], v[216:219], v[76:79]
	v_mfma_f32_16x16x32_bf16 v[72:75], v[166:169], v[216:219], v[72:75]
	s_setprio 0
	s_setprio 1
	v_mfma_f32_16x16x32_bf16 v[116:119], v[170:173], v[188:191], v[116:119]
	v_mfma_f32_16x16x32_bf16 v[112:115], v[178:181], v[188:191], v[112:115]
	v_mfma_f32_16x16x32_bf16 v[100:103], v[170:173], v[196:199], v[100:103]
	v_mfma_f32_16x16x32_bf16 v[96:99], v[178:181], v[196:199], v[96:99]
	v_mfma_f32_16x16x32_bf16 v[84:87], v[170:173], v[204:207], v[84:87]
	v_mfma_f32_16x16x32_bf16 v[80:83], v[178:181], v[204:207], v[80:83]
	v_mfma_f32_16x16x32_bf16 v[68:71], v[170:173], v[212:215], v[68:71]
	v_mfma_f32_16x16x32_bf16 v[64:67], v[178:181], v[212:215], v[64:67]
	v_mfma_f32_16x16x32_bf16 v[116:119], v[174:177], v[192:195], v[116:119]
	v_mfma_f32_16x16x32_bf16 v[112:115], v[182:185], v[192:195], v[112:115]
	v_mfma_f32_16x16x32_bf16 v[100:103], v[174:177], v[200:203], v[100:103]
	v_mfma_f32_16x16x32_bf16 v[96:99], v[182:185], v[200:203], v[96:99]
	v_mfma_f32_16x16x32_bf16 v[84:87], v[174:177], v[208:211], v[84:87]
	v_mfma_f32_16x16x32_bf16 v[80:83], v[182:185], v[208:211], v[80:83]
	v_mfma_f32_16x16x32_bf16 v[68:71], v[174:177], v[216:219], v[68:71]
	v_mfma_f32_16x16x32_bf16 v[64:67], v[182:185], v[216:219], v[64:67]
	s_setprio 0
	s_barrier
	s_add_i32 s36, s66, s19
	s_mov_b32 m0, s36
	ds_read_b128 v[188:191], v161 offset:49152
	ds_read_b128 v[192:195], v161 offset:50176
	ds_read_b128 v[196:199], v161 offset:51200
	ds_read_b128 v[200:203], v161 offset:52224
	ds_read_b128 v[204:207], v161 offset:53248
	ds_read_b128 v[208:211], v161 offset:54272
	ds_read_b128 v[212:215], v161 offset:55296
	ds_read_b128 v[216:219], v161 offset:56320
	global_load_lds_dwordx4 v132, s[98:99]
	s_add_i32 m0, s36, 0x2000
	s_add_u32 s34, s34, 0x40080
	s_addc_u32 s35, s35, 0
	s_add_i32 s36, s67, s19
	global_load_lds_dwordx4 v128, s[98:99]
	s_mov_b32 m0, s36
	s_nop 0
	global_load_lds_dwordx4 v132, s[34:35]
	s_add_i32 m0, s36, 0x2000
	s_nop 0
	global_load_lds_dwordx4 v128, s[34:35]
	s_mov_b32 m0, s53
	s_nop 0
	global_load_lds_dwordx4 v134, s[100:101]
	s_mov_b32 m0, s54
	s_nop 0
	global_load_lds_dwordx4 v130, s[100:101]
	s_waitcnt vmcnt(8)
	s_waitcnt lgkmcnt(0)
	s_barrier
	s_setprio 1
	s_waitcnt lgkmcnt(0)
	v_mfma_f32_16x16x32_bf16 v[60:63], v[144:147], v[188:191], v[60:63]
	v_mfma_f32_16x16x32_bf16 v[56:59], v[162:165], v[188:191], v[56:59]
	v_mfma_f32_16x16x32_bf16 v[44:47], v[144:147], v[196:199], v[44:47]
	v_mfma_f32_16x16x32_bf16 v[40:43], v[162:165], v[196:199], v[40:43]
	v_mfma_f32_16x16x32_bf16 v[28:31], v[144:147], v[204:207], v[28:31]
	v_mfma_f32_16x16x32_bf16 v[24:27], v[162:165], v[204:207], v[24:27]
	v_mfma_f32_16x16x32_bf16 v[12:15], v[144:147], v[212:215], v[12:15]
	v_mfma_f32_16x16x32_bf16 v[8:11], v[162:165], v[212:215], v[8:11]
	v_mfma_f32_16x16x32_bf16 v[60:63], v[148:151], v[192:195], v[60:63]
	v_mfma_f32_16x16x32_bf16 v[56:59], v[166:169], v[192:195], v[56:59]
	v_mfma_f32_16x16x32_bf16 v[44:47], v[148:151], v[200:203], v[44:47]
	v_mfma_f32_16x16x32_bf16 v[40:43], v[166:169], v[200:203], v[40:43]
	v_mfma_f32_16x16x32_bf16 v[28:31], v[148:151], v[208:211], v[28:31]
	v_mfma_f32_16x16x32_bf16 v[24:27], v[166:169], v[208:211], v[24:27]
	v_mfma_f32_16x16x32_bf16 v[12:15], v[148:151], v[216:219], v[12:15]
	v_mfma_f32_16x16x32_bf16 v[8:11], v[166:169], v[216:219], v[8:11]
	s_setprio 0
	s_setprio 1
	v_mfma_f32_16x16x32_bf16 v[52:55], v[170:173], v[188:191], v[52:55]
	v_mfma_f32_16x16x32_bf16 v[48:51], v[178:181], v[188:191], v[48:51]
	v_mfma_f32_16x16x32_bf16 v[36:39], v[170:173], v[196:199], v[36:39]
	v_mfma_f32_16x16x32_bf16 v[32:35], v[178:181], v[196:199], v[32:35]
	v_mfma_f32_16x16x32_bf16 v[20:23], v[170:173], v[204:207], v[20:23]
	v_mfma_f32_16x16x32_bf16 v[16:19], v[178:181], v[204:207], v[16:19]
	v_mfma_f32_16x16x32_bf16 v[4:7], v[170:173], v[212:215], v[4:7]
	v_mfma_f32_16x16x32_bf16 v[0:3], v[178:181], v[212:215], v[0:3]
	v_mfma_f32_16x16x32_bf16 v[52:55], v[174:177], v[192:195], v[52:55]
	v_mfma_f32_16x16x32_bf16 v[48:51], v[182:185], v[192:195], v[48:51]
	v_mfma_f32_16x16x32_bf16 v[36:39], v[174:177], v[200:203], v[36:39]
	v_mfma_f32_16x16x32_bf16 v[32:35], v[182:185], v[200:203], v[32:35]
	v_mfma_f32_16x16x32_bf16 v[20:23], v[174:177], v[208:211], v[20:23]
	v_mfma_f32_16x16x32_bf16 v[16:19], v[182:185], v[208:211], v[16:19]
	v_mfma_f32_16x16x32_bf16 v[4:7], v[174:177], v[216:219], v[4:7]
	v_mfma_f32_16x16x32_bf16 v[0:3], v[182:185], v[216:219], v[0:3]
	s_setprio 0
	s_barrier
	s_add_i32 s65, s65, 2
	s_add_u32 s30, s30, 0x100
	s_addc_u32 s31, s31, 0
	s_add_u32 s63, s63, 0x100
	s_addc_u32 s64, s64, 0
	s_cmp_gt_u32 s65, 13
	s_cbranch_scc0 .LBB0_991
	s_and_b64 vcc, exec, s[16:17]
	s_cbranch_vccz .LBB0_994
	s_barrier

; #define PG8_STAGE(bufoff, gbase, voff) do { _Pragma("unroll") for (int _i = 0; _i < 2; ++_i) \
;         __builtin_amdgcn_global_load_lds((const unsigned*)((const char*)(gbase) + (voff)[_i]), (PG8_LAS unsigned*)(lds + (bufoff) + ldsw + _i * 8192), 16, 0, 0); } while (0)
; #define PG8_LDA(dst, b, h) do { _Pragma("unroll") for (int m = 0; m < 4; ++m) _Pragma("unroll") for (int k = 0; k < 2; ++k) dst[m][k] = *(const PG8_LAS bf16x8*)(lds + PG8_SA(b, h) + aoff + m * 2048 + k * 1024); } while (0)
; #define PG8_LDB(dst, b, h) do { _Pragma("unroll") for (int n = 0; n < 2; ++n) _Pragma("unroll") for (int k = 0; k < 2; ++k) dst[n][k] = *(const PG8_LAS bf16x8*)(lds + PG8_SB(b, h) + boff + n * 2048 + k * 1024); } while (0)
; #define PG8_MMA(ai, bj, At, Bt) do { __builtin_amdgcn_s_setprio(1); _Pragma("unroll") for (int m = 0; m < 4; ++m) _Pragma("unroll") for (int n = 0; n < 2; ++n) _Pragma("unroll") for (int k = 0; k < 2; ++k) \
;         acc[ai][bj][m][n] = __builtin_amdgcn_mfma_f32_16x16x32_bf16(Bt[n][k], At[m][k], acc[ai][bj][m][n], 0, 0, 0); __builtin_amdgcn_s_setprio(0); } while (0)
; #define PG8_WAIT_V(n) asm volatile("s_waitcnt vmcnt(" #n ")" ::: "memory")
; #define PG8_WAIT_L(n) asm volatile("s_waitcnt lgkmcnt(" #n ")" ::: "memory")
; template <class Epi, class Sched, bool ALIGN_EPI = false, bool SP2 = false>
; __device__ __forceinline__ void gemm_phase(PG8_LAS unsigned char* lds, const Gemm g, const Sched S, const Epi E, const int tid) {
;     ...
;             const bool last = (t == nt - 2);
;             const char* a1 = cA + (size_t)(t + 1) * kstep;
;             const char* a2 = last ? nA : cA + (size_t)(t + 2) * kstep; const char* b2 = last ? nB : cB + (size_t)(t + 2) * kstep;
;             const char* a3 = a2 + kstep; const char* b3 = b2 + kstep;
;             if (last && has_next) S.a_ready(nxt);
;             if constexpr (SP2) {
;             PG8_LDB(B0, 0, 0); PG8_LDB(B1, 0, 1); PG8_SCHED; PG8_LDA(At, 0, 0); PG8_STAGE(PG8_SA(1, 1), a1 + hstepA, voffA);
;             PG8_WAIT_V(8); PG8_WAIT_L(0); PG8_BAR; PG8_MMA(0, 0, At, B0); PG8_MMA(0, 1, At, B1); PG8_BAR; PG8_SCHED;
;             PG8_LDA(At, 0, 1); PG8_STAGE(PG8_SB(0, 0), b2, voffB); PG8_STAGE(PG8_SB(0, 1), b2 + hstepB, voffB); PG8_STAGE(PG8_SA(0, 0), a2, voffA);
;             PG8_WAIT_V(8); PG8_WAIT_L(0); PG8_BAR; PG8_MMA(1, 0, At, B0); PG8_MMA(1, 1, At, B1); PG8_BAR; PG8_SCHED;
.LBB0_1196:
	ds_read_b128 v[146:149], v169
	ds_read_b128 v[150:153], v169 offset:1024
	ds_read_b128 v[172:175], v169 offset:2048
	ds_read_b128 v[176:179], v169 offset:3072
	ds_read_b128 v[180:183], v170
	ds_read_b128 v[188:191], v170 offset:1024
	ds_read_b128 v[192:195], v170 offset:2048
	ds_read_b128 v[196:199], v170 offset:3072
	s_add_u32 s34, s30, 0xfffc0080
	s_addc_u32 s35, s31, -1
	s_cmp_eq_u32 s64, 12
	s_cselect_b32 s37, s23, s35
	s_cselect_b32 s36, s60, s34
	s_cselect_b32 s35, s15, s63
	s_cselect_b32 s34, s61, s62
	s_add_i32 m0, s29, 0xc000
	ds_read_b128 v[200:203], v171
	ds_read_b128 v[204:207], v171 offset:1024
	ds_read_b128 v[208:211], v171 offset:2048
	ds_read_b128 v[212:215], v171 offset:3072
	ds_read_b128 v[216:219], v171 offset:4096
	ds_read_b128 v[220:223], v171 offset:5120
	ds_read_b128 v[224:227], v171 offset:6144
	ds_read_b128 v[228:231], v171 offset:7168
	global_load_lds_dwordx4 v138, s[30:31]
	s_add_i32 m0, s29, 0xe000
	s_nop 0
	global_load_lds_dwordx4 v140, s[30:31]
	s_waitcnt vmcnt(8)
	s_waitcnt lgkmcnt(0)
	s_barrier
	s_setprio 1
	s_waitcnt lgkmcnt(0)
	v_mfma_f32_16x16x32_bf16 v[124:127], v[146:149], v[200:203], v[124:127]
	v_mfma_f32_16x16x32_bf16 v[120:123], v[172:175], v[200:203], v[120:123]
	v_mfma_f32_16x16x32_bf16 v[108:111], v[146:149], v[208:211], v[108:111]
	v_mfma_f32_16x16x32_bf16 v[104:107], v[172:175], v[208:211], v[104:107]
	v_mfma_f32_16x16x32_bf16 v[92:95], v[146:149], v[216:219], v[92:95]
	v_mfma_f32_16x16x32_bf16 v[88:91], v[172:175], v[216:219], v[88:91]
	v_mfma_f32_16x16x32_bf16 v[76:79], v[146:149], v[224:227], v[76:79]
	v_mfma_f32_16x16x32_bf16 v[72:75], v[172:175], v[224:227], v[72:75]
	v_mfma_f32_16x16x32_bf16 v[124:127], v[150:153], v[204:207], v[124:127]
	v_mfma_f32_16x16x32_bf16 v[120:123], v[176:179], v[204:207], v[120:123]
	v_mfma_f32_16x16x32_bf16 v[108:111], v[150:153], v[212:215], v[108:111]
	v_mfma_f32_16x16x32_bf16 v[104:107], v[176:179], v[212:215], v[104:107]
	v_mfma_f32_16x16x32_bf16 v[92:95], v[150:153], v[220:223], v[92:95]
	v_mfma_f32_16x16x32_bf16 v[88:91], v[176:179], v[220:223], v[88:91]
	v_mfma_f32_16x16x32_bf16 v[76:79], v[150:153], v[228:231], v[76:79]
	v_mfma_f32_16x16x32_bf16 v[72:75], v[176:179], v[228:231], v[72:75]
	s_setprio 0
	s_setprio 1
	v_mfma_f32_16x16x32_bf16 v[116:119], v[180:183], v[200:203], v[116:119]
	v_mfma_f32_16x16x32_bf16 v[112:115], v[192:195], v[200:203], v[112:115]
	v_mfma_f32_16x16x32_bf16 v[100:103], v[180:183], v[208:211], v[100:103]
	v_mfma_f32_16x16x32_bf16 v[96:99], v[192:195], v[208:211], v[96:99]
	v_mfma_f32_16x16x32_bf16 v[84:87], v[180:183], v[216:219], v[84:87]
	v_mfma_f32_16x16x32_bf16 v[80:83], v[192:195], v[216:219], v[80:83]
	v_mfma_f32_16x16x32_bf16 v[68:71], v[180:183], v[224:227], v[68:71]
	v_mfma_f32_16x16x32_bf16 v[64:67], v[192:195], v[224:227], v[64:67]
	v_mfma_f32_16x16x32_bf16 v[116:119], v[188:191], v[204:207], v[116:119]
	v_mfma_f32_16x16x32_bf16 v[112:115], v[196:199], v[204:207], v[112:115]
	v_mfma_f32_16x16x32_bf16 v[100:103], v[188:191], v[212:215], v[100:103]
	v_mfma_f32_16x16x32_bf16 v[96:99], v[196:199], v[212:215], v[96:99]
	v_mfma_f32_16x16x32_bf16 v[84:87], v[188:191], v[220:223], v[84:87]
	v_mfma_f32_16x16x32_bf16 v[80:83], v[196:199], v[220:223], v[80:83]
	v_mfma_f32_16x16x32_bf16 v[68:71], v[188:191], v[228:231], v[68:71]
	v_mfma_f32_16x16x32_bf16 v[64:67], v[196:199], v[228:231], v[64:67]
	s_setprio 0
	s_barrier
	s_add_u32 s98, s34, 0x80
	s_addc_u32 s99, s35, 0
	s_add_u32 s100, s36, 0x80
	s_addc_u32 s101, s37, 0
	s_add_i32 s65, s52, s13
	s_mov_b32 m0, s65
	ds_read_b128 v[200:203], v171 offset:16384
	ds_read_b128 v[204:207], v171 offset:17408
	ds_read_b128 v[208:211], v171 offset:18432
	ds_read_b128 v[212:215], v171 offset:19456
	ds_read_b128 v[216:219], v171 offset:20480
	ds_read_b128 v[220:223], v171 offset:21504
	ds_read_b128 v[224:227], v171 offset:22528
	ds_read_b128 v[228:231], v171 offset:23552
	global_load_lds_dwordx4 v130, s[34:35]
	s_add_i32 m0, s65, 0x2000
	s_add_u32 s66, s34, 0x40000
	s_addc_u32 s67, s35, 0
	s_add_i32 s65, s53, s13
	global_load_lds_dwordx4 v134, s[34:35]
	s_mov_b32 m0, s65
	s_nop 0
	global_load_lds_dwordx4 v130, s[66:67]
	s_add_i32 m0, s65, 0x2000
	s_nop 0
	global_load_lds_dwordx4 v134, s[66:67]
	s_mov_b32 m0, s29
	s_nop 0
	global_load_lds_dwordx4 v128, s[36:37]
	s_mov_b32 m0, s47
	s_nop 0
	global_load_lds_dwordx4 v132, s[36:37]
	s_waitcnt vmcnt(8)
	s_waitcnt lgkmcnt(0)
	s_barrier
	s_setprio 1
	s_waitcnt lgkmcnt(0)
	v_mfma_f32_16x16x32_bf16 v[60:63], v[146:149], v[200:203], v[60:63]
	v_mfma_f32_16x16x32_bf16 v[56:59], v[172:175], v[200:203], v[56:59]
	v_mfma_f32_16x16x32_bf16 v[44:47], v[146:149], v[208:211], v[44:47]
	v_mfma_f32_16x16x32_bf16 v[40:43], v[172:175], v[208:211], v[40:43]
	v_mfma_f32_16x16x32_bf16 v[28:31], v[146:149], v[216:219], v[28:31]
	v_mfma_f32_16x16x32_bf16 v[24:27], v[172:175], v[216:219], v[24:27]
	v_mfma_f32_16x16x32_bf16 v[12:15], v[146:149], v[224:227], v[12:15]
	v_mfma_f32_16x16x32_bf16 v[8:11], v[172:175], v[224:227], v[8:11]
	v_mfma_f32_16x16x32_bf16 v[60:63], v[150:153], v[204:207], v[60:63]
	v_mfma_f32_16x16x32_bf16 v[56:59], v[176:179], v[204:207], v[56:59]
	v_mfma_f32_16x16x32_bf16 v[44:47], v[150:153], v[212:215], v[44:47]
	v_mfma_f32_16x16x32_bf16 v[40:43], v[176:179], v[212:215], v[40:43]
	v_mfma_f32_16x16x32_bf16 v[28:31], v[150:153], v[220:223], v[28:31]
	v_mfma_f32_16x16x32_bf16 v[24:27], v[176:179], v[220:223], v[24:27]
	v_mfma_f32_16x16x32_bf16 v[12:15], v[150:153], v[228:231], v[12:15]
	v_mfma_f32_16x16x32_bf16 v[8:11], v[176:179], v[228:231], v[8:11]
	s_setprio 0
	s_setprio 1
	v_mfma_f32_16x16x32_bf16 v[52:55], v[180:183], v[200:203], v[52:55]
	v_mfma_f32_16x16x32_bf16 v[48:51], v[192:195], v[200:203], v[48:51]
	v_mfma_f32_16x16x32_bf16 v[36:39], v[180:183], v[208:211], v[36:39]
	v_mfma_f32_16x16x32_bf16 v[32:35], v[192:195], v[208:211], v[32:35]
	v_mfma_f32_16x16x32_bf16 v[20:23], v[180:183], v[216:219], v[20:23]
	v_mfma_f32_16x16x32_bf16 v[16:19], v[192:195], v[216:219], v[16:19]
	v_mfma_f32_16x16x32_bf16 v[4:7], v[180:183], v[224:227], v[4:7]
	v_mfma_f32_16x16x32_bf16 v[0:3], v[192:195], v[224:227], v[0:3]
	v_mfma_f32_16x16x32_bf16 v[52:55], v[188:191], v[204:207], v[52:55]
	v_mfma_f32_16x16x32_bf16 v[48:51], v[196:199], v[204:207], v[48:51]
	v_mfma_f32_16x16x32_bf16 v[36:39], v[188:191], v[212:215], v[36:39]
	v_mfma_f32_16x16x32_bf16 v[32:35], v[196:199], v[212:215], v[32:35]
	v_mfma_f32_16x16x32_bf16 v[20:23], v[188:191], v[220:223], v[20:23]
	v_mfma_f32_16x16x32_bf16 v[16:19], v[196:199], v[220:223], v[16:19]
	v_mfma_f32_16x16x32_bf16 v[4:7], v[188:191], v[228:231], v[4:7]
	v_mfma_f32_16x16x32_bf16 v[0:3], v[196:199], v[228:231], v[0:3]
	s_setprio 0
	s_barrier
; #define PG8_STAGE(bufoff, gbase, voff) do { _Pragma("unroll") for (int _i = 0; _i < 2; ++_i) \
;         __builtin_amdgcn_global_load_lds((const unsigned*)((const char*)(gbase) + (voff)[_i]), (PG8_LAS unsigned*)(lds + (bufoff) + ldsw + _i * 8192), 16, 0, 0); } while (0)
; #define PG8_LDA(dst, b, h) do { _Pragma("unroll") for (int m = 0; m < 4; ++m) _Pragma("unroll") for (int k = 0; k < 2; ++k) dst[m][k] = *(const PG8_LAS bf16x8*)(lds + PG8_SA(b, h) + aoff + m * 2048 + k * 1024); } while (0)
; #define PG8_LDB(dst, b, h) do { _Pragma("unroll") for (int n = 0; n < 2; ++n) _Pragma("unroll") for (int k = 0; k < 2; ++k) dst[n][k] = *(const PG8_LAS bf16x8*)(lds + PG8_SB(b, h) + boff + n * 2048 + k * 1024); } while (0)
; #define PG8_MMA(ai, bj, At, Bt) do { __builtin_amdgcn_s_setprio(1); _Pragma("unroll") for (int m = 0; m < 4; ++m) _Pragma("unroll") for (int n = 0; n < 2; ++n) _Pragma("unroll") for (int k = 0; k < 2; ++k) \
;         acc[ai][bj][m][n] = __builtin_amdgcn_mfma_f32_16x16x32_bf16(Bt[n][k], At[m][k], acc[ai][bj][m][n], 0, 0, 0); __builtin_amdgcn_s_setprio(0); } while (0)
; #define PG8_WAIT_V(n) asm volatile("s_waitcnt vmcnt(" #n ")" ::: "memory")
; #define PG8_WAIT_L(n) asm volatile("s_waitcnt lgkmcnt(" #n ")" ::: "memory")
; #define PG8_BAR __builtin_amdgcn_s_barrier()
; #define PG8_SCHED __builtin_amdgcn_sched_barrier(0)
; template <class Epi, class Sched, bool ALIGN_EPI = false, bool SP2 = false>
; __device__ __forceinline__ void gemm_phase(PG8_LAS unsigned char* lds, const Gemm g, const Sched S, const Epi E, const int tid) {
;     ...
;         for (int t = 0; t < nt; t += 2) {
;     ...
;             PG8_LDB(B0, 1, 0); PG8_LDB(B1, 1, 1); PG8_SCHED; PG8_LDA(At, 1, 0); PG8_STAGE(PG8_SA(0, 1), a2 + hstepA, voffA);
;             PG8_WAIT_V(8); PG8_WAIT_L(0); PG8_BAR; PG8_MMA(0, 0, At, B0); PG8_MMA(0, 1, At, B1); PG8_BAR; PG8_SCHED;
;             PG8_LDA(At, 1, 1); PG8_STAGE(PG8_SB(1, 0), b3, voffB); PG8_STAGE(PG8_SB(1, 1), b3 + hstepB, voffB); PG8_STAGE(PG8_SA(1, 0), a3, voffA);
;             PG8_WAIT_V(8); PG8_WAIT_L(0); PG8_BAR; PG8_MMA(1, 0, At, B0); PG8_MMA(1, 1, At, B1); PG8_BAR; PG8_SCHED;
	s_add_i32 s65, 0, 0x18000
	s_add_i32 s66, 0, 0x1c000
	v_add_u32_e32 v176, s65, v166
	v_add_u32_e32 v187, s66, v166
	ds_read_b128 v[146:149], v176
	ds_read_b128 v[150:153], v176 offset:1024
	ds_read_b128 v[172:175], v176 offset:2048
	ds_read_b128 v[176:179], v176 offset:3072
	ds_read_b128 v[180:183], v187
	ds_read_b128 v[188:191], v187 offset:1024
	ds_read_b128 v[192:195], v187 offset:2048
	ds_read_b128 v[196:199], v187 offset:3072
	s_add_u32 s36, s36, 0x40000
	s_addc_u32 s37, s37, 0
	s_mov_b32 m0, s48
	ds_read_b128 v[200:203], v171 offset:32768
	ds_read_b128 v[204:207], v171 offset:33792
	ds_read_b128 v[208:211], v171 offset:34816
	ds_read_b128 v[212:215], v171 offset:35840
	ds_read_b128 v[216:219], v171 offset:36864
	ds_read_b128 v[220:223], v171 offset:37888
	ds_read_b128 v[224:227], v171 offset:38912
	ds_read_b128 v[228:231], v171 offset:39936
	global_load_lds_dwordx4 v128, s[36:37]
	s_mov_b32 m0, s49
	s_nop 0
	global_load_lds_dwordx4 v132, s[36:37]
	s_waitcnt vmcnt(8)
	s_waitcnt lgkmcnt(0)
	s_barrier
	s_setprio 1
	s_waitcnt lgkmcnt(0)
	v_mfma_f32_16x16x32_bf16 v[124:127], v[146:149], v[200:203], v[124:127]
	v_mfma_f32_16x16x32_bf16 v[120:123], v[172:175], v[200:203], v[120:123]
	v_mfma_f32_16x16x32_bf16 v[108:111], v[146:149], v[208:211], v[108:111]
	v_mfma_f32_16x16x32_bf16 v[104:107], v[172:175], v[208:211], v[104:107]
	v_mfma_f32_16x16x32_bf16 v[92:95], v[146:149], v[216:219], v[92:95]
	v_mfma_f32_16x16x32_bf16 v[88:91], v[172:175], v[216:219], v[88:91]
	v_mfma_f32_16x16x32_bf16 v[76:79], v[146:149], v[224:227], v[76:79]
	v_mfma_f32_16x16x32_bf16 v[72:75], v[172:175], v[224:227], v[72:75]
	v_mfma_f32_16x16x32_bf16 v[124:127], v[150:153], v[204:207], v[124:127]
	v_mfma_f32_16x16x32_bf16 v[120:123], v[176:179], v[204:207], v[120:123]
	v_mfma_f32_16x16x32_bf16 v[108:111], v[150:153], v[212:215], v[108:111]
	v_mfma_f32_16x16x32_bf16 v[104:107], v[176:179], v[212:215], v[104:107]
	v_mfma_f32_16x16x32_bf16 v[92:95], v[150:153], v[220:223], v[92:95]
	v_mfma_f32_16x16x32_bf16 v[88:91], v[176:179], v[220:223], v[88:91]
	v_mfma_f32_16x16x32_bf16 v[76:79], v[150:153], v[228:231], v[76:79]
	v_mfma_f32_16x16x32_bf16 v[72:75], v[176:179], v[228:231], v[72:75]
	s_setprio 0
	s_setprio 1
	v_mfma_f32_16x16x32_bf16 v[116:119], v[180:183], v[200:203], v[116:119]
	v_mfma_f32_16x16x32_bf16 v[112:115], v[192:195], v[200:203], v[112:115]
	v_mfma_f32_16x16x32_bf16 v[100:103], v[180:183], v[208:211], v[100:103]
	v_mfma_f32_16x16x32_bf16 v[96:99], v[192:195], v[208:211], v[96:99]
	v_mfma_f32_16x16x32_bf16 v[84:87], v[180:183], v[216:219], v[84:87]
	v_mfma_f32_16x16x32_bf16 v[80:83], v[192:195], v[216:219], v[80:83]
	v_mfma_f32_16x16x32_bf16 v[68:71], v[180:183], v[224:227], v[68:71]
	v_mfma_f32_16x16x32_bf16 v[64:67], v[192:195], v[224:227], v[64:67]
	v_mfma_f32_16x16x32_bf16 v[116:119], v[188:191], v[204:207], v[116:119]
	v_mfma_f32_16x16x32_bf16 v[112:115], v[196:199], v[204:207], v[112:115]
	v_mfma_f32_16x16x32_bf16 v[100:103], v[188:191], v[212:215], v[100:103]
	v_mfma_f32_16x16x32_bf16 v[96:99], v[196:199], v[212:215], v[96:99]
	v_mfma_f32_16x16x32_bf16 v[84:87], v[188:191], v[220:223], v[84:87]
	v_mfma_f32_16x16x32_bf16 v[80:83], v[196:199], v[220:223], v[80:83]
	v_mfma_f32_16x16x32_bf16 v[68:71], v[188:191], v[228:231], v[68:71]
	v_mfma_f32_16x16x32_bf16 v[64:67], v[196:199], v[228:231], v[64:67]
	s_setprio 0
	s_barrier
	s_add_i32 s36, s65, s13
	s_mov_b32 m0, s36
	ds_read_b128 v[200:203], v171 offset:49152
	ds_read_b128 v[204:207], v171 offset:50176
	ds_read_b128 v[208:211], v171 offset:51200
	ds_read_b128 v[212:215], v171 offset:52224
	ds_read_b128 v[216:219], v171 offset:53248
	ds_read_b128 v[220:223], v171 offset:54272
	ds_read_b128 v[224:227], v171 offset:55296
	ds_read_b128 v[228:231], v171 offset:56320
	global_load_lds_dwordx4 v130, s[98:99]
	s_add_i32 m0, s36, 0x2000
	s_add_u32 s34, s34, 0x40080
	s_addc_u32 s35, s35, 0
	s_add_i32 s36, s66, s13
	global_load_lds_dwordx4 v134, s[98:99]
	s_mov_b32 m0, s36
	s_nop 0
	global_load_lds_dwordx4 v130, s[34:35]
	s_add_i32 m0, s36, 0x2000
	s_nop 0
	global_load_lds_dwordx4 v134, s[34:35]
	s_mov_b32 m0, s50
	s_nop 0
	global_load_lds_dwordx4 v128, s[100:101]
	s_mov_b32 m0, s51
	s_nop 0
	global_load_lds_dwordx4 v132, s[100:101]
	s_waitcnt vmcnt(8)
	s_waitcnt lgkmcnt(0)
	s_barrier
	s_setprio 1
	s_waitcnt lgkmcnt(0)
	v_mfma_f32_16x16x32_bf16 v[60:63], v[146:149], v[200:203], v[60:63]
	v_mfma_f32_16x16x32_bf16 v[56:59], v[172:175], v[200:203], v[56:59]
	v_mfma_f32_16x16x32_bf16 v[44:47], v[146:149], v[208:211], v[44:47]
	v_mfma_f32_16x16x32_bf16 v[40:43], v[172:175], v[208:211], v[40:43]
	v_mfma_f32_16x16x32_bf16 v[28:31], v[146:149], v[216:219], v[28:31]
	v_mfma_f32_16x16x32_bf16 v[24:27], v[172:175], v[216:219], v[24:27]
	v_mfma_f32_16x16x32_bf16 v[12:15], v[146:149], v[224:227], v[12:15]
	v_mfma_f32_16x16x32_bf16 v[8:11], v[172:175], v[224:227], v[8:11]
	v_mfma_f32_16x16x32_bf16 v[60:63], v[150:153], v[204:207], v[60:63]
	v_mfma_f32_16x16x32_bf16 v[56:59], v[176:179], v[204:207], v[56:59]
	v_mfma_f32_16x16x32_bf16 v[44:47], v[150:153], v[212:215], v[44:47]
	v_mfma_f32_16x16x32_bf16 v[40:43], v[176:179], v[212:215], v[40:43]
	v_mfma_f32_16x16x32_bf16 v[28:31], v[150:153], v[220:223], v[28:31]
	v_mfma_f32_16x16x32_bf16 v[24:27], v[176:179], v[220:223], v[24:27]
	v_mfma_f32_16x16x32_bf16 v[12:15], v[150:153], v[228:231], v[12:15]
	v_mfma_f32_16x16x32_bf16 v[8:11], v[176:179], v[228:231], v[8:11]
	s_setprio 0
	s_setprio 1
	v_mfma_f32_16x16x32_bf16 v[52:55], v[180:183], v[200:203], v[52:55]
	v_mfma_f32_16x16x32_bf16 v[48:51], v[192:195], v[200:203], v[48:51]
	v_mfma_f32_16x16x32_bf16 v[36:39], v[180:183], v[208:211], v[36:39]
	v_mfma_f32_16x16x32_bf16 v[32:35], v[192:195], v[208:211], v[32:35]
	v_mfma_f32_16x16x32_bf16 v[20:23], v[180:183], v[216:219], v[20:23]
	v_mfma_f32_16x16x32_bf16 v[16:19], v[192:195], v[216:219], v[16:19]
	v_mfma_f32_16x16x32_bf16 v[4:7], v[180:183], v[224:227], v[4:7]
	v_mfma_f32_16x16x32_bf16 v[0:3], v[192:195], v[224:227], v[0:3]
	v_mfma_f32_16x16x32_bf16 v[52:55], v[188:191], v[204:207], v[52:55]
	v_mfma_f32_16x16x32_bf16 v[48:51], v[196:199], v[204:207], v[48:51]
	v_mfma_f32_16x16x32_bf16 v[36:39], v[188:191], v[212:215], v[36:39]
	v_mfma_f32_16x16x32_bf16 v[32:35], v[196:199], v[212:215], v[32:35]
	v_mfma_f32_16x16x32_bf16 v[20:23], v[188:191], v[220:223], v[20:23]
	v_mfma_f32_16x16x32_bf16 v[16:19], v[196:199], v[220:223], v[16:19]
	v_mfma_f32_16x16x32_bf16 v[4:7], v[188:191], v[228:231], v[4:7]
	v_mfma_f32_16x16x32_bf16 v[0:3], v[196:199], v[228:231], v[0:3]
	s_setprio 0
	s_barrier
	s_add_i32 s64, s64, 2
	s_add_u32 s30, s30, 0x100
	s_addc_u32 s31, s31, 0
	s_add_u32 s62, s62, 0x100
	s_addc_u32 s63, s63, 0
	s_cmp_gt_u32 s64, 13
	s_cbranch_scc0 .LBB0_1196
	s_and_b64 vcc, exec, s[10:11]
	s_cbranch_vccz .LBB0_1199
	s_barrier

; #define PG8_STAGE(bufoff, gbase, voff) do { _Pragma("unroll") for (int _i = 0; _i < 2; ++_i) \
;         __builtin_amdgcn_global_load_lds((const unsigned*)((const char*)(gbase) + (voff)[_i]), (PG8_LAS unsigned*)(lds + (bufoff) + ldsw + _i * 8192), 16, 0, 0); } while (0)
; #define PG8_LDA(dst, b, h) do { _Pragma("unroll") for (int m = 0; m < 4; ++m) _Pragma("unroll") for (int k = 0; k < 2; ++k) dst[m][k] = *(const PG8_LAS bf16x8*)(lds + PG8_SA(b, h) + aoff + m * 2048 + k * 1024); } while (0)
; #define PG8_LDB(dst, b, h) do { _Pragma("unroll") for (int n = 0; n < 2; ++n) _Pragma("unroll") for (int k = 0; k < 2; ++k) dst[n][k] = *(const PG8_LAS bf16x8*)(lds + PG8_SB(b, h) + boff + n * 2048 + k * 1024); } while (0)
; #define PG8_MMA(ai, bj, At, Bt) do { __builtin_amdgcn_s_setprio(1); _Pragma("unroll") for (int m = 0; m < 4; ++m) _Pragma("unroll") for (int n = 0; n < 2; ++n) _Pragma("unroll") for (int k = 0; k < 2; ++k) \
;         acc[ai][bj][m][n] = __builtin_amdgcn_mfma_f32_16x16x32_bf16(Bt[n][k], At[m][k], acc[ai][bj][m][n], 0, 0, 0); __builtin_amdgcn_s_setprio(0); } while (0)
; #define PG8_WAIT_V(n) asm volatile("s_waitcnt vmcnt(" #n ")" ::: "memory")
; #define PG8_WAIT_L(n) asm volatile("s_waitcnt lgkmcnt(" #n ")" ::: "memory")
; template <class Epi, class Sched, bool ALIGN_EPI = false, bool SP2 = false>
; __device__ __forceinline__ void gemm_phase(PG8_LAS unsigned char* lds, const Gemm g, const Sched S, const Epi E, const int tid) {
;     ...
;             const bool last = (t == nt - 2);
;             const char* a1 = cA + (size_t)(t + 1) * kstep;
;             const char* a2 = last ? nA : cA + (size_t)(t + 2) * kstep; const char* b2 = last ? nB : cB + (size_t)(t + 2) * kstep;
;             const char* a3 = a2 + kstep; const char* b3 = b2 + kstep;
;             if (last && has_next) S.a_ready(nxt);
;             if constexpr (SP2) {
;             PG8_LDB(B0, 0, 0); PG8_LDB(B1, 0, 1); PG8_SCHED; PG8_LDA(At, 0, 0); PG8_STAGE(PG8_SA(1, 1), a1 + hstepA, voffA);
;             PG8_WAIT_V(8); PG8_WAIT_L(0); PG8_BAR; PG8_MMA(0, 0, At, B0); PG8_MMA(0, 1, At, B1); PG8_BAR; PG8_SCHED;
;             PG8_LDA(At, 0, 1); PG8_STAGE(PG8_SB(0, 0), b2, voffB); PG8_STAGE(PG8_SB(0, 1), b2 + hstepB, voffB); PG8_STAGE(PG8_SA(0, 0), a2, voffA);
;             PG8_WAIT_V(8); PG8_WAIT_L(0); PG8_BAR; PG8_MMA(1, 0, At, B0); PG8_MMA(1, 1, At, B1); PG8_BAR; PG8_SCHED;
.LBB0_1239:
	ds_read_b128 v[150:153], v147
	ds_read_b128 v[166:169], v147 offset:1024
	ds_read_b128 v[170:173], v147 offset:2048
	ds_read_b128 v[174:177], v147 offset:3072
	ds_read_b128 v[178:181], v148
	ds_read_b128 v[182:185], v148 offset:1024
	ds_read_b128 v[188:191], v148 offset:2048
	ds_read_b128 v[192:195], v148 offset:3072
	s_add_u32 s52, s50, 0xfffc0080
	s_addc_u32 s53, s51, -1
	s_cmp_eq_u32 s79, 12
	s_cselect_b32 s55, s37, s53
	s_cselect_b32 s54, s75, s52
	s_cselect_b32 s53, s35, s78
	s_cselect_b32 s52, s76, s77
	s_add_i32 m0, s49, 0xc000
	ds_read_b128 v[196:199], v149
	ds_read_b128 v[200:203], v149 offset:1024
	ds_read_b128 v[204:207], v149 offset:2048
	ds_read_b128 v[208:211], v149 offset:3072
	ds_read_b128 v[212:215], v149 offset:4096
	ds_read_b128 v[216:219], v149 offset:5120
	ds_read_b128 v[220:223], v149 offset:6144
	ds_read_b128 v[224:227], v149 offset:7168
	global_load_lds_dwordx4 v138, s[50:51]
	s_add_i32 m0, s49, 0xe000
	s_nop 0
	global_load_lds_dwordx4 v140, s[50:51]
	s_waitcnt vmcnt(8)
	s_waitcnt lgkmcnt(0)
	s_barrier
	s_setprio 1
	s_waitcnt lgkmcnt(0)
	v_mfma_f32_16x16x32_bf16 v[124:127], v[150:153], v[196:199], v[124:127]
	v_mfma_f32_16x16x32_bf16 v[120:123], v[170:173], v[196:199], v[120:123]
	v_mfma_f32_16x16x32_bf16 v[112:115], v[150:153], v[204:207], v[112:115]
	v_mfma_f32_16x16x32_bf16 v[104:107], v[170:173], v[204:207], v[104:107]
	v_mfma_f32_16x16x32_bf16 v[96:99], v[150:153], v[212:215], v[96:99]
	v_mfma_f32_16x16x32_bf16 v[88:91], v[170:173], v[212:215], v[88:91]
	v_mfma_f32_16x16x32_bf16 v[80:83], v[150:153], v[220:223], v[80:83]
	v_mfma_f32_16x16x32_bf16 v[72:75], v[170:173], v[220:223], v[72:75]
	v_mfma_f32_16x16x32_bf16 v[124:127], v[166:169], v[200:203], v[124:127]
	v_mfma_f32_16x16x32_bf16 v[120:123], v[174:177], v[200:203], v[120:123]
	v_mfma_f32_16x16x32_bf16 v[112:115], v[166:169], v[208:211], v[112:115]
	v_mfma_f32_16x16x32_bf16 v[104:107], v[174:177], v[208:211], v[104:107]
	v_mfma_f32_16x16x32_bf16 v[96:99], v[166:169], v[216:219], v[96:99]
	v_mfma_f32_16x16x32_bf16 v[88:91], v[174:177], v[216:219], v[88:91]
	v_mfma_f32_16x16x32_bf16 v[80:83], v[166:169], v[224:227], v[80:83]
	v_mfma_f32_16x16x32_bf16 v[72:75], v[174:177], v[224:227], v[72:75]
	s_setprio 0
	s_setprio 1
	v_mfma_f32_16x16x32_bf16 v[116:119], v[178:181], v[196:199], v[116:119]
	v_mfma_f32_16x16x32_bf16 v[108:111], v[188:191], v[196:199], v[108:111]
	v_mfma_f32_16x16x32_bf16 v[100:103], v[178:181], v[204:207], v[100:103]
	v_mfma_f32_16x16x32_bf16 v[92:95], v[188:191], v[204:207], v[92:95]
	v_mfma_f32_16x16x32_bf16 v[84:87], v[178:181], v[212:215], v[84:87]
	v_mfma_f32_16x16x32_bf16 v[76:79], v[188:191], v[212:215], v[76:79]
	v_mfma_f32_16x16x32_bf16 v[68:71], v[178:181], v[220:223], v[68:71]
	v_mfma_f32_16x16x32_bf16 v[64:67], v[188:191], v[220:223], v[64:67]
	v_mfma_f32_16x16x32_bf16 v[116:119], v[182:185], v[200:203], v[116:119]
	v_mfma_f32_16x16x32_bf16 v[108:111], v[192:195], v[200:203], v[108:111]
	v_mfma_f32_16x16x32_bf16 v[100:103], v[182:185], v[208:211], v[100:103]
	v_mfma_f32_16x16x32_bf16 v[92:95], v[192:195], v[208:211], v[92:95]
	v_mfma_f32_16x16x32_bf16 v[84:87], v[182:185], v[216:219], v[84:87]
	v_mfma_f32_16x16x32_bf16 v[76:79], v[192:195], v[216:219], v[76:79]
	v_mfma_f32_16x16x32_bf16 v[68:71], v[182:185], v[224:227], v[68:71]
	v_mfma_f32_16x16x32_bf16 v[64:67], v[192:195], v[224:227], v[64:67]
	s_setprio 0
	s_barrier
	s_add_u32 s98, s52, 0x80
	s_addc_u32 s99, s53, 0
	s_add_u32 s100, s54, 0x80
	s_addc_u32 s101, s55, 0
	s_add_i32 s80, s72, s64
	s_mov_b32 m0, s80
	ds_read_b128 v[196:199], v149 offset:16384
	ds_read_b128 v[200:203], v149 offset:17408
	ds_read_b128 v[204:207], v149 offset:18432
	ds_read_b128 v[208:211], v149 offset:19456
	ds_read_b128 v[212:215], v149 offset:20480
	ds_read_b128 v[216:219], v149 offset:21504
	ds_read_b128 v[220:223], v149 offset:22528
	ds_read_b128 v[224:227], v149 offset:23552
	global_load_lds_dwordx4 v130, s[52:53]
	s_add_i32 m0, s80, 0x2000
	s_add_u32 s80, s52, 0x40000
	s_addc_u32 s81, s53, 0
	s_add_i32 s82, s73, s64
	global_load_lds_dwordx4 v134, s[52:53]
	s_mov_b32 m0, s82
	s_nop 0
	global_load_lds_dwordx4 v130, s[80:81]
	s_add_i32 m0, s82, 0x2000
	s_nop 0
	global_load_lds_dwordx4 v134, s[80:81]
	s_mov_b32 m0, s49
	s_nop 0
	global_load_lds_dwordx4 v128, s[54:55]
	s_mov_b32 m0, s65
	s_nop 0
	global_load_lds_dwordx4 v132, s[54:55]
	s_waitcnt vmcnt(8)
	s_waitcnt lgkmcnt(0)
	s_barrier
	s_setprio 1
	s_waitcnt lgkmcnt(0)
	v_mfma_f32_16x16x32_bf16 v[60:63], v[150:153], v[196:199], v[60:63]
	v_mfma_f32_16x16x32_bf16 v[56:59], v[170:173], v[196:199], v[56:59]
	v_mfma_f32_16x16x32_bf16 v[52:55], v[150:153], v[204:207], v[52:55]
	v_mfma_f32_16x16x32_bf16 v[44:47], v[170:173], v[204:207], v[44:47]
	v_mfma_f32_16x16x32_bf16 v[36:39], v[150:153], v[212:215], v[36:39]
	v_mfma_f32_16x16x32_bf16 v[28:31], v[170:173], v[212:215], v[28:31]
	v_mfma_f32_16x16x32_bf16 v[20:23], v[150:153], v[220:223], v[20:23]
	v_mfma_f32_16x16x32_bf16 v[12:15], v[170:173], v[220:223], v[12:15]
	v_mfma_f32_16x16x32_bf16 v[60:63], v[166:169], v[200:203], v[60:63]
	v_mfma_f32_16x16x32_bf16 v[56:59], v[174:177], v[200:203], v[56:59]
	v_mfma_f32_16x16x32_bf16 v[52:55], v[166:169], v[208:211], v[52:55]
	v_mfma_f32_16x16x32_bf16 v[44:47], v[174:177], v[208:211], v[44:47]
	v_mfma_f32_16x16x32_bf16 v[36:39], v[166:169], v[216:219], v[36:39]
	v_mfma_f32_16x16x32_bf16 v[28:31], v[174:177], v[216:219], v[28:31]
	v_mfma_f32_16x16x32_bf16 v[20:23], v[166:169], v[224:227], v[20:23]
	v_mfma_f32_16x16x32_bf16 v[12:15], v[174:177], v[224:227], v[12:15]
	s_setprio 0
	s_setprio 1
	v_mfma_f32_16x16x32_bf16 v[48:51], v[178:181], v[196:199], v[48:51]
	v_mfma_f32_16x16x32_bf16 v[40:43], v[188:191], v[196:199], v[40:43]
	v_mfma_f32_16x16x32_bf16 v[32:35], v[178:181], v[204:207], v[32:35]
	v_mfma_f32_16x16x32_bf16 v[24:27], v[188:191], v[204:207], v[24:27]
	v_mfma_f32_16x16x32_bf16 v[16:19], v[178:181], v[212:215], v[16:19]
	v_mfma_f32_16x16x32_bf16 v[8:11], v[188:191], v[212:215], v[8:11]
	v_mfma_f32_16x16x32_bf16 v[4:7], v[178:181], v[220:223], v[4:7]
	v_mfma_f32_16x16x32_bf16 v[0:3], v[188:191], v[220:223], v[0:3]
	v_mfma_f32_16x16x32_bf16 v[48:51], v[182:185], v[200:203], v[48:51]
	v_mfma_f32_16x16x32_bf16 v[40:43], v[192:195], v[200:203], v[40:43]
	v_mfma_f32_16x16x32_bf16 v[32:35], v[182:185], v[208:211], v[32:35]
	v_mfma_f32_16x16x32_bf16 v[24:27], v[192:195], v[208:211], v[24:27]
	v_mfma_f32_16x16x32_bf16 v[16:19], v[182:185], v[216:219], v[16:19]
	v_mfma_f32_16x16x32_bf16 v[8:11], v[192:195], v[216:219], v[8:11]
	v_mfma_f32_16x16x32_bf16 v[4:7], v[182:185], v[224:227], v[4:7]
	v_mfma_f32_16x16x32_bf16 v[0:3], v[192:195], v[224:227], v[0:3]
	s_setprio 0
	s_barrier
; #define PG8_STAGE(bufoff, gbase, voff) do { _Pragma("unroll") for (int _i = 0; _i < 2; ++_i) \
;         __builtin_amdgcn_global_load_lds((const unsigned*)((const char*)(gbase) + (voff)[_i]), (PG8_LAS unsigned*)(lds + (bufoff) + ldsw + _i * 8192), 16, 0, 0); } while (0)
; #define PG8_LDA(dst, b, h) do { _Pragma("unroll") for (int m = 0; m < 4; ++m) _Pragma("unroll") for (int k = 0; k < 2; ++k) dst[m][k] = *(const PG8_LAS bf16x8*)(lds + PG8_SA(b, h) + aoff + m * 2048 + k * 1024); } while (0)
; #define PG8_LDB(dst, b, h) do { _Pragma("unroll") for (int n = 0; n < 2; ++n) _Pragma("unroll") for (int k = 0; k < 2; ++k) dst[n][k] = *(const PG8_LAS bf16x8*)(lds + PG8_SB(b, h) + boff + n * 2048 + k * 1024); } while (0)
; #define PG8_MMA(ai, bj, At, Bt) do { __builtin_amdgcn_s_setprio(1); _Pragma("unroll") for (int m = 0; m < 4; ++m) _Pragma("unroll") for (int n = 0; n < 2; ++n) _Pragma("unroll") for (int k = 0; k < 2; ++k) \
;         acc[ai][bj][m][n] = __builtin_amdgcn_mfma_f32_16x16x32_bf16(Bt[n][k], At[m][k], acc[ai][bj][m][n], 0, 0, 0); __builtin_amdgcn_s_setprio(0); } while (0)
; #define PG8_WAIT_V(n) asm volatile("s_waitcnt vmcnt(" #n ")" ::: "memory")
; #define PG8_WAIT_L(n) asm volatile("s_waitcnt lgkmcnt(" #n ")" ::: "memory")
; #define PG8_BAR __builtin_amdgcn_s_barrier()
; #define PG8_SCHED __builtin_amdgcn_sched_barrier(0)
; template <class Epi, class Sched, bool ALIGN_EPI = false, bool SP2 = false>
; __device__ __forceinline__ void gemm_phase(PG8_LAS unsigned char* lds, const Gemm g, const Sched S, const Epi E, const int tid) {
;     ...
;         for (int t = 0; t < nt; t += 2) {
;     ...
;             PG8_LDB(B0, 1, 0); PG8_LDB(B1, 1, 1); PG8_SCHED; PG8_LDA(At, 1, 0); PG8_STAGE(PG8_SA(0, 1), a2 + hstepA, voffA);
;             PG8_WAIT_V(8); PG8_WAIT_L(0); PG8_BAR; PG8_MMA(0, 0, At, B0); PG8_MMA(0, 1, At, B1); PG8_BAR; PG8_SCHED;
;             PG8_LDA(At, 1, 1); PG8_STAGE(PG8_SB(1, 0), b3, voffB); PG8_STAGE(PG8_SB(1, 1), b3 + hstepB, voffB); PG8_STAGE(PG8_SA(1, 0), a3, voffA);
;             PG8_WAIT_V(8); PG8_WAIT_L(0); PG8_BAR; PG8_MMA(1, 0, At, B0); PG8_MMA(1, 1, At, B1); PG8_BAR; PG8_SCHED;
	s_add_i32 s80, 0, 0x18000
	v_add_u32_e32 v165, s80, v145
	s_add_i32 s81, 0, 0x1c000
	ds_read_b128 v[150:153], v165
	ds_read_b128 v[166:169], v165 offset:1024
	ds_read_b128 v[170:173], v165 offset:2048
	ds_read_b128 v[174:177], v165 offset:3072
	v_add_u32_e32 v165, s81, v145
	ds_read_b128 v[178:181], v165
	ds_read_b128 v[182:185], v165 offset:1024
	ds_read_b128 v[188:191], v165 offset:2048
	ds_read_b128 v[192:195], v165 offset:3072
	s_add_u32 s54, s54, 0x40000
	s_addc_u32 s55, s55, 0
	s_mov_b32 m0, s66
	ds_read_b128 v[196:199], v149 offset:32768
	ds_read_b128 v[200:203], v149 offset:33792
	ds_read_b128 v[204:207], v149 offset:34816
	ds_read_b128 v[208:211], v149 offset:35840
	ds_read_b128 v[212:215], v149 offset:36864
	ds_read_b128 v[216:219], v149 offset:37888
	ds_read_b128 v[220:223], v149 offset:38912
	ds_read_b128 v[224:227], v149 offset:39936
	global_load_lds_dwordx4 v128, s[54:55]
	s_mov_b32 m0, s67
	s_nop 0
	global_load_lds_dwordx4 v132, s[54:55]
	s_waitcnt vmcnt(8)
	s_waitcnt lgkmcnt(0)
	s_barrier
	s_setprio 1
	s_waitcnt lgkmcnt(0)
	v_mfma_f32_16x16x32_bf16 v[124:127], v[150:153], v[196:199], v[124:127]
	v_mfma_f32_16x16x32_bf16 v[120:123], v[170:173], v[196:199], v[120:123]
	v_mfma_f32_16x16x32_bf16 v[112:115], v[150:153], v[204:207], v[112:115]
	v_mfma_f32_16x16x32_bf16 v[104:107], v[170:173], v[204:207], v[104:107]
	v_mfma_f32_16x16x32_bf16 v[96:99], v[150:153], v[212:215], v[96:99]
	v_mfma_f32_16x16x32_bf16 v[88:91], v[170:173], v[212:215], v[88:91]
	v_mfma_f32_16x16x32_bf16 v[80:83], v[150:153], v[220:223], v[80:83]
	v_mfma_f32_16x16x32_bf16 v[72:75], v[170:173], v[220:223], v[72:75]
	v_mfma_f32_16x16x32_bf16 v[124:127], v[166:169], v[200:203], v[124:127]
	v_mfma_f32_16x16x32_bf16 v[120:123], v[174:177], v[200:203], v[120:123]
	v_mfma_f32_16x16x32_bf16 v[112:115], v[166:169], v[208:211], v[112:115]
	v_mfma_f32_16x16x32_bf16 v[104:107], v[174:177], v[208:211], v[104:107]
	v_mfma_f32_16x16x32_bf16 v[96:99], v[166:169], v[216:219], v[96:99]
	v_mfma_f32_16x16x32_bf16 v[88:91], v[174:177], v[216:219], v[88:91]
	v_mfma_f32_16x16x32_bf16 v[80:83], v[166:169], v[224:227], v[80:83]
	v_mfma_f32_16x16x32_bf16 v[72:75], v[174:177], v[224:227], v[72:75]
	s_setprio 0
	s_setprio 1
	v_mfma_f32_16x16x32_bf16 v[116:119], v[178:181], v[196:199], v[116:119]
	v_mfma_f32_16x16x32_bf16 v[108:111], v[188:191], v[196:199], v[108:111]
	v_mfma_f32_16x16x32_bf16 v[100:103], v[178:181], v[204:207], v[100:103]
	v_mfma_f32_16x16x32_bf16 v[92:95], v[188:191], v[204:207], v[92:95]
	v_mfma_f32_16x16x32_bf16 v[84:87], v[178:181], v[212:215], v[84:87]
	v_mfma_f32_16x16x32_bf16 v[76:79], v[188:191], v[212:215], v[76:79]
	v_mfma_f32_16x16x32_bf16 v[68:71], v[178:181], v[220:223], v[68:71]
	v_mfma_f32_16x16x32_bf16 v[64:67], v[188:191], v[220:223], v[64:67]
	v_mfma_f32_16x16x32_bf16 v[116:119], v[182:185], v[200:203], v[116:119]
	v_mfma_f32_16x16x32_bf16 v[108:111], v[192:195], v[200:203], v[108:111]
	v_mfma_f32_16x16x32_bf16 v[100:103], v[182:185], v[208:211], v[100:103]
	v_mfma_f32_16x16x32_bf16 v[92:95], v[192:195], v[208:211], v[92:95]
	v_mfma_f32_16x16x32_bf16 v[84:87], v[182:185], v[216:219], v[84:87]
	v_mfma_f32_16x16x32_bf16 v[76:79], v[192:195], v[216:219], v[76:79]
	v_mfma_f32_16x16x32_bf16 v[68:71], v[182:185], v[224:227], v[68:71]
	v_mfma_f32_16x16x32_bf16 v[64:67], v[192:195], v[224:227], v[64:67]
	s_setprio 0
	s_barrier
	s_add_i32 s54, s80, s64
	s_mov_b32 m0, s54
	ds_read_b128 v[196:199], v149 offset:49152
	ds_read_b128 v[200:203], v149 offset:50176
	ds_read_b128 v[204:207], v149 offset:51200
	ds_read_b128 v[208:211], v149 offset:52224
	ds_read_b128 v[212:215], v149 offset:53248
	ds_read_b128 v[216:219], v149 offset:54272
	ds_read_b128 v[220:223], v149 offset:55296
	ds_read_b128 v[224:227], v149 offset:56320
	global_load_lds_dwordx4 v130, s[98:99]
	s_add_i32 m0, s54, 0x2000
	s_add_u32 s52, s52, 0x40080
	s_addc_u32 s53, s53, 0
	s_add_i32 s54, s81, s64
	global_load_lds_dwordx4 v134, s[98:99]
	s_mov_b32 m0, s54
	s_nop 0
	global_load_lds_dwordx4 v130, s[52:53]
	s_add_i32 m0, s54, 0x2000
	s_nop 0
	global_load_lds_dwordx4 v134, s[52:53]
	s_mov_b32 m0, s70
	s_nop 0
	global_load_lds_dwordx4 v128, s[100:101]
	s_mov_b32 m0, s71
	s_nop 0
	global_load_lds_dwordx4 v132, s[100:101]
	s_waitcnt vmcnt(8)
	s_waitcnt lgkmcnt(0)
	s_barrier
	s_setprio 1
	s_waitcnt lgkmcnt(0)
	v_mfma_f32_16x16x32_bf16 v[60:63], v[150:153], v[196:199], v[60:63]
	v_mfma_f32_16x16x32_bf16 v[56:59], v[170:173], v[196:199], v[56:59]
	v_mfma_f32_16x16x32_bf16 v[52:55], v[150:153], v[204:207], v[52:55]
	v_mfma_f32_16x16x32_bf16 v[44:47], v[170:173], v[204:207], v[44:47]
	v_mfma_f32_16x16x32_bf16 v[36:39], v[150:153], v[212:215], v[36:39]
	v_mfma_f32_16x16x32_bf16 v[28:31], v[170:173], v[212:215], v[28:31]
	v_mfma_f32_16x16x32_bf16 v[20:23], v[150:153], v[220:223], v[20:23]
	v_mfma_f32_16x16x32_bf16 v[12:15], v[170:173], v[220:223], v[12:15]
	v_mfma_f32_16x16x32_bf16 v[60:63], v[166:169], v[200:203], v[60:63]
	v_mfma_f32_16x16x32_bf16 v[56:59], v[174:177], v[200:203], v[56:59]
	v_mfma_f32_16x16x32_bf16 v[52:55], v[166:169], v[208:211], v[52:55]
	v_mfma_f32_16x16x32_bf16 v[44:47], v[174:177], v[208:211], v[44:47]
	v_mfma_f32_16x16x32_bf16 v[36:39], v[166:169], v[216:219], v[36:39]
	v_mfma_f32_16x16x32_bf16 v[28:31], v[174:177], v[216:219], v[28:31]
	v_mfma_f32_16x16x32_bf16 v[20:23], v[166:169], v[224:227], v[20:23]
	v_mfma_f32_16x16x32_bf16 v[12:15], v[174:177], v[224:227], v[12:15]
	s_setprio 0
	s_setprio 1
	v_mfma_f32_16x16x32_bf16 v[48:51], v[178:181], v[196:199], v[48:51]
	v_mfma_f32_16x16x32_bf16 v[40:43], v[188:191], v[196:199], v[40:43]
	v_mfma_f32_16x16x32_bf16 v[32:35], v[178:181], v[204:207], v[32:35]
	v_mfma_f32_16x16x32_bf16 v[24:27], v[188:191], v[204:207], v[24:27]
	v_mfma_f32_16x16x32_bf16 v[16:19], v[178:181], v[212:215], v[16:19]
	v_mfma_f32_16x16x32_bf16 v[8:11], v[188:191], v[212:215], v[8:11]
	v_mfma_f32_16x16x32_bf16 v[4:7], v[178:181], v[220:223], v[4:7]
	v_mfma_f32_16x16x32_bf16 v[0:3], v[188:191], v[220:223], v[0:3]
	v_mfma_f32_16x16x32_bf16 v[48:51], v[182:185], v[200:203], v[48:51]
	v_mfma_f32_16x16x32_bf16 v[40:43], v[192:195], v[200:203], v[40:43]
	v_mfma_f32_16x16x32_bf16 v[32:35], v[182:185], v[208:211], v[32:35]
	v_mfma_f32_16x16x32_bf16 v[24:27], v[192:195], v[208:211], v[24:27]
	v_mfma_f32_16x16x32_bf16 v[16:19], v[182:185], v[216:219], v[16:19]
	v_mfma_f32_16x16x32_bf16 v[8:11], v[192:195], v[216:219], v[8:11]
	v_mfma_f32_16x16x32_bf16 v[4:7], v[182:185], v[224:227], v[4:7]
	v_mfma_f32_16x16x32_bf16 v[0:3], v[192:195], v[224:227], v[0:3]
	s_setprio 0
	s_barrier
	s_add_i32 s79, s79, 2
	s_add_u32 s50, s50, 0x100
	s_addc_u32 s51, s51, 0
	s_add_u32 s77, s77, 0x100
	s_addc_u32 s78, s78, 0
	s_cmp_gt_u32 s79, 13
	s_cbranch_scc0 .LBB0_1239
	s_and_b64 vcc, exec, s[10:11]
	s_cbranch_vccz .LBB0_1242
	s_barrier

; #define PG8_STAGE(bufoff, gbase, voff) do { _Pragma("unroll") for (int _i = 0; _i < 2; ++_i) \
;         __builtin_amdgcn_global_load_lds((const unsigned*)((const char*)(gbase) + (voff)[_i]), (PG8_LAS unsigned*)(lds + (bufoff) + ldsw + _i * 8192), 16, 0, 0); } while (0)
; #define PG8_LDA(dst, b, h) do { _Pragma("unroll") for (int m = 0; m < 4; ++m) _Pragma("unroll") for (int k = 0; k < 2; ++k) dst[m][k] = *(const PG8_LAS bf16x8*)(lds + PG8_SA(b, h) + aoff + m * 2048 + k * 1024); } while (0)
; #define PG8_LDB(dst, b, h) do { _Pragma("unroll") for (int n = 0; n < 2; ++n) _Pragma("unroll") for (int k = 0; k < 2; ++k) dst[n][k] = *(const PG8_LAS bf16x8*)(lds + PG8_SB(b, h) + boff + n * 2048 + k * 1024); } while (0)
; #define PG8_MMA(ai, bj, At, Bt) do { __builtin_amdgcn_s_setprio(1); _Pragma("unroll") for (int m = 0; m < 4; ++m) _Pragma("unroll") for (int n = 0; n < 2; ++n) _Pragma("unroll") for (int k = 0; k < 2; ++k) \
;         acc[ai][bj][m][n] = __builtin_amdgcn_mfma_f32_16x16x32_bf16(Bt[n][k], At[m][k], acc[ai][bj][m][n], 0, 0, 0); __builtin_amdgcn_s_setprio(0); } while (0)
; #define PG8_WAIT_V(n) asm volatile("s_waitcnt vmcnt(" #n ")" ::: "memory")
; #define PG8_WAIT_L(n) asm volatile("s_waitcnt lgkmcnt(" #n ")" ::: "memory")
; template <class Epi, class Sched, bool ALIGN_EPI = false, bool SP2 = false>
; __device__ __forceinline__ void gemm_phase(PG8_LAS unsigned char* lds, const Gemm g, const Sched S, const Epi E, const int tid) {
;     ...
;             const bool last = (t == nt - 2);
;             const char* a1 = cA + (size_t)(t + 1) * kstep;
;             const char* a2 = last ? nA : cA + (size_t)(t + 2) * kstep; const char* b2 = last ? nB : cB + (size_t)(t + 2) * kstep;
;             const char* a3 = a2 + kstep; const char* b3 = b2 + kstep;
;             if (last && has_next) S.a_ready(nxt);
;             if constexpr (SP2) {
;             PG8_LDB(B0, 0, 0); PG8_LDB(B1, 0, 1); PG8_SCHED; PG8_LDA(At, 0, 0); PG8_STAGE(PG8_SA(1, 1), a1 + hstepA, voffA);
;             PG8_WAIT_V(8); PG8_WAIT_L(0); PG8_BAR; PG8_MMA(0, 0, At, B0); PG8_MMA(0, 1, At, B1); PG8_BAR; PG8_SCHED;
;             PG8_LDA(At, 0, 1); PG8_STAGE(PG8_SB(0, 0), b2, voffB); PG8_STAGE(PG8_SB(0, 1), b2 + hstepB, voffB); PG8_STAGE(PG8_SA(0, 0), a2, voffA);
;             PG8_WAIT_V(8); PG8_WAIT_L(0); PG8_BAR; PG8_MMA(1, 0, At, B0); PG8_MMA(1, 1, At, B1); PG8_BAR; PG8_SCHED;
.LBB0_1255:
	ds_read_b128 v[148:151], v145
	ds_read_b128 v[152:155], v145 offset:1024
	ds_read_b128 v[156:159], v145 offset:2048
	ds_read_b128 v[160:163], v145 offset:3072
	ds_read_b128 v[164:167], v146
	ds_read_b128 v[168:171], v146 offset:1024
	ds_read_b128 v[172:175], v146 offset:2048
	ds_read_b128 v[176:179], v146 offset:3072
	s_add_u32 s52, s50, 0xfffc0080
	s_addc_u32 s53, s51, -1
	s_cmp_eq_u32 s76, 12
	s_cselect_b32 s55, s37, s53
	s_cselect_b32 s54, s72, s52
	s_cselect_b32 s53, s35, s75
	s_cselect_b32 s52, s73, s74
	s_add_i32 m0, s49, 0xc000
	ds_read_b128 v[180:183], v147
	ds_read_b128 v[188:191], v147 offset:1024
	ds_read_b128 v[192:195], v147 offset:2048
	ds_read_b128 v[196:199], v147 offset:3072
	ds_read_b128 v[200:203], v147 offset:4096
	ds_read_b128 v[204:207], v147 offset:5120
	ds_read_b128 v[208:211], v147 offset:6144
	ds_read_b128 v[212:215], v147 offset:7168
	global_load_lds_dwordx4 v136, s[50:51]
	s_add_i32 m0, s49, 0xe000
	s_nop 0
	global_load_lds_dwordx4 v138, s[50:51]
	s_waitcnt vmcnt(8)
	s_waitcnt lgkmcnt(0)
	s_barrier
	s_setprio 1
	s_waitcnt lgkmcnt(0)
	v_mfma_f32_16x16x32_bf16 v[124:127], v[148:151], v[180:183], v[124:127]
	v_mfma_f32_16x16x32_bf16 v[120:123], v[156:159], v[180:183], v[120:123]
	v_mfma_f32_16x16x32_bf16 v[112:115], v[148:151], v[192:195], v[112:115]
	v_mfma_f32_16x16x32_bf16 v[104:107], v[156:159], v[192:195], v[104:107]
	v_mfma_f32_16x16x32_bf16 v[96:99], v[148:151], v[200:203], v[96:99]
	v_mfma_f32_16x16x32_bf16 v[88:91], v[156:159], v[200:203], v[88:91]
	v_mfma_f32_16x16x32_bf16 v[80:83], v[148:151], v[208:211], v[80:83]
	v_mfma_f32_16x16x32_bf16 v[72:75], v[156:159], v[208:211], v[72:75]
	v_mfma_f32_16x16x32_bf16 v[124:127], v[152:155], v[188:191], v[124:127]
	v_mfma_f32_16x16x32_bf16 v[120:123], v[160:163], v[188:191], v[120:123]
	v_mfma_f32_16x16x32_bf16 v[112:115], v[152:155], v[196:199], v[112:115]
	v_mfma_f32_16x16x32_bf16 v[104:107], v[160:163], v[196:199], v[104:107]
	v_mfma_f32_16x16x32_bf16 v[96:99], v[152:155], v[204:207], v[96:99]
	v_mfma_f32_16x16x32_bf16 v[88:91], v[160:163], v[204:207], v[88:91]
	v_mfma_f32_16x16x32_bf16 v[80:83], v[152:155], v[212:215], v[80:83]
	v_mfma_f32_16x16x32_bf16 v[72:75], v[160:163], v[212:215], v[72:75]
	s_setprio 0
	s_setprio 1
	v_mfma_f32_16x16x32_bf16 v[116:119], v[164:167], v[180:183], v[116:119]
	v_mfma_f32_16x16x32_bf16 v[108:111], v[172:175], v[180:183], v[108:111]
	v_mfma_f32_16x16x32_bf16 v[100:103], v[164:167], v[192:195], v[100:103]
	v_mfma_f32_16x16x32_bf16 v[92:95], v[172:175], v[192:195], v[92:95]
	v_mfma_f32_16x16x32_bf16 v[84:87], v[164:167], v[200:203], v[84:87]
	v_mfma_f32_16x16x32_bf16 v[76:79], v[172:175], v[200:203], v[76:79]
	v_mfma_f32_16x16x32_bf16 v[68:71], v[164:167], v[208:211], v[68:71]
	v_mfma_f32_16x16x32_bf16 v[64:67], v[172:175], v[208:211], v[64:67]
	v_mfma_f32_16x16x32_bf16 v[116:119], v[168:171], v[188:191], v[116:119]
	v_mfma_f32_16x16x32_bf16 v[108:111], v[176:179], v[188:191], v[108:111]
	v_mfma_f32_16x16x32_bf16 v[100:103], v[168:171], v[196:199], v[100:103]
	v_mfma_f32_16x16x32_bf16 v[92:95], v[176:179], v[196:199], v[92:95]
	v_mfma_f32_16x16x32_bf16 v[84:87], v[168:171], v[204:207], v[84:87]
	v_mfma_f32_16x16x32_bf16 v[76:79], v[176:179], v[204:207], v[76:79]
	v_mfma_f32_16x16x32_bf16 v[68:71], v[168:171], v[212:215], v[68:71]
	v_mfma_f32_16x16x32_bf16 v[64:67], v[176:179], v[212:215], v[64:67]
	s_setprio 0
	s_barrier
	s_add_u32 s98, s52, 0x80
	s_addc_u32 s99, s53, 0
	s_add_u32 s100, s54, 0x80
	s_addc_u32 s101, s55, 0
	s_add_i32 s77, s69, s61
	s_mov_b32 m0, s77
	ds_read_b128 v[180:183], v147 offset:16384
	ds_read_b128 v[188:191], v147 offset:17408
	ds_read_b128 v[192:195], v147 offset:18432
	ds_read_b128 v[196:199], v147 offset:19456
	ds_read_b128 v[200:203], v147 offset:20480
	ds_read_b128 v[204:207], v147 offset:21504
	ds_read_b128 v[208:211], v147 offset:22528
	ds_read_b128 v[212:215], v147 offset:23552
	global_load_lds_dwordx4 v130, s[52:53]
	s_add_i32 m0, s77, 0x2000
	s_add_u32 s78, s52, 0x40000
	s_addc_u32 s79, s53, 0
	s_add_i32 s77, s70, s61
	global_load_lds_dwordx4 v134, s[52:53]
	s_mov_b32 m0, s77
	s_nop 0
	global_load_lds_dwordx4 v130, s[78:79]
	s_add_i32 m0, s77, 0x2000
	s_nop 0
	global_load_lds_dwordx4 v134, s[78:79]
	s_mov_b32 m0, s49
	s_nop 0
	global_load_lds_dwordx4 v128, s[54:55]
	s_mov_b32 m0, s62
	s_nop 0
	global_load_lds_dwordx4 v132, s[54:55]
	s_waitcnt vmcnt(8)
	s_waitcnt lgkmcnt(0)
	s_barrier
	s_setprio 1
	s_waitcnt lgkmcnt(0)
	v_mfma_f32_16x16x32_bf16 v[60:63], v[148:151], v[180:183], v[60:63]
	v_mfma_f32_16x16x32_bf16 v[56:59], v[156:159], v[180:183], v[56:59]
	v_mfma_f32_16x16x32_bf16 v[52:55], v[148:151], v[192:195], v[52:55]
	v_mfma_f32_16x16x32_bf16 v[44:47], v[156:159], v[192:195], v[44:47]
	v_mfma_f32_16x16x32_bf16 v[36:39], v[148:151], v[200:203], v[36:39]
	v_mfma_f32_16x16x32_bf16 v[28:31], v[156:159], v[200:203], v[28:31]
	v_mfma_f32_16x16x32_bf16 v[20:23], v[148:151], v[208:211], v[20:23]
	v_mfma_f32_16x16x32_bf16 v[12:15], v[156:159], v[208:211], v[12:15]
	v_mfma_f32_16x16x32_bf16 v[60:63], v[152:155], v[188:191], v[60:63]
	v_mfma_f32_16x16x32_bf16 v[56:59], v[160:163], v[188:191], v[56:59]
	v_mfma_f32_16x16x32_bf16 v[52:55], v[152:155], v[196:199], v[52:55]
	v_mfma_f32_16x16x32_bf16 v[44:47], v[160:163], v[196:199], v[44:47]
	v_mfma_f32_16x16x32_bf16 v[36:39], v[152:155], v[204:207], v[36:39]
	v_mfma_f32_16x16x32_bf16 v[28:31], v[160:163], v[204:207], v[28:31]
	v_mfma_f32_16x16x32_bf16 v[20:23], v[152:155], v[212:215], v[20:23]
	v_mfma_f32_16x16x32_bf16 v[12:15], v[160:163], v[212:215], v[12:15]
	s_setprio 0
	s_setprio 1
	v_mfma_f32_16x16x32_bf16 v[48:51], v[164:167], v[180:183], v[48:51]
	v_mfma_f32_16x16x32_bf16 v[40:43], v[172:175], v[180:183], v[40:43]
	v_mfma_f32_16x16x32_bf16 v[32:35], v[164:167], v[192:195], v[32:35]
	v_mfma_f32_16x16x32_bf16 v[24:27], v[172:175], v[192:195], v[24:27]
	v_mfma_f32_16x16x32_bf16 v[16:19], v[164:167], v[200:203], v[16:19]
	v_mfma_f32_16x16x32_bf16 v[8:11], v[172:175], v[200:203], v[8:11]
	v_mfma_f32_16x16x32_bf16 v[4:7], v[164:167], v[208:211], v[4:7]
	v_mfma_f32_16x16x32_bf16 v[0:3], v[172:175], v[208:211], v[0:3]
	v_mfma_f32_16x16x32_bf16 v[48:51], v[168:171], v[188:191], v[48:51]
	v_mfma_f32_16x16x32_bf16 v[40:43], v[176:179], v[188:191], v[40:43]
	v_mfma_f32_16x16x32_bf16 v[32:35], v[168:171], v[196:199], v[32:35]
	v_mfma_f32_16x16x32_bf16 v[24:27], v[176:179], v[196:199], v[24:27]
	v_mfma_f32_16x16x32_bf16 v[16:19], v[168:171], v[204:207], v[16:19]
	v_mfma_f32_16x16x32_bf16 v[8:11], v[176:179], v[204:207], v[8:11]
	v_mfma_f32_16x16x32_bf16 v[4:7], v[168:171], v[212:215], v[4:7]
	v_mfma_f32_16x16x32_bf16 v[0:3], v[176:179], v[212:215], v[0:3]
	s_setprio 0
	s_barrier
; #define PG8_STAGE(bufoff, gbase, voff) do { _Pragma("unroll") for (int _i = 0; _i < 2; ++_i) \
;         __builtin_amdgcn_global_load_lds((const unsigned*)((const char*)(gbase) + (voff)[_i]), (PG8_LAS unsigned*)(lds + (bufoff) + ldsw + _i * 8192), 16, 0, 0); } while (0)
; #define PG8_LDA(dst, b, h) do { _Pragma("unroll") for (int m = 0; m < 4; ++m) _Pragma("unroll") for (int k = 0; k < 2; ++k) dst[m][k] = *(const PG8_LAS bf16x8*)(lds + PG8_SA(b, h) + aoff + m * 2048 + k * 1024); } while (0)
; #define PG8_LDB(dst, b, h) do { _Pragma("unroll") for (int n = 0; n < 2; ++n) _Pragma("unroll") for (int k = 0; k < 2; ++k) dst[n][k] = *(const PG8_LAS bf16x8*)(lds + PG8_SB(b, h) + boff + n * 2048 + k * 1024); } while (0)
; #define PG8_MMA(ai, bj, At, Bt) do { __builtin_amdgcn_s_setprio(1); _Pragma("unroll") for (int m = 0; m < 4; ++m) _Pragma("unroll") for (int n = 0; n < 2; ++n) _Pragma("unroll") for (int k = 0; k < 2; ++k) \
;         acc[ai][bj][m][n] = __builtin_amdgcn_mfma_f32_16x16x32_bf16(Bt[n][k], At[m][k], acc[ai][bj][m][n], 0, 0, 0); __builtin_amdgcn_s_setprio(0); } while (0)
; #define PG8_WAIT_V(n) asm volatile("s_waitcnt vmcnt(" #n ")" ::: "memory")
; #define PG8_WAIT_L(n) asm volatile("s_waitcnt lgkmcnt(" #n ")" ::: "memory")
; #define PG8_BAR __builtin_amdgcn_s_barrier()
; #define PG8_SCHED __builtin_amdgcn_sched_barrier(0)
; template <class Epi, class Sched, bool ALIGN_EPI = false, bool SP2 = false>
; __device__ __forceinline__ void gemm_phase(PG8_LAS unsigned char* lds, const Gemm g, const Sched S, const Epi E, const int tid) {
;     ...
;         for (int t = 0; t < nt; t += 2) {
;     ...
;             PG8_LDB(B0, 1, 0); PG8_LDB(B1, 1, 1); PG8_SCHED; PG8_LDA(At, 1, 0); PG8_STAGE(PG8_SA(0, 1), a2 + hstepA, voffA);
;             PG8_WAIT_V(8); PG8_WAIT_L(0); PG8_BAR; PG8_MMA(0, 0, At, B0); PG8_MMA(0, 1, At, B1); PG8_BAR; PG8_SCHED;
;             PG8_LDA(At, 1, 1); PG8_STAGE(PG8_SB(1, 0), b3, voffB); PG8_STAGE(PG8_SB(1, 1), b3 + hstepB, voffB); PG8_STAGE(PG8_SA(1, 0), a3, voffA);
;             PG8_WAIT_V(8); PG8_WAIT_L(0); PG8_BAR; PG8_MMA(1, 0, At, B0); PG8_MMA(1, 1, At, B1); PG8_BAR; PG8_SCHED;
	s_add_i32 s77, 0, 0x18000
	s_add_i32 s78, 0, 0x1c000
	v_add_u32_e32 v160, s77, v143
	v_add_u32_e32 v176, s78, v143
	ds_read_b128 v[148:151], v160
	ds_read_b128 v[152:155], v160 offset:1024
	ds_read_b128 v[156:159], v160 offset:2048
	ds_read_b128 v[160:163], v160 offset:3072
	ds_read_b128 v[164:167], v176
	ds_read_b128 v[168:171], v176 offset:1024
	ds_read_b128 v[172:175], v176 offset:2048
	ds_read_b128 v[176:179], v176 offset:3072
	s_add_u32 s54, s54, 0x40000
	s_addc_u32 s55, s55, 0
	s_mov_b32 m0, s63
	ds_read_b128 v[180:183], v147 offset:32768
	ds_read_b128 v[188:191], v147 offset:33792
	ds_read_b128 v[192:195], v147 offset:34816
	ds_read_b128 v[196:199], v147 offset:35840
	ds_read_b128 v[200:203], v147 offset:36864
	ds_read_b128 v[204:207], v147 offset:37888
	ds_read_b128 v[208:211], v147 offset:38912
	ds_read_b128 v[212:215], v147 offset:39936
	global_load_lds_dwordx4 v128, s[54:55]
	s_mov_b32 m0, s64
	s_nop 0
	global_load_lds_dwordx4 v132, s[54:55]
	s_waitcnt vmcnt(8)
	s_waitcnt lgkmcnt(0)
	s_barrier
	s_setprio 1
	s_waitcnt lgkmcnt(0)
	v_mfma_f32_16x16x32_bf16 v[124:127], v[148:151], v[180:183], v[124:127]
	v_mfma_f32_16x16x32_bf16 v[120:123], v[156:159], v[180:183], v[120:123]
	v_mfma_f32_16x16x32_bf16 v[112:115], v[148:151], v[192:195], v[112:115]
	v_mfma_f32_16x16x32_bf16 v[104:107], v[156:159], v[192:195], v[104:107]
	v_mfma_f32_16x16x32_bf16 v[96:99], v[148:151], v[200:203], v[96:99]
	v_mfma_f32_16x16x32_bf16 v[88:91], v[156:159], v[200:203], v[88:91]
	v_mfma_f32_16x16x32_bf16 v[80:83], v[148:151], v[208:211], v[80:83]
	v_mfma_f32_16x16x32_bf16 v[72:75], v[156:159], v[208:211], v[72:75]
	v_mfma_f32_16x16x32_bf16 v[124:127], v[152:155], v[188:191], v[124:127]
	v_mfma_f32_16x16x32_bf16 v[120:123], v[160:163], v[188:191], v[120:123]
	v_mfma_f32_16x16x32_bf16 v[112:115], v[152:155], v[196:199], v[112:115]
	v_mfma_f32_16x16x32_bf16 v[104:107], v[160:163], v[196:199], v[104:107]
	v_mfma_f32_16x16x32_bf16 v[96:99], v[152:155], v[204:207], v[96:99]
	v_mfma_f32_16x16x32_bf16 v[88:91], v[160:163], v[204:207], v[88:91]
	v_mfma_f32_16x16x32_bf16 v[80:83], v[152:155], v[212:215], v[80:83]
	v_mfma_f32_16x16x32_bf16 v[72:75], v[160:163], v[212:215], v[72:75]
	s_setprio 0
	s_setprio 1
	v_mfma_f32_16x16x32_bf16 v[116:119], v[164:167], v[180:183], v[116:119]
	v_mfma_f32_16x16x32_bf16 v[108:111], v[172:175], v[180:183], v[108:111]
	v_mfma_f32_16x16x32_bf16 v[100:103], v[164:167], v[192:195], v[100:103]
	v_mfma_f32_16x16x32_bf16 v[92:95], v[172:175], v[192:195], v[92:95]
	v_mfma_f32_16x16x32_bf16 v[84:87], v[164:167], v[200:203], v[84:87]
	v_mfma_f32_16x16x32_bf16 v[76:79], v[172:175], v[200:203], v[76:79]
	v_mfma_f32_16x16x32_bf16 v[68:71], v[164:167], v[208:211], v[68:71]
	v_mfma_f32_16x16x32_bf16 v[64:67], v[172:175], v[208:211], v[64:67]
	v_mfma_f32_16x16x32_bf16 v[116:119], v[168:171], v[188:191], v[116:119]
	v_mfma_f32_16x16x32_bf16 v[108:111], v[176:179], v[188:191], v[108:111]
	v_mfma_f32_16x16x32_bf16 v[100:103], v[168:171], v[196:199], v[100:103]
	v_mfma_f32_16x16x32_bf16 v[92:95], v[176:179], v[196:199], v[92:95]
	v_mfma_f32_16x16x32_bf16 v[84:87], v[168:171], v[204:207], v[84:87]
	v_mfma_f32_16x16x32_bf16 v[76:79], v[176:179], v[204:207], v[76:79]
	v_mfma_f32_16x16x32_bf16 v[68:71], v[168:171], v[212:215], v[68:71]
	v_mfma_f32_16x16x32_bf16 v[64:67], v[176:179], v[212:215], v[64:67]
	s_setprio 0
	s_barrier
	s_add_i32 s54, s77, s61
	s_mov_b32 m0, s54
	ds_read_b128 v[180:183], v147 offset:49152
	ds_read_b128 v[188:191], v147 offset:50176
	ds_read_b128 v[192:195], v147 offset:51200
	ds_read_b128 v[196:199], v147 offset:52224
	ds_read_b128 v[200:203], v147 offset:53248
	ds_read_b128 v[204:207], v147 offset:54272
	ds_read_b128 v[208:211], v147 offset:55296
	ds_read_b128 v[212:215], v147 offset:56320
	global_load_lds_dwordx4 v130, s[98:99]
	s_add_i32 m0, s54, 0x2000
	s_add_u32 s52, s52, 0x40080
	s_addc_u32 s53, s53, 0
	s_add_i32 s54, s78, s61
	global_load_lds_dwordx4 v134, s[98:99]
	s_mov_b32 m0, s54
	s_nop 0
	global_load_lds_dwordx4 v130, s[52:53]
	s_add_i32 m0, s54, 0x2000
	s_nop 0
	global_load_lds_dwordx4 v134, s[52:53]
	s_mov_b32 m0, s66
	s_nop 0
	global_load_lds_dwordx4 v128, s[100:101]
	s_mov_b32 m0, s67
	s_nop 0
	global_load_lds_dwordx4 v132, s[100:101]
	s_waitcnt vmcnt(8)
	s_waitcnt lgkmcnt(0)
	s_barrier
	s_setprio 1
	s_waitcnt lgkmcnt(0)
	v_mfma_f32_16x16x32_bf16 v[60:63], v[148:151], v[180:183], v[60:63]
	v_mfma_f32_16x16x32_bf16 v[56:59], v[156:159], v[180:183], v[56:59]
	v_mfma_f32_16x16x32_bf16 v[52:55], v[148:151], v[192:195], v[52:55]
	v_mfma_f32_16x16x32_bf16 v[44:47], v[156:159], v[192:195], v[44:47]
	v_mfma_f32_16x16x32_bf16 v[36:39], v[148:151], v[200:203], v[36:39]
	v_mfma_f32_16x16x32_bf16 v[28:31], v[156:159], v[200:203], v[28:31]
	v_mfma_f32_16x16x32_bf16 v[20:23], v[148:151], v[208:211], v[20:23]
	v_mfma_f32_16x16x32_bf16 v[12:15], v[156:159], v[208:211], v[12:15]
	v_mfma_f32_16x16x32_bf16 v[60:63], v[152:155], v[188:191], v[60:63]
	v_mfma_f32_16x16x32_bf16 v[56:59], v[160:163], v[188:191], v[56:59]
	v_mfma_f32_16x16x32_bf16 v[52:55], v[152:155], v[196:199], v[52:55]
	v_mfma_f32_16x16x32_bf16 v[44:47], v[160:163], v[196:199], v[44:47]
	v_mfma_f32_16x16x32_bf16 v[36:39], v[152:155], v[204:207], v[36:39]
	v_mfma_f32_16x16x32_bf16 v[28:31], v[160:163], v[204:207], v[28:31]
	v_mfma_f32_16x16x32_bf16 v[20:23], v[152:155], v[212:215], v[20:23]
	v_mfma_f32_16x16x32_bf16 v[12:15], v[160:163], v[212:215], v[12:15]
	s_setprio 0
	s_setprio 1
	v_mfma_f32_16x16x32_bf16 v[48:51], v[164:167], v[180:183], v[48:51]
	v_mfma_f32_16x16x32_bf16 v[40:43], v[172:175], v[180:183], v[40:43]
	v_mfma_f32_16x16x32_bf16 v[32:35], v[164:167], v[192:195], v[32:35]
	v_mfma_f32_16x16x32_bf16 v[24:27], v[172:175], v[192:195], v[24:27]
	v_mfma_f32_16x16x32_bf16 v[16:19], v[164:167], v[200:203], v[16:19]
	v_mfma_f32_16x16x32_bf16 v[8:11], v[172:175], v[200:203], v[8:11]
	v_mfma_f32_16x16x32_bf16 v[4:7], v[164:167], v[208:211], v[4:7]
	v_mfma_f32_16x16x32_bf16 v[0:3], v[172:175], v[208:211], v[0:3]
	v_mfma_f32_16x16x32_bf16 v[48:51], v[168:171], v[188:191], v[48:51]
	v_mfma_f32_16x16x32_bf16 v[40:43], v[176:179], v[188:191], v[40:43]
	v_mfma_f32_16x16x32_bf16 v[32:35], v[168:171], v[196:199], v[32:35]
	v_mfma_f32_16x16x32_bf16 v[24:27], v[176:179], v[196:199], v[24:27]
	v_mfma_f32_16x16x32_bf16 v[16:19], v[168:171], v[204:207], v[16:19]
	v_mfma_f32_16x16x32_bf16 v[8:11], v[176:179], v[204:207], v[8:11]
	v_mfma_f32_16x16x32_bf16 v[4:7], v[168:171], v[212:215], v[4:7]
	v_mfma_f32_16x16x32_bf16 v[0:3], v[176:179], v[212:215], v[0:3]
	s_setprio 0
	s_barrier
	s_add_i32 s76, s76, 2
	s_add_u32 s50, s50, 0x100
	s_addc_u32 s51, s51, 0
	s_add_u32 s74, s74, 0x100
	s_addc_u32 s75, s75, 0
	s_cmp_gt_u32 s76, 13
	s_cbranch_scc0 .LBB0_1255
	s_and_b64 vcc, exec, s[8:9]
	s_cbranch_vccz .LBB0_1258
	s_barrier

; __global__ void __launch_bounds__(512, 2) mk_fwd(Args a) {
	.amdhsa_kernel _Z6mk_fwd4Args
		.amdhsa_group_segment_fixed_size 0
		.amdhsa_private_segment_fixed_size 0
		.amdhsa_kernarg_size 448
		.amdhsa_user_sgpr_count 2
		.amdhsa_user_sgpr_dispatch_ptr 0
		.amdhsa_user_sgpr_queue_ptr 0
		.amdhsa_user_sgpr_kernarg_segment_ptr 1
		.amdhsa_user_sgpr_dispatch_id 0
		.amdhsa_user_sgpr_kernarg_preload_length 0
		.amdhsa_user_sgpr_kernarg_preload_offset 0
		.amdhsa_user_sgpr_private_segment_size 0
		.amdhsa_uses_dynamic_stack 0
		.amdhsa_enable_private_segment 0
		.amdhsa_system_sgpr_workgroup_id_x 1
		.amdhsa_system_sgpr_workgroup_id_y 0
		.amdhsa_system_sgpr_workgroup_id_z 0
		.amdhsa_system_sgpr_workgroup_info 0
		.amdhsa_system_vgpr_workitem_id 2
		.amdhsa_next_free_vgpr 253
		.amdhsa_next_free_sgpr 102
		.amdhsa_accum_offset 256
		.amdhsa_reserve_vcc 1
		.amdhsa_float_round_mode_32 0
		.amdhsa_float_round_mode_16_64 0
		.amdhsa_float_denorm_mode_32 3
		.amdhsa_float_denorm_mode_16_64 3
		.amdhsa_dx10_clamp 1
		.amdhsa_ieee_mode 1
		.amdhsa_fp16_overflow 0
		.amdhsa_tg_split 0
		.amdhsa_exception_fp_ieee_invalid_op 0
		.amdhsa_exception_fp_denorm_src 0
		.amdhsa_exception_fp_ieee_div_zero 0
		.amdhsa_exception_fp_ieee_overflow 0
		.amdhsa_exception_fp_ieee_underflow 0
		.amdhsa_exception_fp_ieee_inexact 0
		.amdhsa_exception_int_div_zero 0
	.end_amdhsa_kernel

; __global__ void __launch_bounds__(512, 2) mk_fwd(Args a) {
amdhsa.kernels:
  - .agpr_count:     0
    .args:
      - .offset:         0
        .size:           192
        .value_kind:     by_value
      - .offset:         192
        .size:           4
        .value_kind:     hidden_block_count_x
      - .offset:         196
        .size:           4
        .value_kind:     hidden_block_count_y
      - .offset:         200
        .size:           4
        .value_kind:     hidden_block_count_z
      - .offset:         204
        .size:           2
        .value_kind:     hidden_group_size_x
      - .offset:         206
        .size:           2
        .value_kind:     hidden_group_size_y
      - .offset:         208
        .size:           2
        .value_kind:     hidden_group_size_z
      - .offset:         210
        .size:           2
        .value_kind:     hidden_remainder_x
      - .offset:         212
        .size:           2
        .value_kind:     hidden_remainder_y
      - .offset:         214
        .size:           2
        .value_kind:     hidden_remainder_z
      - .offset:         232
        .size:           8
        .value_kind:     hidden_global_offset_x
      - .offset:         240
        .size:           8
        .value_kind:     hidden_global_offset_y
      - .offset:         248
        .size:           8
        .value_kind:     hidden_global_offset_z
      - .offset:         256
        .size:           2
        .value_kind:     hidden_grid_dims
      - .offset:         280
        .size:           8
        .value_kind:     hidden_multigrid_sync_arg
      - .offset:         312
        .size:           4
        .value_kind:     hidden_dynamic_lds_size
    .group_segment_fixed_size: 0
    .kernarg_segment_align: 8
    .kernarg_segment_size: 448
    .language:       OpenCL C
    .language_version:
      - 2
      - 0
    .max_flat_workgroup_size: 512
    .name:           _Z6mk_fwd4Args
    .private_segment_fixed_size: 0
    .sgpr_count:     108
    .sgpr_spill_count: 12
    .symbol:         _Z6mk_fwd4Args.kd
    .uniform_work_group_size: 1
    .uses_dynamic_stack: false
    .vgpr_count:     253
    .vgpr_spill_count: 0
    .wavefront_size: 64
